# EpiResid epilogues: accumulators re-laid out with DPP row_ror:8 + cndmask so each load/store instruction covers 8 rows x full 128-B lines (was 16 rows x 64 B); 2-set prefetch (on top of v11)
# speedup vs baseline: 1.0179x; 1.0118x over previous
;     __device__ __forceinline__ void operator()(const f32x4 (&acc)[2][2][4][2], const Unit& u, int wr, int wc, int fr, int fq) const {
;         const int row0 = u.pm * BM + wr * 64 + fr, col0 = u.pn * BM + wc * 32 + 4 * fq;
;         const float* rbase = (u.pm * BM < SEQ_P) ? resA : (resB - (size_t)SEQ_P * ldc);
;         f32x4 wv[2][2];
;         if (xn) {
; #pragma unroll
;             for (int bj = 0; bj < 2; ++bj)
; #pragma unroll
;                 for (int n = 0; n < 2; ++n) wv[bj][n] = *(const f32x4*)(wn + col0 + bj * HALF + n * 16);
;         }
; #pragma unroll
;         for (int ai = 0; ai < 2; ++ai)
; #pragma unroll
;             for (int m = 0; m < 4; ++m) {
;                 const int row = row0 + ai * HALF + m * 16;
;                 const size_t off = (size_t)row * ldc + col0;
;                 float q = 0.f;
; #pragma unroll
;                 for (int bj = 0; bj < 2; ++bj)
; #pragma unroll
;                     for (int n = 0; n < 2; ++n) {
;                         const f32x4 rv = *(const f32x4*)(rbase + off + bj * HALF + n * 16);
;                         const f32x4 v = rv + acc[ai][bj][m][n] * scale;
;                         if (out) *(f32x4*)(out + off + bj * HALF + n * 16) = v;
;                         if (xn) { q += (v.x * v.x + v.y * v.y) + (v.z * v.z + v.w * v.w); const f32x4 o = v * wv[bj][n];
;                             u32x2 p; p.x = pk2(o.x, o.y); p.y = pk2(o.z, o.w); *(u32x2*)(xn + off + bj * HALF + n * 16) = p; }
.LBB0_312:
	v_lshl_add_u32 v212, s62, 8, v168
	v_lshl_or_b32 v214, s61, 8, v170
	v_and_b32_e32 v243, 8, v174
	v_mov_b32_e32 v213, 0
	v_cmp_eq_u32_e64 s[34:35], 0, v243
	v_lshlrev_b32_e32 v175, 1, v243
	v_add_u32_e32 v216, v214, v175
	v_sub_u32_e32 v234, 16, v175
	v_add_u32_e32 v234, v214, v234
	v_mov_b32_e32 v214, v216
	v_mov_b32_e32 v216, v234
	v_mov_b32_e32 v215, 0
	v_mov_b32_e32 v217, 0
	v_sub_u32_e32 v210, v212, v243
	v_mov_b32_e32 v211, 0
	v_lshlrev_b64 v[208:209], 11, v[210:211]
	v_add_u32_e32 v210, 8, v210
	v_lshlrev_b64 v[210:211], 11, v[210:211]
	s_cmp_lt_i32 s62, 32
	s_cselect_b32 s31, s2, s54
	s_cselect_b32 s30, s33, s53
	v_lshl_add_u64 v[208:209], v[208:209], 0, v[214:215]
	v_lshl_add_u64 v[210:211], v[210:211], 0, v[216:217]
	v_lshl_add_u64 v[164:165], v[208:209], 2, s[30:31]
	v_lshl_add_u64 v[200:201], v[210:211], 2, s[30:31]
	v_lshl_add_u64 v[202:203], v[214:215], 2, s[10:11]
	v_lshl_add_u64 v[204:205], v[216:217], 2, s[10:11]
	global_load_dwordx4 v[64:67], v[202:203], off
	global_load_dwordx4 v[72:75], v[202:203], off offset:512
	global_load_dwordx4 v[80:83], v[204:205], off
	global_load_dwordx4 v[84:87], v[204:205], off offset:512
	global_load_dwordx4 v[156:159], v[164:165], off
	global_load_dwordx4 v[160:163], v[164:165], off offset:512
	global_load_dwordx4 v[176:179], v[200:201], off
	global_load_dwordx4 v[180:183], v[200:201], off offset:512
	s_mov_b64 vcc, 0x20000
	v_lshl_add_u64 v[164:165], v[164:165], 0, vcc
	v_lshl_add_u64 v[200:201], v[200:201], 0, vcc
	global_load_dwordx4 v[184:187], v[164:165], off
	global_load_dwordx4 v[188:191], v[164:165], off offset:512
	global_load_dwordx4 v[192:195], v[200:201], off
	global_load_dwordx4 v[196:199], v[200:201], off offset:512
	s_mov_b64 vcc, 0x20000
	v_lshl_add_u64 v[164:165], v[164:165], 0, vcc
	v_lshl_add_u64 v[200:201], v[200:201], 0, vcc
	v_lshl_add_u64 v[218:219], v[208:209], 2, s[8:9]
	v_lshl_add_u64 v[220:221], v[210:211], 2, s[8:9]
	v_lshl_add_u64 v[202:203], v[208:209], 1, s[14:15]
	v_lshl_add_u64 v[204:205], v[210:211], 1, s[14:15]
	v_lshl_add_u64 v[206:207], v[212:213], 2, s[18:19]
	v_xor_b32_e32 v235, 16, v174
	v_xor_b32_e32 v240, 32, v174
	v_lshlrev_b32_e32 v235, 2, v235
	v_lshlrev_b32_e32 v240, 2, v240
	v_mov_b32_dpp v236, v136 row_ror:8 row_mask:0xf bank_mask:0xf
	v_mov_b32_dpp v237, v137 row_ror:8 row_mask:0xf bank_mask:0xf
	v_mov_b32_dpp v238, v138 row_ror:8 row_mask:0xf bank_mask:0xf
	v_mov_b32_dpp v239, v139 row_ror:8 row_mask:0xf bank_mask:0xf
	v_cndmask_b32_e64 v136, v236, v140, s[34:35]
	v_cndmask_b32_e64 v137, v237, v141, s[34:35]
	v_cndmask_b32_e64 v138, v238, v142, s[34:35]
	v_cndmask_b32_e64 v139, v239, v143, s[34:35]
	v_cndmask_b32_e64 v140, v140, v236, s[34:35]
	v_cndmask_b32_e64 v141, v141, v237, s[34:35]
	v_cndmask_b32_e64 v142, v142, v238, s[34:35]
	v_cndmask_b32_e64 v143, v143, v239, s[34:35]
	v_mov_b32_dpp v236, v128 row_ror:8 row_mask:0xf bank_mask:0xf
	v_mov_b32_dpp v237, v129 row_ror:8 row_mask:0xf bank_mask:0xf
	v_mov_b32_dpp v238, v130 row_ror:8 row_mask:0xf bank_mask:0xf
	v_mov_b32_dpp v239, v131 row_ror:8 row_mask:0xf bank_mask:0xf
	v_cndmask_b32_e64 v128, v236, v132, s[34:35]
	v_cndmask_b32_e64 v129, v237, v133, s[34:35]
	v_cndmask_b32_e64 v130, v238, v134, s[34:35]
	v_cndmask_b32_e64 v131, v239, v135, s[34:35]
	v_cndmask_b32_e64 v132, v132, v236, s[34:35]
	v_cndmask_b32_e64 v133, v133, v237, s[34:35]
	v_cndmask_b32_e64 v134, v134, v238, s[34:35]
	v_cndmask_b32_e64 v135, v135, v239, s[34:35]
	s_waitcnt vmcnt(4)
	v_pk_fma_f32 v[138:139], v[138:139], 0.5, v[158:159] op_sel_hi:[1,0,1]
	v_pk_fma_f32 v[136:137], v[136:137], 0.5, v[156:157] op_sel_hi:[1,0,1]
	global_store_dwordx4 v[218:219], v[136:139], off
	v_pk_mul_f32 v[224:225], v[64:65], v[136:137]
	v_pk_mul_f32 v[226:227], v[66:67], v[138:139]
	v_mul_f32_e32 v175, v136, v136
	v_add_u32_e32 v224, 0x8000, v224
	v_add_u32_e32 v225, 0x8000, v225
	v_add_u32_e32 v226, 0x8000, v226
	v_add_u32_e32 v227, 0x8000, v227
	v_fmac_f32_e32 v175, v137, v137
	v_fmac_f32_e32 v175, v138, v138
	v_fmac_f32_e32 v175, v139, v139
	v_perm_b32 v222, v225, v224, s58
	v_perm_b32 v223, v227, v226, s58
	global_store_dwordx2 v[202:203], v[222:223], off
	v_pk_fma_f32 v[130:131], v[130:131], 0.5, v[162:163] op_sel_hi:[1,0,1]
	v_pk_fma_f32 v[128:129], v[128:129], 0.5, v[160:161] op_sel_hi:[1,0,1]
	global_store_dwordx4 v[218:219], v[128:131], off offset:512
	v_pk_mul_f32 v[228:229], v[72:73], v[128:129]
	v_pk_mul_f32 v[230:231], v[74:75], v[130:131]
	v_fmac_f32_e32 v175, v128, v128
	v_add_u32_e32 v228, 0x8000, v228
	v_add_u32_e32 v229, 0x8000, v229
	v_add_u32_e32 v230, 0x8000, v230
	v_add_u32_e32 v231, 0x8000, v231
	v_fmac_f32_e32 v175, v129, v129
	v_fmac_f32_e32 v175, v130, v130
	v_fmac_f32_e32 v175, v131, v131
	v_perm_b32 v232, v229, v228, s58
	v_perm_b32 v233, v231, v230, s58
	global_store_dwordx2 v[202:203], v[232:233], off offset:256
	v_pk_fma_f32 v[142:143], v[142:143], 0.5, v[178:179] op_sel_hi:[1,0,1]
	v_pk_fma_f32 v[140:141], v[140:141], 0.5, v[176:177] op_sel_hi:[1,0,1]
	global_store_dwordx4 v[220:221], v[140:143], off
	v_pk_mul_f32 v[224:225], v[80:81], v[140:141]
	v_pk_mul_f32 v[226:227], v[82:83], v[142:143]
	v_mul_f32_e32 v234, v140, v140
	v_add_u32_e32 v224, 0x8000, v224
	v_add_u32_e32 v225, 0x8000, v225
	v_add_u32_e32 v226, 0x8000, v226
	v_add_u32_e32 v227, 0x8000, v227
	v_fmac_f32_e32 v234, v141, v141
	v_fmac_f32_e32 v234, v142, v142
	v_fmac_f32_e32 v234, v143, v143
	v_perm_b32 v222, v225, v224, s58
	v_perm_b32 v223, v227, v226, s58
	global_store_dwordx2 v[204:205], v[222:223], off
	v_pk_fma_f32 v[134:135], v[134:135], 0.5, v[182:183] op_sel_hi:[1,0,1]
	v_pk_fma_f32 v[132:133], v[132:133], 0.5, v[180:181] op_sel_hi:[1,0,1]
;     __device__ __forceinline__ void operator()(const f32x4 (&acc)[2][2][4][2], const Unit& u, int wr, int wc, int fr, int fq) const {
;     ...
;         for (int ai = 0; ai < 2; ++ai)
; #pragma unroll
;             for (int m = 0; m < 4; ++m) {
;                 const int row = row0 + ai * HALF + m * 16;
;                 const size_t off = (size_t)row * ldc + col0;
;                 float q = 0.f;
; #pragma unroll
;                 for (int bj = 0; bj < 2; ++bj)
; #pragma unroll
;                     for (int n = 0; n < 2; ++n) {
;                         const f32x4 rv = *(const f32x4*)(rbase + off + bj * HALF + n * 16);
;                         const f32x4 v = rv + acc[ai][bj][m][n] * scale;
;                         if (out) *(f32x4*)(out + off + bj * HALF + n * 16) = v;
;                         if (xn) { q += (v.x * v.x + v.y * v.y) + (v.z * v.z + v.w * v.w); const f32x4 o = v * wv[bj][n];
;                             u32x2 p; p.x = pk2(o.x, o.y); p.y = pk2(o.z, o.w); *(u32x2*)(xn + off + bj * HALF + n * 16) = p; }
;                     }
;                 if (xn) { q += __shfl_xor(q, 16); q += __shfl_xor(q, 32); if (fq == 0) (void)__hip_atomic_fetch_add(ss + row, q, __ATOMIC_RELAXED, __HIP_MEMORY_SCOPE_AGENT); }
	global_store_dwordx4 v[220:221], v[132:135], off offset:512
	v_pk_mul_f32 v[228:229], v[84:85], v[132:133]
	v_pk_mul_f32 v[230:231], v[86:87], v[134:135]
	v_fmac_f32_e32 v234, v132, v132
	v_add_u32_e32 v228, 0x8000, v228
	v_add_u32_e32 v229, 0x8000, v229
	v_add_u32_e32 v230, 0x8000, v230
	v_add_u32_e32 v231, 0x8000, v231
	v_fmac_f32_e32 v234, v133, v133
	v_fmac_f32_e32 v234, v134, v134
	v_fmac_f32_e32 v234, v135, v135
	v_perm_b32 v232, v229, v228, s58
	v_perm_b32 v233, v231, v230, s58
	global_store_dwordx2 v[204:205], v[232:233], off offset:256
	s_nop 1
	v_mov_b32_dpp v241, v175 row_ror:8 row_mask:0xf bank_mask:0xf
	v_mov_b32_dpp v242, v234 row_ror:8 row_mask:0xf bank_mask:0xf
	v_add_f32_e32 v175, v175, v241
	v_add_f32_e32 v234, v234, v242
	v_cndmask_b32_e64 v175, v234, v175, s[34:35]
	s_nop 0
	ds_bpermute_b32 v241, v235, v175
	global_load_dwordx4 v[156:159], v[164:165], off
	global_load_dwordx4 v[160:163], v[164:165], off offset:512
	global_load_dwordx4 v[176:179], v[200:201], off
	global_load_dwordx4 v[180:183], v[200:201], off offset:512
	s_mov_b64 vcc, 0x20000
	v_lshl_add_u64 v[164:165], v[164:165], 0, vcc
	v_lshl_add_u64 v[200:201], v[200:201], 0, vcc
	s_mov_b64 vcc, 0x20000
	v_lshl_add_u64 v[218:219], v[218:219], 0, vcc
	v_lshl_add_u64 v[220:221], v[220:221], 0, vcc
	s_mov_b64 vcc, 0x10000
	v_lshl_add_u64 v[202:203], v[202:203], 0, vcc
	v_lshl_add_u64 v[204:205], v[204:205], 0, vcc
	s_waitcnt lgkmcnt(0)
	v_add_f32_e32 v175, v175, v241
	s_nop 0
	ds_bpermute_b32 v242, v240, v175
	s_waitcnt lgkmcnt(0)
	v_add_f32_e32 v175, v175, v242
	s_mov_b64 exec, s[0:1]
	global_atomic_add_f32 v[206:207], v175, off
	s_mov_b64 exec, -1
	s_mov_b64 vcc, 64
	v_lshl_add_u64 v[206:207], v[206:207], 0, vcc
	v_mov_b32_dpp v236, v120 row_ror:8 row_mask:0xf bank_mask:0xf
	v_mov_b32_dpp v237, v121 row_ror:8 row_mask:0xf bank_mask:0xf
	v_mov_b32_dpp v238, v122 row_ror:8 row_mask:0xf bank_mask:0xf
	v_mov_b32_dpp v239, v123 row_ror:8 row_mask:0xf bank_mask:0xf
	v_cndmask_b32_e64 v120, v236, v124, s[34:35]
	v_cndmask_b32_e64 v121, v237, v125, s[34:35]
	v_cndmask_b32_e64 v122, v238, v126, s[34:35]
	v_cndmask_b32_e64 v123, v239, v127, s[34:35]
	v_cndmask_b32_e64 v124, v124, v236, s[34:35]
	v_cndmask_b32_e64 v125, v125, v237, s[34:35]
	v_cndmask_b32_e64 v126, v126, v238, s[34:35]
	v_cndmask_b32_e64 v127, v127, v239, s[34:35]
	v_mov_b32_dpp v236, v112 row_ror:8 row_mask:0xf bank_mask:0xf
	v_mov_b32_dpp v237, v113 row_ror:8 row_mask:0xf bank_mask:0xf
	v_mov_b32_dpp v238, v114 row_ror:8 row_mask:0xf bank_mask:0xf
	v_mov_b32_dpp v239, v115 row_ror:8 row_mask:0xf bank_mask:0xf
	v_cndmask_b32_e64 v112, v236, v116, s[34:35]
	v_cndmask_b32_e64 v113, v237, v117, s[34:35]
	v_cndmask_b32_e64 v114, v238, v118, s[34:35]
	v_cndmask_b32_e64 v115, v239, v119, s[34:35]
	v_cndmask_b32_e64 v116, v116, v236, s[34:35]
	v_cndmask_b32_e64 v117, v117, v237, s[34:35]
	v_cndmask_b32_e64 v118, v118, v238, s[34:35]
	v_cndmask_b32_e64 v119, v119, v239, s[34:35]
	s_waitcnt vmcnt(13)
	v_pk_fma_f32 v[122:123], v[122:123], 0.5, v[186:187] op_sel_hi:[1,0,1]
	v_pk_fma_f32 v[120:121], v[120:121], 0.5, v[184:185] op_sel_hi:[1,0,1]
	global_store_dwordx4 v[218:219], v[120:123], off
	v_pk_mul_f32 v[224:225], v[64:65], v[120:121]
	v_pk_mul_f32 v[226:227], v[66:67], v[122:123]
	v_mul_f32_e32 v175, v120, v120
	v_add_u32_e32 v224, 0x8000, v224
	v_add_u32_e32 v225, 0x8000, v225
	v_add_u32_e32 v226, 0x8000, v226
	v_add_u32_e32 v227, 0x8000, v227
	v_fmac_f32_e32 v175, v121, v121
	v_fmac_f32_e32 v175, v122, v122
	v_fmac_f32_e32 v175, v123, v123
	v_perm_b32 v222, v225, v224, s58
	v_perm_b32 v223, v227, v226, s58
	global_store_dwordx2 v[202:203], v[222:223], off
	v_pk_fma_f32 v[114:115], v[114:115], 0.5, v[190:191] op_sel_hi:[1,0,1]
	v_pk_fma_f32 v[112:113], v[112:113], 0.5, v[188:189] op_sel_hi:[1,0,1]
	global_store_dwordx4 v[218:219], v[112:115], off offset:512
	v_pk_mul_f32 v[228:229], v[72:73], v[112:113]
	v_pk_mul_f32 v[230:231], v[74:75], v[114:115]
	v_fmac_f32_e32 v175, v112, v112
	v_add_u32_e32 v228, 0x8000, v228
	v_add_u32_e32 v229, 0x8000, v229
	v_add_u32_e32 v230, 0x8000, v230
	v_add_u32_e32 v231, 0x8000, v231
	v_fmac_f32_e32 v175, v113, v113
	v_fmac_f32_e32 v175, v114, v114
	v_fmac_f32_e32 v175, v115, v115
	v_perm_b32 v232, v229, v228, s58
	v_perm_b32 v233, v231, v230, s58
	global_store_dwordx2 v[202:203], v[232:233], off offset:256
	v_pk_fma_f32 v[126:127], v[126:127], 0.5, v[194:195] op_sel_hi:[1,0,1]
	v_pk_fma_f32 v[124:125], v[124:125], 0.5, v[192:193] op_sel_hi:[1,0,1]
	global_store_dwordx4 v[220:221], v[124:127], off
	v_pk_mul_f32 v[224:225], v[80:81], v[124:125]
	v_pk_mul_f32 v[226:227], v[82:83], v[126:127]
	v_mul_f32_e32 v234, v124, v124
	v_add_u32_e32 v224, 0x8000, v224
	v_add_u32_e32 v225, 0x8000, v225
	v_add_u32_e32 v226, 0x8000, v226
	v_add_u32_e32 v227, 0x8000, v227
	v_fmac_f32_e32 v234, v125, v125
	v_fmac_f32_e32 v234, v126, v126
	v_fmac_f32_e32 v234, v127, v127
	v_perm_b32 v222, v225, v224, s58
	v_perm_b32 v223, v227, v226, s58
	global_store_dwordx2 v[204:205], v[222:223], off
	v_pk_fma_f32 v[118:119], v[118:119], 0.5, v[198:199] op_sel_hi:[1,0,1]
	v_pk_fma_f32 v[116:117], v[116:117], 0.5, v[196:197] op_sel_hi:[1,0,1]
	global_store_dwordx4 v[220:221], v[116:119], off offset:512
	v_pk_mul_f32 v[228:229], v[84:85], v[116:117]
	v_pk_mul_f32 v[230:231], v[86:87], v[118:119]
	v_fmac_f32_e32 v234, v116, v116
	v_add_u32_e32 v228, 0x8000, v228
	v_add_u32_e32 v229, 0x8000, v229
	v_add_u32_e32 v230, 0x8000, v230
	v_add_u32_e32 v231, 0x8000, v231
	v_fmac_f32_e32 v234, v117, v117
	v_fmac_f32_e32 v234, v118, v118
	v_fmac_f32_e32 v234, v119, v119
	v_perm_b32 v232, v229, v228, s58
	v_perm_b32 v233, v231, v230, s58
	global_store_dwordx2 v[204:205], v[232:233], off offset:256
	s_nop 1
	v_mov_b32_dpp v241, v175 row_ror:8 row_mask:0xf bank_mask:0xf
	v_mov_b32_dpp v242, v234 row_ror:8 row_mask:0xf bank_mask:0xf
	v_add_f32_e32 v175, v175, v241
	v_add_f32_e32 v234, v234, v242
	v_cndmask_b32_e64 v175, v234, v175, s[34:35]
	s_nop 0
	ds_bpermute_b32 v241, v235, v175
	global_load_dwordx4 v[184:187], v[164:165], off
	global_load_dwordx4 v[188:191], v[164:165], off offset:512
	global_load_dwordx4 v[192:195], v[200:201], off
	global_load_dwordx4 v[196:199], v[200:201], off offset:512
	s_mov_b64 vcc, 0xa0000
	v_lshl_add_u64 v[164:165], v[164:165], 0, vcc
	v_lshl_add_u64 v[200:201], v[200:201], 0, vcc
	s_mov_b64 vcc, 0x20000
	v_lshl_add_u64 v[218:219], v[218:219], 0, vcc
	v_lshl_add_u64 v[220:221], v[220:221], 0, vcc
	s_mov_b64 vcc, 0x10000
	v_lshl_add_u64 v[202:203], v[202:203], 0, vcc
	v_lshl_add_u64 v[204:205], v[204:205], 0, vcc
	s_waitcnt lgkmcnt(0)
;     __device__ __forceinline__ void operator()(const f32x4 (&acc)[2][2][4][2], const Unit& u, int wr, int wc, int fr, int fq) const {
;     ...
;         for (int ai = 0; ai < 2; ++ai)
; #pragma unroll
;             for (int m = 0; m < 4; ++m) {
;                 const int row = row0 + ai * HALF + m * 16;
;                 const size_t off = (size_t)row * ldc + col0;
;                 float q = 0.f;
; #pragma unroll
;                 for (int bj = 0; bj < 2; ++bj)
; #pragma unroll
;                     for (int n = 0; n < 2; ++n) {
;                         const f32x4 rv = *(const f32x4*)(rbase + off + bj * HALF + n * 16);
;                         const f32x4 v = rv + acc[ai][bj][m][n] * scale;
;                         if (out) *(f32x4*)(out + off + bj * HALF + n * 16) = v;
;                         if (xn) { q += (v.x * v.x + v.y * v.y) + (v.z * v.z + v.w * v.w); const f32x4 o = v * wv[bj][n];
;                             u32x2 p; p.x = pk2(o.x, o.y); p.y = pk2(o.z, o.w); *(u32x2*)(xn + off + bj * HALF + n * 16) = p; }
;                     }
;                 if (xn) { q += __shfl_xor(q, 16); q += __shfl_xor(q, 32); if (fq == 0) (void)__hip_atomic_fetch_add(ss + row, q, __ATOMIC_RELAXED, __HIP_MEMORY_SCOPE_AGENT); }
	v_add_f32_e32 v175, v175, v241
	s_nop 0
	ds_bpermute_b32 v242, v240, v175
	s_waitcnt lgkmcnt(0)
	v_add_f32_e32 v175, v175, v242
	s_mov_b64 exec, s[0:1]
	global_atomic_add_f32 v[206:207], v175, off
	s_mov_b64 exec, -1
	s_mov_b64 vcc, 64
	v_lshl_add_u64 v[206:207], v[206:207], 0, vcc
	v_mov_b32_dpp v236, v104 row_ror:8 row_mask:0xf bank_mask:0xf
	v_mov_b32_dpp v237, v105 row_ror:8 row_mask:0xf bank_mask:0xf
	v_mov_b32_dpp v238, v106 row_ror:8 row_mask:0xf bank_mask:0xf
	v_mov_b32_dpp v239, v107 row_ror:8 row_mask:0xf bank_mask:0xf
	v_cndmask_b32_e64 v104, v236, v108, s[34:35]
	v_cndmask_b32_e64 v105, v237, v109, s[34:35]
	v_cndmask_b32_e64 v106, v238, v110, s[34:35]
	v_cndmask_b32_e64 v107, v239, v111, s[34:35]
	v_cndmask_b32_e64 v108, v108, v236, s[34:35]
	v_cndmask_b32_e64 v109, v109, v237, s[34:35]
	v_cndmask_b32_e64 v110, v110, v238, s[34:35]
	v_cndmask_b32_e64 v111, v111, v239, s[34:35]
	v_mov_b32_dpp v236, v96 row_ror:8 row_mask:0xf bank_mask:0xf
	v_mov_b32_dpp v237, v97 row_ror:8 row_mask:0xf bank_mask:0xf
	v_mov_b32_dpp v238, v98 row_ror:8 row_mask:0xf bank_mask:0xf
	v_mov_b32_dpp v239, v99 row_ror:8 row_mask:0xf bank_mask:0xf
	v_cndmask_b32_e64 v96, v236, v100, s[34:35]
	v_cndmask_b32_e64 v97, v237, v101, s[34:35]
	v_cndmask_b32_e64 v98, v238, v102, s[34:35]
	v_cndmask_b32_e64 v99, v239, v103, s[34:35]
	v_cndmask_b32_e64 v100, v100, v236, s[34:35]
	v_cndmask_b32_e64 v101, v101, v237, s[34:35]
	v_cndmask_b32_e64 v102, v102, v238, s[34:35]
	v_cndmask_b32_e64 v103, v103, v239, s[34:35]
	s_waitcnt vmcnt(14)
	v_pk_fma_f32 v[106:107], v[106:107], 0.5, v[158:159] op_sel_hi:[1,0,1]
	v_pk_fma_f32 v[104:105], v[104:105], 0.5, v[156:157] op_sel_hi:[1,0,1]
	global_store_dwordx4 v[218:219], v[104:107], off
	v_pk_mul_f32 v[224:225], v[64:65], v[104:105]
	v_pk_mul_f32 v[226:227], v[66:67], v[106:107]
	v_mul_f32_e32 v175, v104, v104
	v_add_u32_e32 v224, 0x8000, v224
	v_add_u32_e32 v225, 0x8000, v225
	v_add_u32_e32 v226, 0x8000, v226
	v_add_u32_e32 v227, 0x8000, v227
	v_fmac_f32_e32 v175, v105, v105
	v_fmac_f32_e32 v175, v106, v106
	v_fmac_f32_e32 v175, v107, v107
	v_perm_b32 v222, v225, v224, s58
	v_perm_b32 v223, v227, v226, s58
	global_store_dwordx2 v[202:203], v[222:223], off
	v_pk_fma_f32 v[98:99], v[98:99], 0.5, v[162:163] op_sel_hi:[1,0,1]
	v_pk_fma_f32 v[96:97], v[96:97], 0.5, v[160:161] op_sel_hi:[1,0,1]
	global_store_dwordx4 v[218:219], v[96:99], off offset:512
	v_pk_mul_f32 v[228:229], v[72:73], v[96:97]
	v_pk_mul_f32 v[230:231], v[74:75], v[98:99]
	v_fmac_f32_e32 v175, v96, v96
	v_add_u32_e32 v228, 0x8000, v228
	v_add_u32_e32 v229, 0x8000, v229
	v_add_u32_e32 v230, 0x8000, v230
	v_add_u32_e32 v231, 0x8000, v231
	v_fmac_f32_e32 v175, v97, v97
	v_fmac_f32_e32 v175, v98, v98
	v_fmac_f32_e32 v175, v99, v99
	v_perm_b32 v232, v229, v228, s58
	v_perm_b32 v233, v231, v230, s58
	global_store_dwordx2 v[202:203], v[232:233], off offset:256
	v_pk_fma_f32 v[110:111], v[110:111], 0.5, v[178:179] op_sel_hi:[1,0,1]
	v_pk_fma_f32 v[108:109], v[108:109], 0.5, v[176:177] op_sel_hi:[1,0,1]
	global_store_dwordx4 v[220:221], v[108:111], off
	v_pk_mul_f32 v[224:225], v[80:81], v[108:109]
	v_pk_mul_f32 v[226:227], v[82:83], v[110:111]
	v_mul_f32_e32 v234, v108, v108
	v_add_u32_e32 v224, 0x8000, v224
	v_add_u32_e32 v225, 0x8000, v225
	v_add_u32_e32 v226, 0x8000, v226
	v_add_u32_e32 v227, 0x8000, v227
	v_fmac_f32_e32 v234, v109, v109
	v_fmac_f32_e32 v234, v110, v110
	v_fmac_f32_e32 v234, v111, v111
	v_perm_b32 v222, v225, v224, s58
	v_perm_b32 v223, v227, v226, s58
	global_store_dwordx2 v[204:205], v[222:223], off
	v_pk_fma_f32 v[102:103], v[102:103], 0.5, v[182:183] op_sel_hi:[1,0,1]
	v_pk_fma_f32 v[100:101], v[100:101], 0.5, v[180:181] op_sel_hi:[1,0,1]
	global_store_dwordx4 v[220:221], v[100:103], off offset:512
	v_pk_mul_f32 v[228:229], v[84:85], v[100:101]
	v_pk_mul_f32 v[230:231], v[86:87], v[102:103]
	v_fmac_f32_e32 v234, v100, v100
	v_add_u32_e32 v228, 0x8000, v228
	v_add_u32_e32 v229, 0x8000, v229
	v_add_u32_e32 v230, 0x8000, v230
	v_add_u32_e32 v231, 0x8000, v231
	v_fmac_f32_e32 v234, v101, v101
	v_fmac_f32_e32 v234, v102, v102
	v_fmac_f32_e32 v234, v103, v103
	v_perm_b32 v232, v229, v228, s58
	v_perm_b32 v233, v231, v230, s58
	global_store_dwordx2 v[204:205], v[232:233], off offset:256
	s_nop 1
	v_mov_b32_dpp v241, v175 row_ror:8 row_mask:0xf bank_mask:0xf
	v_mov_b32_dpp v242, v234 row_ror:8 row_mask:0xf bank_mask:0xf
	v_add_f32_e32 v175, v175, v241
	v_add_f32_e32 v234, v234, v242
	v_cndmask_b32_e64 v175, v234, v175, s[34:35]
	s_nop 0
	ds_bpermute_b32 v241, v235, v175
	global_load_dwordx4 v[156:159], v[164:165], off
	global_load_dwordx4 v[160:163], v[164:165], off offset:512
	global_load_dwordx4 v[176:179], v[200:201], off
	global_load_dwordx4 v[180:183], v[200:201], off offset:512
	s_mov_b64 vcc, 0x20000
	v_lshl_add_u64 v[164:165], v[164:165], 0, vcc
	v_lshl_add_u64 v[200:201], v[200:201], 0, vcc
	s_mov_b64 vcc, 0x20000
	v_lshl_add_u64 v[218:219], v[218:219], 0, vcc
	v_lshl_add_u64 v[220:221], v[220:221], 0, vcc
	s_mov_b64 vcc, 0x10000
	v_lshl_add_u64 v[202:203], v[202:203], 0, vcc
	v_lshl_add_u64 v[204:205], v[204:205], 0, vcc
	s_waitcnt lgkmcnt(0)
	v_add_f32_e32 v175, v175, v241
	s_nop 0
	ds_bpermute_b32 v242, v240, v175
	s_waitcnt lgkmcnt(0)
;     __device__ __forceinline__ void operator()(const f32x4 (&acc)[2][2][4][2], const Unit& u, int wr, int wc, int fr, int fq) const {
;     ...
;         for (int ai = 0; ai < 2; ++ai)
; #pragma unroll
;             for (int m = 0; m < 4; ++m) {
;                 const int row = row0 + ai * HALF + m * 16;
;                 const size_t off = (size_t)row * ldc + col0;
;                 float q = 0.f;
; #pragma unroll
;                 for (int bj = 0; bj < 2; ++bj)
; #pragma unroll
;                     for (int n = 0; n < 2; ++n) {
;                         const f32x4 rv = *(const f32x4*)(rbase + off + bj * HALF + n * 16);
;                         const f32x4 v = rv + acc[ai][bj][m][n] * scale;
;                         if (out) *(f32x4*)(out + off + bj * HALF + n * 16) = v;
;                         if (xn) { q += (v.x * v.x + v.y * v.y) + (v.z * v.z + v.w * v.w); const f32x4 o = v * wv[bj][n];
;                             u32x2 p; p.x = pk2(o.x, o.y); p.y = pk2(o.z, o.w); *(u32x2*)(xn + off + bj * HALF + n * 16) = p; }
;                     }
;                 if (xn) { q += __shfl_xor(q, 16); q += __shfl_xor(q, 32); if (fq == 0) (void)__hip_atomic_fetch_add(ss + row, q, __ATOMIC_RELAXED, __HIP_MEMORY_SCOPE_AGENT); }
	v_add_f32_e32 v175, v175, v242
	s_mov_b64 exec, s[0:1]
	global_atomic_add_f32 v[206:207], v175, off
	s_mov_b64 exec, -1
	s_mov_b64 vcc, 64
	v_lshl_add_u64 v[206:207], v[206:207], 0, vcc
	v_mov_b32_dpp v236, v88 row_ror:8 row_mask:0xf bank_mask:0xf
	v_mov_b32_dpp v237, v89 row_ror:8 row_mask:0xf bank_mask:0xf
	v_mov_b32_dpp v238, v90 row_ror:8 row_mask:0xf bank_mask:0xf
	v_mov_b32_dpp v239, v91 row_ror:8 row_mask:0xf bank_mask:0xf
	v_cndmask_b32_e64 v88, v236, v92, s[34:35]
	v_cndmask_b32_e64 v89, v237, v93, s[34:35]
	v_cndmask_b32_e64 v90, v238, v94, s[34:35]
	v_cndmask_b32_e64 v91, v239, v95, s[34:35]
	v_cndmask_b32_e64 v92, v92, v236, s[34:35]
	v_cndmask_b32_e64 v93, v93, v237, s[34:35]
	v_cndmask_b32_e64 v94, v94, v238, s[34:35]
	v_cndmask_b32_e64 v95, v95, v239, s[34:35]
	v_mov_b32_dpp v236, v68 row_ror:8 row_mask:0xf bank_mask:0xf
	v_mov_b32_dpp v237, v69 row_ror:8 row_mask:0xf bank_mask:0xf
	v_mov_b32_dpp v238, v70 row_ror:8 row_mask:0xf bank_mask:0xf
	v_mov_b32_dpp v239, v71 row_ror:8 row_mask:0xf bank_mask:0xf
	v_cndmask_b32_e64 v68, v236, v76, s[34:35]
	v_cndmask_b32_e64 v69, v237, v77, s[34:35]
	v_cndmask_b32_e64 v70, v238, v78, s[34:35]
	v_cndmask_b32_e64 v71, v239, v79, s[34:35]
	v_cndmask_b32_e64 v76, v76, v236, s[34:35]
	v_cndmask_b32_e64 v77, v77, v237, s[34:35]
	v_cndmask_b32_e64 v78, v78, v238, s[34:35]
	v_cndmask_b32_e64 v79, v79, v239, s[34:35]
	s_waitcnt vmcnt(14)
	v_pk_fma_f32 v[90:91], v[90:91], 0.5, v[186:187] op_sel_hi:[1,0,1]
	v_pk_fma_f32 v[88:89], v[88:89], 0.5, v[184:185] op_sel_hi:[1,0,1]
	global_store_dwordx4 v[218:219], v[88:91], off
	v_pk_mul_f32 v[224:225], v[64:65], v[88:89]
	v_pk_mul_f32 v[226:227], v[66:67], v[90:91]
	v_mul_f32_e32 v175, v88, v88
	v_add_u32_e32 v224, 0x8000, v224
	v_add_u32_e32 v225, 0x8000, v225
	v_add_u32_e32 v226, 0x8000, v226
	v_add_u32_e32 v227, 0x8000, v227
	v_fmac_f32_e32 v175, v89, v89
	v_fmac_f32_e32 v175, v90, v90
	v_fmac_f32_e32 v175, v91, v91
	v_perm_b32 v222, v225, v224, s58
	v_perm_b32 v223, v227, v226, s58
	global_store_dwordx2 v[202:203], v[222:223], off
	v_pk_fma_f32 v[70:71], v[70:71], 0.5, v[190:191] op_sel_hi:[1,0,1]
	v_pk_fma_f32 v[68:69], v[68:69], 0.5, v[188:189] op_sel_hi:[1,0,1]
	global_store_dwordx4 v[218:219], v[68:71], off offset:512
	v_pk_mul_f32 v[228:229], v[72:73], v[68:69]
	v_pk_mul_f32 v[230:231], v[74:75], v[70:71]
	v_fmac_f32_e32 v175, v68, v68
	v_add_u32_e32 v228, 0x8000, v228
	v_add_u32_e32 v229, 0x8000, v229
	v_add_u32_e32 v230, 0x8000, v230
	v_add_u32_e32 v231, 0x8000, v231
	v_fmac_f32_e32 v175, v69, v69
	v_fmac_f32_e32 v175, v70, v70
	v_fmac_f32_e32 v175, v71, v71
	v_perm_b32 v232, v229, v228, s58
	v_perm_b32 v233, v231, v230, s58
	global_store_dwordx2 v[202:203], v[232:233], off offset:256
	v_pk_fma_f32 v[94:95], v[94:95], 0.5, v[194:195] op_sel_hi:[1,0,1]
	v_pk_fma_f32 v[92:93], v[92:93], 0.5, v[192:193] op_sel_hi:[1,0,1]
	global_store_dwordx4 v[220:221], v[92:95], off
	v_pk_mul_f32 v[224:225], v[80:81], v[92:93]
	v_pk_mul_f32 v[226:227], v[82:83], v[94:95]
	v_mul_f32_e32 v234, v92, v92
	v_add_u32_e32 v224, 0x8000, v224
	v_add_u32_e32 v225, 0x8000, v225
	v_add_u32_e32 v226, 0x8000, v226
	v_add_u32_e32 v227, 0x8000, v227
	v_fmac_f32_e32 v234, v93, v93
	v_fmac_f32_e32 v234, v94, v94
	v_fmac_f32_e32 v234, v95, v95
	v_perm_b32 v222, v225, v224, s58
	v_perm_b32 v223, v227, v226, s58
	global_store_dwordx2 v[204:205], v[222:223], off
	v_pk_fma_f32 v[78:79], v[78:79], 0.5, v[198:199] op_sel_hi:[1,0,1]
	v_pk_fma_f32 v[76:77], v[76:77], 0.5, v[196:197] op_sel_hi:[1,0,1]
	global_store_dwordx4 v[220:221], v[76:79], off offset:512
	v_pk_mul_f32 v[228:229], v[84:85], v[76:77]
	v_pk_mul_f32 v[230:231], v[86:87], v[78:79]
	v_fmac_f32_e32 v234, v76, v76
	v_add_u32_e32 v228, 0x8000, v228
	v_add_u32_e32 v229, 0x8000, v229
	v_add_u32_e32 v230, 0x8000, v230
	v_add_u32_e32 v231, 0x8000, v231
	v_fmac_f32_e32 v234, v77, v77
	v_fmac_f32_e32 v234, v78, v78
	v_fmac_f32_e32 v234, v79, v79
	v_perm_b32 v232, v229, v228, s58
	v_perm_b32 v233, v231, v230, s58
	global_store_dwordx2 v[204:205], v[232:233], off offset:256
	s_nop 1
	v_mov_b32_dpp v241, v175 row_ror:8 row_mask:0xf bank_mask:0xf
	v_mov_b32_dpp v242, v234 row_ror:8 row_mask:0xf bank_mask:0xf
	v_add_f32_e32 v175, v175, v241
	v_add_f32_e32 v234, v234, v242
	v_cndmask_b32_e64 v175, v234, v175, s[34:35]
	s_nop 0
	ds_bpermute_b32 v241, v235, v175
	global_load_dwordx4 v[184:187], v[164:165], off
	global_load_dwordx4 v[188:191], v[164:165], off offset:512
	global_load_dwordx4 v[192:195], v[200:201], off
	global_load_dwordx4 v[196:199], v[200:201], off offset:512
	s_mov_b64 vcc, 0x20000
	v_lshl_add_u64 v[164:165], v[164:165], 0, vcc
	v_lshl_add_u64 v[200:201], v[200:201], 0, vcc
	s_mov_b64 vcc, 0xa0000
	v_lshl_add_u64 v[218:219], v[218:219], 0, vcc
	v_lshl_add_u64 v[220:221], v[220:221], 0, vcc
	s_mov_b64 vcc, 0x50000
	v_lshl_add_u64 v[202:203], v[202:203], 0, vcc
	v_lshl_add_u64 v[204:205], v[204:205], 0, vcc
	s_waitcnt lgkmcnt(0)
	v_add_f32_e32 v175, v175, v241
	s_nop 0
	ds_bpermute_b32 v242, v240, v175
	s_waitcnt lgkmcnt(0)
;     __device__ __forceinline__ void operator()(const f32x4 (&acc)[2][2][4][2], const Unit& u, int wr, int wc, int fr, int fq) const {
;     ...
;         for (int ai = 0; ai < 2; ++ai)
; #pragma unroll
;             for (int m = 0; m < 4; ++m) {
;                 const int row = row0 + ai * HALF + m * 16;
;                 const size_t off = (size_t)row * ldc + col0;
;                 float q = 0.f;
; #pragma unroll
;                 for (int bj = 0; bj < 2; ++bj)
; #pragma unroll
;                     for (int n = 0; n < 2; ++n) {
;                         const f32x4 rv = *(const f32x4*)(rbase + off + bj * HALF + n * 16);
;                         const f32x4 v = rv + acc[ai][bj][m][n] * scale;
;                         if (out) *(f32x4*)(out + off + bj * HALF + n * 16) = v;
;                         if (xn) { q += (v.x * v.x + v.y * v.y) + (v.z * v.z + v.w * v.w); const f32x4 o = v * wv[bj][n];
;                             u32x2 p; p.x = pk2(o.x, o.y); p.y = pk2(o.z, o.w); *(u32x2*)(xn + off + bj * HALF + n * 16) = p; }
;                     }
;                 if (xn) { q += __shfl_xor(q, 16); q += __shfl_xor(q, 32); if (fq == 0) (void)__hip_atomic_fetch_add(ss + row, q, __ATOMIC_RELAXED, __HIP_MEMORY_SCOPE_AGENT); }
	v_add_f32_e32 v175, v175, v242
	s_mov_b64 exec, s[0:1]
	global_atomic_add_f32 v[206:207], v175, off
	s_mov_b64 exec, -1
	s_mov_b64 vcc, 320
	v_lshl_add_u64 v[206:207], v[206:207], 0, vcc
	v_mov_b32_dpp v236, v56 row_ror:8 row_mask:0xf bank_mask:0xf
	v_mov_b32_dpp v237, v57 row_ror:8 row_mask:0xf bank_mask:0xf
	v_mov_b32_dpp v238, v58 row_ror:8 row_mask:0xf bank_mask:0xf
	v_mov_b32_dpp v239, v59 row_ror:8 row_mask:0xf bank_mask:0xf
	v_cndmask_b32_e64 v56, v236, v60, s[34:35]
	v_cndmask_b32_e64 v57, v237, v61, s[34:35]
	v_cndmask_b32_e64 v58, v238, v62, s[34:35]
	v_cndmask_b32_e64 v59, v239, v63, s[34:35]
	v_cndmask_b32_e64 v60, v60, v236, s[34:35]
	v_cndmask_b32_e64 v61, v61, v237, s[34:35]
	v_cndmask_b32_e64 v62, v62, v238, s[34:35]
	v_cndmask_b32_e64 v63, v63, v239, s[34:35]
	v_mov_b32_dpp v236, v48 row_ror:8 row_mask:0xf bank_mask:0xf
	v_mov_b32_dpp v237, v49 row_ror:8 row_mask:0xf bank_mask:0xf
	v_mov_b32_dpp v238, v50 row_ror:8 row_mask:0xf bank_mask:0xf
	v_mov_b32_dpp v239, v51 row_ror:8 row_mask:0xf bank_mask:0xf
	v_cndmask_b32_e64 v48, v236, v52, s[34:35]
	v_cndmask_b32_e64 v49, v237, v53, s[34:35]
	v_cndmask_b32_e64 v50, v238, v54, s[34:35]
	v_cndmask_b32_e64 v51, v239, v55, s[34:35]
	v_cndmask_b32_e64 v52, v52, v236, s[34:35]
	v_cndmask_b32_e64 v53, v53, v237, s[34:35]
	v_cndmask_b32_e64 v54, v54, v238, s[34:35]
	v_cndmask_b32_e64 v55, v55, v239, s[34:35]
	s_waitcnt vmcnt(14)
	v_pk_fma_f32 v[58:59], v[58:59], 0.5, v[158:159] op_sel_hi:[1,0,1]
	v_pk_fma_f32 v[56:57], v[56:57], 0.5, v[156:157] op_sel_hi:[1,0,1]
	global_store_dwordx4 v[218:219], v[56:59], off
	v_pk_mul_f32 v[224:225], v[64:65], v[56:57]
	v_pk_mul_f32 v[226:227], v[66:67], v[58:59]
	v_mul_f32_e32 v175, v56, v56
	v_add_u32_e32 v224, 0x8000, v224
	v_add_u32_e32 v225, 0x8000, v225
	v_add_u32_e32 v226, 0x8000, v226
	v_add_u32_e32 v227, 0x8000, v227
	v_fmac_f32_e32 v175, v57, v57
	v_fmac_f32_e32 v175, v58, v58
	v_fmac_f32_e32 v175, v59, v59
	v_perm_b32 v222, v225, v224, s58
	v_perm_b32 v223, v227, v226, s58
	global_store_dwordx2 v[202:203], v[222:223], off
	v_pk_fma_f32 v[50:51], v[50:51], 0.5, v[162:163] op_sel_hi:[1,0,1]
	v_pk_fma_f32 v[48:49], v[48:49], 0.5, v[160:161] op_sel_hi:[1,0,1]
	global_store_dwordx4 v[218:219], v[48:51], off offset:512
	v_pk_mul_f32 v[228:229], v[72:73], v[48:49]
	v_pk_mul_f32 v[230:231], v[74:75], v[50:51]
	v_fmac_f32_e32 v175, v48, v48
	v_add_u32_e32 v228, 0x8000, v228
	v_add_u32_e32 v229, 0x8000, v229
	v_add_u32_e32 v230, 0x8000, v230
	v_add_u32_e32 v231, 0x8000, v231
	v_fmac_f32_e32 v175, v49, v49
	v_fmac_f32_e32 v175, v50, v50
	v_fmac_f32_e32 v175, v51, v51
	v_perm_b32 v232, v229, v228, s58
	v_perm_b32 v233, v231, v230, s58
	global_store_dwordx2 v[202:203], v[232:233], off offset:256
	v_pk_fma_f32 v[62:63], v[62:63], 0.5, v[178:179] op_sel_hi:[1,0,1]
	v_pk_fma_f32 v[60:61], v[60:61], 0.5, v[176:177] op_sel_hi:[1,0,1]
	global_store_dwordx4 v[220:221], v[60:63], off
	v_pk_mul_f32 v[224:225], v[80:81], v[60:61]
	v_pk_mul_f32 v[226:227], v[82:83], v[62:63]
	v_mul_f32_e32 v234, v60, v60
	v_add_u32_e32 v224, 0x8000, v224
	v_add_u32_e32 v225, 0x8000, v225
	v_add_u32_e32 v226, 0x8000, v226
	v_add_u32_e32 v227, 0x8000, v227
	v_fmac_f32_e32 v234, v61, v61
	v_fmac_f32_e32 v234, v62, v62
	v_fmac_f32_e32 v234, v63, v63
	v_perm_b32 v222, v225, v224, s58
	v_perm_b32 v223, v227, v226, s58
	global_store_dwordx2 v[204:205], v[222:223], off
	v_pk_fma_f32 v[54:55], v[54:55], 0.5, v[182:183] op_sel_hi:[1,0,1]
	v_pk_fma_f32 v[52:53], v[52:53], 0.5, v[180:181] op_sel_hi:[1,0,1]
	global_store_dwordx4 v[220:221], v[52:55], off offset:512
	v_pk_mul_f32 v[228:229], v[84:85], v[52:53]
	v_pk_mul_f32 v[230:231], v[86:87], v[54:55]
	v_fmac_f32_e32 v234, v52, v52
	v_add_u32_e32 v228, 0x8000, v228
	v_add_u32_e32 v229, 0x8000, v229
	v_add_u32_e32 v230, 0x8000, v230
	v_add_u32_e32 v231, 0x8000, v231
	v_fmac_f32_e32 v234, v53, v53
	v_fmac_f32_e32 v234, v54, v54
	v_fmac_f32_e32 v234, v55, v55
	v_perm_b32 v232, v229, v228, s58
	v_perm_b32 v233, v231, v230, s58
	global_store_dwordx2 v[204:205], v[232:233], off offset:256
	s_nop 1
	v_mov_b32_dpp v241, v175 row_ror:8 row_mask:0xf bank_mask:0xf
	v_mov_b32_dpp v242, v234 row_ror:8 row_mask:0xf bank_mask:0xf
	v_add_f32_e32 v175, v175, v241
	v_add_f32_e32 v234, v234, v242
	v_cndmask_b32_e64 v175, v234, v175, s[34:35]
	s_nop 0
	ds_bpermute_b32 v241, v235, v175
	global_load_dwordx4 v[156:159], v[164:165], off
	global_load_dwordx4 v[160:163], v[164:165], off offset:512
	global_load_dwordx4 v[176:179], v[200:201], off
	global_load_dwordx4 v[180:183], v[200:201], off offset:512
	s_mov_b64 vcc, 0x20000
	v_lshl_add_u64 v[164:165], v[164:165], 0, vcc
	v_lshl_add_u64 v[200:201], v[200:201], 0, vcc
	s_mov_b64 vcc, 0x20000
	v_lshl_add_u64 v[218:219], v[218:219], 0, vcc
	v_lshl_add_u64 v[220:221], v[220:221], 0, vcc
	s_mov_b64 vcc, 0x10000
	v_lshl_add_u64 v[202:203], v[202:203], 0, vcc
	v_lshl_add_u64 v[204:205], v[204:205], 0, vcc
	s_waitcnt lgkmcnt(0)
	v_add_f32_e32 v175, v175, v241
	s_nop 0
	ds_bpermute_b32 v242, v240, v175
	s_waitcnt lgkmcnt(0)
;     __device__ __forceinline__ void operator()(const f32x4 (&acc)[2][2][4][2], const Unit& u, int wr, int wc, int fr, int fq) const {
;     ...
; #pragma unroll
;         for (int ai = 0; ai < 2; ++ai)
; #pragma unroll
;             for (int m = 0; m < 4; ++m) {
;                 const int row = row0 + ai * HALF + m * 16;
;                 const size_t off = (size_t)row * ldc + col0;
;                 float q = 0.f;
; #pragma unroll
;                 for (int bj = 0; bj < 2; ++bj)
; #pragma unroll
;                     for (int n = 0; n < 2; ++n) {
;                         const f32x4 rv = *(const f32x4*)(rbase + off + bj * HALF + n * 16);
;                         const f32x4 v = rv + acc[ai][bj][m][n] * scale;
;                         if (out) *(f32x4*)(out + off + bj * HALF + n * 16) = v;
;                         if (xn) { q += (v.x * v.x + v.y * v.y) + (v.z * v.z + v.w * v.w); const f32x4 o = v * wv[bj][n];
;                             u32x2 p; p.x = pk2(o.x, o.y); p.y = pk2(o.z, o.w); *(u32x2*)(xn + off + bj * HALF + n * 16) = p; }
;                     }
;                 if (xn) { q += __shfl_xor(q, 16); q += __shfl_xor(q, 32); if (fq == 0) (void)__hip_atomic_fetch_add(ss + row, q, __ATOMIC_RELAXED, __HIP_MEMORY_SCOPE_AGENT); }
;             }
	v_add_f32_e32 v175, v175, v242
	s_mov_b64 exec, s[0:1]
	global_atomic_add_f32 v[206:207], v175, off
	s_mov_b64 exec, -1
	s_mov_b64 vcc, 64
	v_lshl_add_u64 v[206:207], v[206:207], 0, vcc
	v_mov_b32_dpp v236, v40 row_ror:8 row_mask:0xf bank_mask:0xf
	v_mov_b32_dpp v237, v41 row_ror:8 row_mask:0xf bank_mask:0xf
	v_mov_b32_dpp v238, v42 row_ror:8 row_mask:0xf bank_mask:0xf
	v_mov_b32_dpp v239, v43 row_ror:8 row_mask:0xf bank_mask:0xf
	v_cndmask_b32_e64 v40, v236, v44, s[34:35]
	v_cndmask_b32_e64 v41, v237, v45, s[34:35]
	v_cndmask_b32_e64 v42, v238, v46, s[34:35]
	v_cndmask_b32_e64 v43, v239, v47, s[34:35]
	v_cndmask_b32_e64 v44, v44, v236, s[34:35]
	v_cndmask_b32_e64 v45, v45, v237, s[34:35]
	v_cndmask_b32_e64 v46, v46, v238, s[34:35]
	v_cndmask_b32_e64 v47, v47, v239, s[34:35]
	v_mov_b32_dpp v236, v32 row_ror:8 row_mask:0xf bank_mask:0xf
	v_mov_b32_dpp v237, v33 row_ror:8 row_mask:0xf bank_mask:0xf
	v_mov_b32_dpp v238, v34 row_ror:8 row_mask:0xf bank_mask:0xf
	v_mov_b32_dpp v239, v35 row_ror:8 row_mask:0xf bank_mask:0xf
	v_cndmask_b32_e64 v32, v236, v36, s[34:35]
	v_cndmask_b32_e64 v33, v237, v37, s[34:35]
	v_cndmask_b32_e64 v34, v238, v38, s[34:35]
	v_cndmask_b32_e64 v35, v239, v39, s[34:35]
	v_cndmask_b32_e64 v36, v36, v236, s[34:35]
	v_cndmask_b32_e64 v37, v37, v237, s[34:35]
	v_cndmask_b32_e64 v38, v38, v238, s[34:35]
	v_cndmask_b32_e64 v39, v39, v239, s[34:35]
	s_waitcnt vmcnt(14)
	v_pk_fma_f32 v[42:43], v[42:43], 0.5, v[186:187] op_sel_hi:[1,0,1]
	v_pk_fma_f32 v[40:41], v[40:41], 0.5, v[184:185] op_sel_hi:[1,0,1]
	global_store_dwordx4 v[218:219], v[40:43], off
	v_pk_mul_f32 v[224:225], v[64:65], v[40:41]
	v_pk_mul_f32 v[226:227], v[66:67], v[42:43]
	v_mul_f32_e32 v175, v40, v40
	v_add_u32_e32 v224, 0x8000, v224
	v_add_u32_e32 v225, 0x8000, v225
	v_add_u32_e32 v226, 0x8000, v226
	v_add_u32_e32 v227, 0x8000, v227
	v_fmac_f32_e32 v175, v41, v41
	v_fmac_f32_e32 v175, v42, v42
	v_fmac_f32_e32 v175, v43, v43
	v_perm_b32 v222, v225, v224, s58
	v_perm_b32 v223, v227, v226, s58
	global_store_dwordx2 v[202:203], v[222:223], off
	v_pk_fma_f32 v[34:35], v[34:35], 0.5, v[190:191] op_sel_hi:[1,0,1]
	v_pk_fma_f32 v[32:33], v[32:33], 0.5, v[188:189] op_sel_hi:[1,0,1]
	global_store_dwordx4 v[218:219], v[32:35], off offset:512
	v_pk_mul_f32 v[228:229], v[72:73], v[32:33]
	v_pk_mul_f32 v[230:231], v[74:75], v[34:35]
	v_fmac_f32_e32 v175, v32, v32
	v_add_u32_e32 v228, 0x8000, v228
	v_add_u32_e32 v229, 0x8000, v229
	v_add_u32_e32 v230, 0x8000, v230
	v_add_u32_e32 v231, 0x8000, v231
	v_fmac_f32_e32 v175, v33, v33
	v_fmac_f32_e32 v175, v34, v34
	v_fmac_f32_e32 v175, v35, v35
	v_perm_b32 v232, v229, v228, s58
	v_perm_b32 v233, v231, v230, s58
	global_store_dwordx2 v[202:203], v[232:233], off offset:256
	v_pk_fma_f32 v[46:47], v[46:47], 0.5, v[194:195] op_sel_hi:[1,0,1]
	v_pk_fma_f32 v[44:45], v[44:45], 0.5, v[192:193] op_sel_hi:[1,0,1]
	global_store_dwordx4 v[220:221], v[44:47], off
	v_pk_mul_f32 v[224:225], v[80:81], v[44:45]
	v_pk_mul_f32 v[226:227], v[82:83], v[46:47]
	v_mul_f32_e32 v234, v44, v44
	v_add_u32_e32 v224, 0x8000, v224
	v_add_u32_e32 v225, 0x8000, v225
	v_add_u32_e32 v226, 0x8000, v226
	v_add_u32_e32 v227, 0x8000, v227
	v_fmac_f32_e32 v234, v45, v45
	v_fmac_f32_e32 v234, v46, v46
	v_fmac_f32_e32 v234, v47, v47
	v_perm_b32 v222, v225, v224, s58
	v_perm_b32 v223, v227, v226, s58
	global_store_dwordx2 v[204:205], v[222:223], off
	v_pk_fma_f32 v[38:39], v[38:39], 0.5, v[198:199] op_sel_hi:[1,0,1]
	v_pk_fma_f32 v[36:37], v[36:37], 0.5, v[196:197] op_sel_hi:[1,0,1]
	global_store_dwordx4 v[220:221], v[36:39], off offset:512
	v_pk_mul_f32 v[228:229], v[84:85], v[36:37]
	v_pk_mul_f32 v[230:231], v[86:87], v[38:39]
	v_fmac_f32_e32 v234, v36, v36
	v_add_u32_e32 v228, 0x8000, v228
	v_add_u32_e32 v229, 0x8000, v229
	v_add_u32_e32 v230, 0x8000, v230
	v_add_u32_e32 v231, 0x8000, v231
	v_fmac_f32_e32 v234, v37, v37
	v_fmac_f32_e32 v234, v38, v38
	v_fmac_f32_e32 v234, v39, v39
	v_perm_b32 v232, v229, v228, s58
	v_perm_b32 v233, v231, v230, s58
	global_store_dwordx2 v[204:205], v[232:233], off offset:256
	s_nop 1
	v_mov_b32_dpp v241, v175 row_ror:8 row_mask:0xf bank_mask:0xf
	v_mov_b32_dpp v242, v234 row_ror:8 row_mask:0xf bank_mask:0xf
	v_add_f32_e32 v175, v175, v241
	v_add_f32_e32 v234, v234, v242
	v_cndmask_b32_e64 v175, v234, v175, s[34:35]
	s_nop 0
	ds_bpermute_b32 v241, v235, v175
	global_load_dwordx4 v[184:187], v[164:165], off
	global_load_dwordx4 v[188:191], v[164:165], off offset:512
	global_load_dwordx4 v[192:195], v[200:201], off
	global_load_dwordx4 v[196:199], v[200:201], off offset:512
	s_mov_b64 vcc, 0x20000
	v_lshl_add_u64 v[218:219], v[218:219], 0, vcc
	v_lshl_add_u64 v[220:221], v[220:221], 0, vcc
	s_mov_b64 vcc, 0x10000
	v_lshl_add_u64 v[202:203], v[202:203], 0, vcc
	v_lshl_add_u64 v[204:205], v[204:205], 0, vcc
	s_waitcnt lgkmcnt(0)
	v_add_f32_e32 v175, v175, v241
	s_nop 0
	ds_bpermute_b32 v242, v240, v175
	s_waitcnt lgkmcnt(0)
	v_add_f32_e32 v175, v175, v242
	s_mov_b64 exec, s[0:1]
	global_atomic_add_f32 v[206:207], v175, off
	s_mov_b64 exec, -1
	s_mov_b64 vcc, 64
	v_lshl_add_u64 v[206:207], v[206:207], 0, vcc
	v_mov_b32_dpp v236, v24 row_ror:8 row_mask:0xf bank_mask:0xf
	v_mov_b32_dpp v237, v25 row_ror:8 row_mask:0xf bank_mask:0xf
	v_mov_b32_dpp v238, v26 row_ror:8 row_mask:0xf bank_mask:0xf
	v_mov_b32_dpp v239, v27 row_ror:8 row_mask:0xf bank_mask:0xf
	v_cndmask_b32_e64 v24, v236, v28, s[34:35]
	v_cndmask_b32_e64 v25, v237, v29, s[34:35]
	v_cndmask_b32_e64 v26, v238, v30, s[34:35]
	v_cndmask_b32_e64 v27, v239, v31, s[34:35]
	v_cndmask_b32_e64 v28, v28, v236, s[34:35]
	v_cndmask_b32_e64 v29, v29, v237, s[34:35]
	v_cndmask_b32_e64 v30, v30, v238, s[34:35]
	v_cndmask_b32_e64 v31, v31, v239, s[34:35]
	v_mov_b32_dpp v236, v16 row_ror:8 row_mask:0xf bank_mask:0xf
	v_mov_b32_dpp v237, v17 row_ror:8 row_mask:0xf bank_mask:0xf
	v_mov_b32_dpp v238, v18 row_ror:8 row_mask:0xf bank_mask:0xf
	v_mov_b32_dpp v239, v19 row_ror:8 row_mask:0xf bank_mask:0xf
	v_cndmask_b32_e64 v16, v236, v20, s[34:35]
	v_cndmask_b32_e64 v17, v237, v21, s[34:35]
	v_cndmask_b32_e64 v18, v238, v22, s[34:35]
	v_cndmask_b32_e64 v19, v239, v23, s[34:35]
	v_cndmask_b32_e64 v20, v20, v236, s[34:35]
	v_cndmask_b32_e64 v21, v21, v237, s[34:35]
	v_cndmask_b32_e64 v22, v22, v238, s[34:35]
	v_cndmask_b32_e64 v23, v23, v239, s[34:35]
	s_waitcnt vmcnt(14)
;     __device__ __forceinline__ void operator()(const f32x4 (&acc)[2][2][4][2], const Unit& u, int wr, int wc, int fr, int fq) const {
;     ...
; #pragma unroll
;                 for (int bj = 0; bj < 2; ++bj)
; #pragma unroll
;                     for (int n = 0; n < 2; ++n) {
;                         const f32x4 rv = *(const f32x4*)(rbase + off + bj * HALF + n * 16);
;                         const f32x4 v = rv + acc[ai][bj][m][n] * scale;
;                         if (out) *(f32x4*)(out + off + bj * HALF + n * 16) = v;
;                         if (xn) { q += (v.x * v.x + v.y * v.y) + (v.z * v.z + v.w * v.w); const f32x4 o = v * wv[bj][n];
;                             u32x2 p; p.x = pk2(o.x, o.y); p.y = pk2(o.z, o.w); *(u32x2*)(xn + off + bj * HALF + n * 16) = p; }
;                     }
;                 if (xn) { q += __shfl_xor(q, 16); q += __shfl_xor(q, 32); if (fq == 0) (void)__hip_atomic_fetch_add(ss + row, q, __ATOMIC_RELAXED, __HIP_MEMORY_SCOPE_AGENT); }
	v_pk_fma_f32 v[26:27], v[26:27], 0.5, v[158:159] op_sel_hi:[1,0,1]
	v_pk_fma_f32 v[24:25], v[24:25], 0.5, v[156:157] op_sel_hi:[1,0,1]
	global_store_dwordx4 v[218:219], v[24:27], off
	v_pk_mul_f32 v[224:225], v[64:65], v[24:25]
	v_pk_mul_f32 v[226:227], v[66:67], v[26:27]
	v_mul_f32_e32 v175, v24, v24
	v_add_u32_e32 v224, 0x8000, v224
	v_add_u32_e32 v225, 0x8000, v225
	v_add_u32_e32 v226, 0x8000, v226
	v_add_u32_e32 v227, 0x8000, v227
	v_fmac_f32_e32 v175, v25, v25
	v_fmac_f32_e32 v175, v26, v26
	v_fmac_f32_e32 v175, v27, v27
	v_perm_b32 v222, v225, v224, s58
	v_perm_b32 v223, v227, v226, s58
	global_store_dwordx2 v[202:203], v[222:223], off
	v_pk_fma_f32 v[18:19], v[18:19], 0.5, v[162:163] op_sel_hi:[1,0,1]
	v_pk_fma_f32 v[16:17], v[16:17], 0.5, v[160:161] op_sel_hi:[1,0,1]
	global_store_dwordx4 v[218:219], v[16:19], off offset:512
	v_pk_mul_f32 v[228:229], v[72:73], v[16:17]
	v_pk_mul_f32 v[230:231], v[74:75], v[18:19]
	v_fmac_f32_e32 v175, v16, v16
	v_add_u32_e32 v228, 0x8000, v228
	v_add_u32_e32 v229, 0x8000, v229
	v_add_u32_e32 v230, 0x8000, v230
	v_add_u32_e32 v231, 0x8000, v231
	v_fmac_f32_e32 v175, v17, v17
	v_fmac_f32_e32 v175, v18, v18
	v_fmac_f32_e32 v175, v19, v19
	v_perm_b32 v232, v229, v228, s58
	v_perm_b32 v233, v231, v230, s58
	global_store_dwordx2 v[202:203], v[232:233], off offset:256
	v_pk_fma_f32 v[30:31], v[30:31], 0.5, v[178:179] op_sel_hi:[1,0,1]
	v_pk_fma_f32 v[28:29], v[28:29], 0.5, v[176:177] op_sel_hi:[1,0,1]
	global_store_dwordx4 v[220:221], v[28:31], off
	v_pk_mul_f32 v[224:225], v[80:81], v[28:29]
	v_pk_mul_f32 v[226:227], v[82:83], v[30:31]
	v_mul_f32_e32 v234, v28, v28
	v_add_u32_e32 v224, 0x8000, v224
	v_add_u32_e32 v225, 0x8000, v225
	v_add_u32_e32 v226, 0x8000, v226
	v_add_u32_e32 v227, 0x8000, v227
	v_fmac_f32_e32 v234, v29, v29
	v_fmac_f32_e32 v234, v30, v30
	v_fmac_f32_e32 v234, v31, v31
	v_perm_b32 v222, v225, v224, s58
	v_perm_b32 v223, v227, v226, s58
	global_store_dwordx2 v[204:205], v[222:223], off
	v_pk_fma_f32 v[22:23], v[22:23], 0.5, v[182:183] op_sel_hi:[1,0,1]
	v_pk_fma_f32 v[20:21], v[20:21], 0.5, v[180:181] op_sel_hi:[1,0,1]
	global_store_dwordx4 v[220:221], v[20:23], off offset:512
	v_pk_mul_f32 v[228:229], v[84:85], v[20:21]
	v_pk_mul_f32 v[230:231], v[86:87], v[22:23]
	v_fmac_f32_e32 v234, v20, v20
	v_add_u32_e32 v228, 0x8000, v228
	v_add_u32_e32 v229, 0x8000, v229
	v_add_u32_e32 v230, 0x8000, v230
	v_add_u32_e32 v231, 0x8000, v231
	v_fmac_f32_e32 v234, v21, v21
	v_fmac_f32_e32 v234, v22, v22
	v_fmac_f32_e32 v234, v23, v23
	v_perm_b32 v232, v229, v228, s58
	v_perm_b32 v233, v231, v230, s58
	global_store_dwordx2 v[204:205], v[232:233], off offset:256
	s_nop 1
	v_mov_b32_dpp v241, v175 row_ror:8 row_mask:0xf bank_mask:0xf
	v_mov_b32_dpp v242, v234 row_ror:8 row_mask:0xf bank_mask:0xf
	v_add_f32_e32 v175, v175, v241
	v_add_f32_e32 v234, v234, v242
	v_cndmask_b32_e64 v175, v234, v175, s[34:35]
	s_nop 0
	ds_bpermute_b32 v241, v235, v175
	s_mov_b64 vcc, 0x20000
	v_lshl_add_u64 v[218:219], v[218:219], 0, vcc
	v_lshl_add_u64 v[220:221], v[220:221], 0, vcc
	s_mov_b64 vcc, 0x10000
	v_lshl_add_u64 v[202:203], v[202:203], 0, vcc
	v_lshl_add_u64 v[204:205], v[204:205], 0, vcc
	s_waitcnt lgkmcnt(0)
	v_add_f32_e32 v175, v175, v241
	s_nop 0
	ds_bpermute_b32 v242, v240, v175
	s_waitcnt lgkmcnt(0)
;     __device__ __forceinline__ void operator()(const f32x4 (&acc)[2][2][4][2], const Unit& u, int wr, int wc, int fr, int fq) const {
;     ...
; #pragma unroll
;         for (int ai = 0; ai < 2; ++ai)
; #pragma unroll
;             for (int m = 0; m < 4; ++m) {
;                 const int row = row0 + ai * HALF + m * 16;
;                 const size_t off = (size_t)row * ldc + col0;
;                 float q = 0.f;
; #pragma unroll
;                 for (int bj = 0; bj < 2; ++bj)
; #pragma unroll
;                     for (int n = 0; n < 2; ++n) {
;                         const f32x4 rv = *(const f32x4*)(rbase + off + bj * HALF + n * 16);
;                         const f32x4 v = rv + acc[ai][bj][m][n] * scale;
;                         if (out) *(f32x4*)(out + off + bj * HALF + n * 16) = v;
;                         if (xn) { q += (v.x * v.x + v.y * v.y) + (v.z * v.z + v.w * v.w); const f32x4 o = v * wv[bj][n];
;                             u32x2 p; p.x = pk2(o.x, o.y); p.y = pk2(o.z, o.w); *(u32x2*)(xn + off + bj * HALF + n * 16) = p; }
;                     }
;                 if (xn) { q += __shfl_xor(q, 16); q += __shfl_xor(q, 32); if (fq == 0) (void)__hip_atomic_fetch_add(ss + row, q, __ATOMIC_RELAXED, __HIP_MEMORY_SCOPE_AGENT); }
;             }
	v_add_f32_e32 v175, v175, v242
	s_mov_b64 exec, s[0:1]
	global_atomic_add_f32 v[206:207], v175, off
	s_mov_b64 exec, -1
	s_mov_b64 vcc, 64
	v_lshl_add_u64 v[206:207], v[206:207], 0, vcc
	v_mov_b32_dpp v236, v8 row_ror:8 row_mask:0xf bank_mask:0xf
	v_mov_b32_dpp v237, v9 row_ror:8 row_mask:0xf bank_mask:0xf
	v_mov_b32_dpp v238, v10 row_ror:8 row_mask:0xf bank_mask:0xf
	v_mov_b32_dpp v239, v11 row_ror:8 row_mask:0xf bank_mask:0xf
	v_cndmask_b32_e64 v8, v236, v12, s[34:35]
	v_cndmask_b32_e64 v9, v237, v13, s[34:35]
	v_cndmask_b32_e64 v10, v238, v14, s[34:35]
	v_cndmask_b32_e64 v11, v239, v15, s[34:35]
	v_cndmask_b32_e64 v12, v12, v236, s[34:35]
	v_cndmask_b32_e64 v13, v13, v237, s[34:35]
	v_cndmask_b32_e64 v14, v14, v238, s[34:35]
	v_cndmask_b32_e64 v15, v15, v239, s[34:35]
	v_mov_b32_dpp v236, v0 row_ror:8 row_mask:0xf bank_mask:0xf
	v_mov_b32_dpp v237, v1 row_ror:8 row_mask:0xf bank_mask:0xf
	v_mov_b32_dpp v238, v2 row_ror:8 row_mask:0xf bank_mask:0xf
	v_mov_b32_dpp v239, v3 row_ror:8 row_mask:0xf bank_mask:0xf
	v_cndmask_b32_e64 v0, v236, v4, s[34:35]
	v_cndmask_b32_e64 v1, v237, v5, s[34:35]
	v_cndmask_b32_e64 v2, v238, v6, s[34:35]
	v_cndmask_b32_e64 v3, v239, v7, s[34:35]
	v_cndmask_b32_e64 v4, v4, v236, s[34:35]
	v_cndmask_b32_e64 v5, v5, v237, s[34:35]
	v_cndmask_b32_e64 v6, v6, v238, s[34:35]
	v_cndmask_b32_e64 v7, v7, v239, s[34:35]
	s_waitcnt vmcnt(10)
	v_pk_fma_f32 v[10:11], v[10:11], 0.5, v[186:187] op_sel_hi:[1,0,1]
	v_pk_fma_f32 v[8:9], v[8:9], 0.5, v[184:185] op_sel_hi:[1,0,1]
	global_store_dwordx4 v[218:219], v[8:11], off
	v_pk_mul_f32 v[224:225], v[64:65], v[8:9]
	v_pk_mul_f32 v[226:227], v[66:67], v[10:11]
	v_mul_f32_e32 v175, v8, v8
	v_add_u32_e32 v224, 0x8000, v224
	v_add_u32_e32 v225, 0x8000, v225
	v_add_u32_e32 v226, 0x8000, v226
	v_add_u32_e32 v227, 0x8000, v227
	v_fmac_f32_e32 v175, v9, v9
	v_fmac_f32_e32 v175, v10, v10
	v_fmac_f32_e32 v175, v11, v11
	v_perm_b32 v222, v225, v224, s58
	v_perm_b32 v223, v227, v226, s58
	global_store_dwordx2 v[202:203], v[222:223], off
	v_pk_fma_f32 v[2:3], v[2:3], 0.5, v[190:191] op_sel_hi:[1,0,1]
	v_pk_fma_f32 v[0:1], v[0:1], 0.5, v[188:189] op_sel_hi:[1,0,1]
	global_store_dwordx4 v[218:219], v[0:3], off offset:512
	v_pk_mul_f32 v[228:229], v[72:73], v[0:1]
	v_pk_mul_f32 v[230:231], v[74:75], v[2:3]
	v_fmac_f32_e32 v175, v0, v0
	v_add_u32_e32 v228, 0x8000, v228
	v_add_u32_e32 v229, 0x8000, v229
	v_add_u32_e32 v230, 0x8000, v230
	v_add_u32_e32 v231, 0x8000, v231
	v_fmac_f32_e32 v175, v1, v1
	v_fmac_f32_e32 v175, v2, v2
	v_fmac_f32_e32 v175, v3, v3
	v_perm_b32 v232, v229, v228, s58
	v_perm_b32 v233, v231, v230, s58
	global_store_dwordx2 v[202:203], v[232:233], off offset:256
	v_pk_fma_f32 v[14:15], v[14:15], 0.5, v[194:195] op_sel_hi:[1,0,1]
	v_pk_fma_f32 v[12:13], v[12:13], 0.5, v[192:193] op_sel_hi:[1,0,1]
	global_store_dwordx4 v[220:221], v[12:15], off
	v_pk_mul_f32 v[224:225], v[80:81], v[12:13]
	v_pk_mul_f32 v[226:227], v[82:83], v[14:15]
	v_mul_f32_e32 v234, v12, v12
	v_add_u32_e32 v224, 0x8000, v224
	v_add_u32_e32 v225, 0x8000, v225
	v_add_u32_e32 v226, 0x8000, v226
	v_add_u32_e32 v227, 0x8000, v227
	v_fmac_f32_e32 v234, v13, v13
	v_fmac_f32_e32 v234, v14, v14
	v_fmac_f32_e32 v234, v15, v15
	v_perm_b32 v222, v225, v224, s58
	v_perm_b32 v223, v227, v226, s58
	global_store_dwordx2 v[204:205], v[222:223], off
	v_pk_fma_f32 v[6:7], v[6:7], 0.5, v[198:199] op_sel_hi:[1,0,1]
	v_pk_fma_f32 v[4:5], v[4:5], 0.5, v[196:197] op_sel_hi:[1,0,1]
	global_store_dwordx4 v[220:221], v[4:7], off offset:512
	v_pk_mul_f32 v[228:229], v[84:85], v[4:5]
	v_pk_mul_f32 v[230:231], v[86:87], v[6:7]
	v_fmac_f32_e32 v234, v4, v4
	v_add_u32_e32 v228, 0x8000, v228
	v_add_u32_e32 v229, 0x8000, v229
	v_add_u32_e32 v230, 0x8000, v230
	v_add_u32_e32 v231, 0x8000, v231
	v_fmac_f32_e32 v234, v5, v5
	v_fmac_f32_e32 v234, v6, v6
	v_fmac_f32_e32 v234, v7, v7
	v_perm_b32 v232, v229, v228, s58
	v_perm_b32 v233, v231, v230, s58
	global_store_dwordx2 v[204:205], v[232:233], off offset:256
	s_nop 1
	v_mov_b32_dpp v241, v175 row_ror:8 row_mask:0xf bank_mask:0xf
	v_mov_b32_dpp v242, v234 row_ror:8 row_mask:0xf bank_mask:0xf
	v_add_f32_e32 v175, v175, v241
	v_add_f32_e32 v234, v234, v242
	v_cndmask_b32_e64 v175, v234, v175, s[34:35]
	s_nop 0
	ds_bpermute_b32 v241, v235, v175
	s_waitcnt lgkmcnt(0)
	v_add_f32_e32 v175, v175, v241
	s_nop 0
	ds_bpermute_b32 v242, v240, v175
	s_waitcnt lgkmcnt(0)
	v_add_f32_e32 v175, v175, v242
	s_mov_b64 exec, s[0:1]
	global_atomic_add_f32 v[206:207], v175, off
	s_mov_b64 exec, -1
	s_and_b64 vcc, exec, s[6:7]
	s_mov_b64 s[4:5], -1
	s_cbranch_vccnz .LBB0_301
	s_andn2_b64 vcc, exec, s[12:13]
	s_cbranch_vccnz .LBB0_300
	s_barrier
	s_branch .LBB0_300

;     __device__ __forceinline__ void operator()(const f32x4 (&acc)[2][2][4][2], const Unit& u, int wr, int wc, int fr, int fq) const {
;         const int row0 = u.pm * BM + wr * 64 + fr, col0 = u.pn * BM + wc * 32 + 4 * fq;
;         const float* rbase = (u.pm * BM < SEQ_P) ? resA : (resB - (size_t)SEQ_P * ldc);
;         f32x4 wv[2][2];
;         if (xn) {
; #pragma unroll
;             for (int bj = 0; bj < 2; ++bj)
; #pragma unroll
;                 for (int n = 0; n < 2; ++n) wv[bj][n] = *(const f32x4*)(wn + col0 + bj * HALF + n * 16);
;         }
; #pragma unroll
;         for (int ai = 0; ai < 2; ++ai)
; #pragma unroll
;             for (int m = 0; m < 4; ++m) {
;                 const int row = row0 + ai * HALF + m * 16;
;                 const size_t off = (size_t)row * ldc + col0;
;                 float q = 0.f;
; #pragma unroll
;                 for (int bj = 0; bj < 2; ++bj)
; #pragma unroll
;                     for (int n = 0; n < 2; ++n) {
;                         const f32x4 rv = *(const f32x4*)(rbase + off + bj * HALF + n * 16);
;                         const f32x4 v = rv + acc[ai][bj][m][n] * scale;
;                         if (out) *(f32x4*)(out + off + bj * HALF + n * 16) = v;
;                         if (xn) { q += (v.x * v.x + v.y * v.y) + (v.z * v.z + v.w * v.w); const f32x4 o = v * wv[bj][n];
;                             u32x2 p; p.x = pk2(o.x, o.y); p.y = pk2(o.z, o.w); *(u32x2*)(xn + off + bj * HALF + n * 16) = p; }
;                     }
;                 if (xn) { q += __shfl_xor(q, 16); q += __shfl_xor(q, 32); if (fq == 0) (void)__hip_atomic_fetch_add(ss + row, q, __ATOMIC_RELAXED, __HIP_MEMORY_SCOPE_AGENT); }
;             }
.LBB0_1085:
	v_lshl_add_u32 v212, s34, 8, v164
	v_lshl_or_b32 v214, s4, 8, v168
	v_and_b32_e32 v243, 8, v172
	v_mov_b32_e32 v213, 0
	v_cmp_eq_u32_e64 s[34:35], 0, v243
	v_lshlrev_b32_e32 v173, 1, v243
	v_add_u32_e32 v216, v214, v173
	v_sub_u32_e32 v234, 16, v173
	v_add_u32_e32 v234, v214, v234
	v_mov_b32_e32 v214, v216
	v_mov_b32_e32 v216, v234
	v_mov_b32_e32 v215, 0
	v_mov_b32_e32 v217, 0
	v_sub_u32_e32 v210, v212, v243
	v_mov_b32_e32 v211, 0
	v_lshlrev_b64 v[208:209], 11, v[210:211]
	v_add_u32_e32 v210, 8, v210
	v_lshlrev_b64 v[210:211], 11, v[210:211]
	v_lshl_add_u64 v[208:209], v[208:209], 0, v[214:215]
	v_lshl_add_u64 v[210:211], v[210:211], 0, v[216:217]
	v_lshl_add_u64 v[174:175], v[208:209], 2, s[8:9]
	v_lshl_add_u64 v[200:201], v[210:211], 2, s[8:9]
	v_lshl_add_u64 v[202:203], v[214:215], 2, s[10:11]
	v_lshl_add_u64 v[204:205], v[216:217], 2, s[10:11]
	global_load_dwordx4 v[64:67], v[202:203], off
	global_load_dwordx4 v[72:75], v[202:203], off offset:512
	global_load_dwordx4 v[76:79], v[204:205], off
	global_load_dwordx4 v[84:87], v[204:205], off offset:512
	global_load_dwordx4 v[156:159], v[174:175], off
	global_load_dwordx4 v[160:163], v[174:175], off offset:512
	global_load_dwordx4 v[176:179], v[200:201], off
	global_load_dwordx4 v[180:183], v[200:201], off offset:512
	s_mov_b64 vcc, 0x20000
	v_lshl_add_u64 v[174:175], v[174:175], 0, vcc
	v_lshl_add_u64 v[200:201], v[200:201], 0, vcc
	global_load_dwordx4 v[184:187], v[174:175], off
	global_load_dwordx4 v[188:191], v[174:175], off offset:512
	global_load_dwordx4 v[192:195], v[200:201], off
	global_load_dwordx4 v[196:199], v[200:201], off offset:512
	s_mov_b64 vcc, 0x20000
	v_lshl_add_u64 v[174:175], v[174:175], 0, vcc
	v_lshl_add_u64 v[200:201], v[200:201], 0, vcc
	v_lshl_add_u64 v[218:219], v[208:209], 2, s[8:9]
	v_lshl_add_u64 v[220:221], v[210:211], 2, s[8:9]
	v_lshl_add_u64 v[202:203], v[208:209], 1, s[14:15]
	v_lshl_add_u64 v[204:205], v[210:211], 1, s[14:15]
	v_lshl_add_u64 v[206:207], v[212:213], 2, s[16:17]
	v_xor_b32_e32 v235, 16, v172
	v_xor_b32_e32 v240, 32, v172
	v_lshlrev_b32_e32 v235, 2, v235
	v_lshlrev_b32_e32 v240, 2, v240
	v_mov_b32_dpp v236, v136 row_ror:8 row_mask:0xf bank_mask:0xf
	v_mov_b32_dpp v237, v137 row_ror:8 row_mask:0xf bank_mask:0xf
	v_mov_b32_dpp v238, v138 row_ror:8 row_mask:0xf bank_mask:0xf
	v_mov_b32_dpp v239, v139 row_ror:8 row_mask:0xf bank_mask:0xf
	v_cndmask_b32_e64 v136, v236, v140, s[34:35]
	v_cndmask_b32_e64 v137, v237, v141, s[34:35]
	v_cndmask_b32_e64 v138, v238, v142, s[34:35]
	v_cndmask_b32_e64 v139, v239, v143, s[34:35]
	v_cndmask_b32_e64 v140, v140, v236, s[34:35]
	v_cndmask_b32_e64 v141, v141, v237, s[34:35]
	v_cndmask_b32_e64 v142, v142, v238, s[34:35]
	v_cndmask_b32_e64 v143, v143, v239, s[34:35]
	v_mov_b32_dpp v236, v128 row_ror:8 row_mask:0xf bank_mask:0xf
	v_mov_b32_dpp v237, v129 row_ror:8 row_mask:0xf bank_mask:0xf
	v_mov_b32_dpp v238, v130 row_ror:8 row_mask:0xf bank_mask:0xf
	v_mov_b32_dpp v239, v131 row_ror:8 row_mask:0xf bank_mask:0xf
	v_cndmask_b32_e64 v128, v236, v132, s[34:35]
	v_cndmask_b32_e64 v129, v237, v133, s[34:35]
	v_cndmask_b32_e64 v130, v238, v134, s[34:35]
	v_cndmask_b32_e64 v131, v239, v135, s[34:35]
	v_cndmask_b32_e64 v132, v132, v236, s[34:35]
	v_cndmask_b32_e64 v133, v133, v237, s[34:35]
	v_cndmask_b32_e64 v134, v134, v238, s[34:35]
	v_cndmask_b32_e64 v135, v135, v239, s[34:35]
	s_waitcnt vmcnt(4)
	v_pk_add_f32 v[138:139], v[138:139], v[158:159]
	v_pk_add_f32 v[136:137], v[136:137], v[156:157]
	global_store_dwordx4 v[218:219], v[136:139], off
	v_pk_mul_f32 v[224:225], v[64:65], v[136:137]
	v_pk_mul_f32 v[226:227], v[66:67], v[138:139]
	v_mul_f32_e32 v173, v136, v136
	v_add_u32_e32 v224, 0x8000, v224
	v_add_u32_e32 v225, 0x8000, v225
	v_add_u32_e32 v226, 0x8000, v226
	v_add_u32_e32 v227, 0x8000, v227
	v_fmac_f32_e32 v173, v137, v137
	v_fmac_f32_e32 v173, v138, v138
	v_fmac_f32_e32 v173, v139, v139
	v_perm_b32 v222, v225, v224, s58
	v_perm_b32 v223, v227, v226, s58
	global_store_dwordx2 v[202:203], v[222:223], off
	v_pk_add_f32 v[130:131], v[130:131], v[162:163]
	v_pk_add_f32 v[128:129], v[128:129], v[160:161]
	global_store_dwordx4 v[218:219], v[128:131], off offset:512
	v_pk_mul_f32 v[228:229], v[72:73], v[128:129]
	v_pk_mul_f32 v[230:231], v[74:75], v[130:131]
	v_fmac_f32_e32 v173, v128, v128
	v_add_u32_e32 v228, 0x8000, v228
	v_add_u32_e32 v229, 0x8000, v229
	v_add_u32_e32 v230, 0x8000, v230
	v_add_u32_e32 v231, 0x8000, v231
	v_fmac_f32_e32 v173, v129, v129
	v_fmac_f32_e32 v173, v130, v130
	v_fmac_f32_e32 v173, v131, v131
	v_perm_b32 v232, v229, v228, s58
	v_perm_b32 v233, v231, v230, s58
	global_store_dwordx2 v[202:203], v[232:233], off offset:256
	v_pk_add_f32 v[142:143], v[142:143], v[178:179]
	v_pk_add_f32 v[140:141], v[140:141], v[176:177]
	global_store_dwordx4 v[220:221], v[140:143], off
	v_pk_mul_f32 v[224:225], v[76:77], v[140:141]
	v_pk_mul_f32 v[226:227], v[78:79], v[142:143]
	v_mul_f32_e32 v234, v140, v140
	v_add_u32_e32 v224, 0x8000, v224
	v_add_u32_e32 v225, 0x8000, v225
	v_add_u32_e32 v226, 0x8000, v226
	v_add_u32_e32 v227, 0x8000, v227
	v_fmac_f32_e32 v234, v141, v141
	v_fmac_f32_e32 v234, v142, v142
	v_fmac_f32_e32 v234, v143, v143
	v_perm_b32 v222, v225, v224, s58
	v_perm_b32 v223, v227, v226, s58
	global_store_dwordx2 v[204:205], v[222:223], off
	v_pk_add_f32 v[134:135], v[134:135], v[182:183]
	v_pk_add_f32 v[132:133], v[132:133], v[180:181]
	global_store_dwordx4 v[220:221], v[132:135], off offset:512
	v_pk_mul_f32 v[228:229], v[84:85], v[132:133]
	v_pk_mul_f32 v[230:231], v[86:87], v[134:135]
	v_fmac_f32_e32 v234, v132, v132
	v_add_u32_e32 v228, 0x8000, v228
	v_add_u32_e32 v229, 0x8000, v229
	v_add_u32_e32 v230, 0x8000, v230
	v_add_u32_e32 v231, 0x8000, v231
	v_fmac_f32_e32 v234, v133, v133
	v_fmac_f32_e32 v234, v134, v134
	v_fmac_f32_e32 v234, v135, v135
	v_perm_b32 v232, v229, v228, s58
	v_perm_b32 v233, v231, v230, s58
	global_store_dwordx2 v[204:205], v[232:233], off offset:256
	s_nop 1
	v_mov_b32_dpp v241, v173 row_ror:8 row_mask:0xf bank_mask:0xf
	v_mov_b32_dpp v242, v234 row_ror:8 row_mask:0xf bank_mask:0xf
	v_add_f32_e32 v173, v173, v241
	v_add_f32_e32 v234, v234, v242
	v_cndmask_b32_e64 v173, v234, v173, s[34:35]
	s_nop 0
	ds_bpermute_b32 v241, v235, v173
	global_load_dwordx4 v[156:159], v[174:175], off
	global_load_dwordx4 v[160:163], v[174:175], off offset:512
	global_load_dwordx4 v[176:179], v[200:201], off
	global_load_dwordx4 v[180:183], v[200:201], off offset:512
	s_mov_b64 vcc, 0x20000
	v_lshl_add_u64 v[174:175], v[174:175], 0, vcc
	v_lshl_add_u64 v[200:201], v[200:201], 0, vcc
	s_mov_b64 vcc, 0x20000
	v_lshl_add_u64 v[218:219], v[218:219], 0, vcc
	v_lshl_add_u64 v[220:221], v[220:221], 0, vcc
	s_mov_b64 vcc, 0x10000
	v_lshl_add_u64 v[202:203], v[202:203], 0, vcc
	v_lshl_add_u64 v[204:205], v[204:205], 0, vcc
	s_waitcnt lgkmcnt(0)
;     __device__ __forceinline__ void operator()(const f32x4 (&acc)[2][2][4][2], const Unit& u, int wr, int wc, int fr, int fq) const {
;     ...
; #pragma unroll
;         for (int ai = 0; ai < 2; ++ai)
; #pragma unroll
;             for (int m = 0; m < 4; ++m) {
;                 const int row = row0 + ai * HALF + m * 16;
;                 const size_t off = (size_t)row * ldc + col0;
;                 float q = 0.f;
; #pragma unroll
;                 for (int bj = 0; bj < 2; ++bj)
; #pragma unroll
;                     for (int n = 0; n < 2; ++n) {
;                         const f32x4 rv = *(const f32x4*)(rbase + off + bj * HALF + n * 16);
;                         const f32x4 v = rv + acc[ai][bj][m][n] * scale;
;                         if (out) *(f32x4*)(out + off + bj * HALF + n * 16) = v;
;                         if (xn) { q += (v.x * v.x + v.y * v.y) + (v.z * v.z + v.w * v.w); const f32x4 o = v * wv[bj][n];
;                             u32x2 p; p.x = pk2(o.x, o.y); p.y = pk2(o.z, o.w); *(u32x2*)(xn + off + bj * HALF + n * 16) = p; }
;                     }
;                 if (xn) { q += __shfl_xor(q, 16); q += __shfl_xor(q, 32); if (fq == 0) (void)__hip_atomic_fetch_add(ss + row, q, __ATOMIC_RELAXED, __HIP_MEMORY_SCOPE_AGENT); }
;             }
	v_add_f32_e32 v173, v173, v241
	s_nop 0
	ds_bpermute_b32 v242, v240, v173
	s_waitcnt lgkmcnt(0)
	v_add_f32_e32 v173, v173, v242
	s_mov_b64 exec, s[0:1]
	global_atomic_add_f32 v[206:207], v173, off
	s_mov_b64 exec, -1
	s_mov_b64 vcc, 64
	v_lshl_add_u64 v[206:207], v[206:207], 0, vcc
	v_mov_b32_dpp v236, v120 row_ror:8 row_mask:0xf bank_mask:0xf
	v_mov_b32_dpp v237, v121 row_ror:8 row_mask:0xf bank_mask:0xf
	v_mov_b32_dpp v238, v122 row_ror:8 row_mask:0xf bank_mask:0xf
	v_mov_b32_dpp v239, v123 row_ror:8 row_mask:0xf bank_mask:0xf
	v_cndmask_b32_e64 v120, v236, v124, s[34:35]
	v_cndmask_b32_e64 v121, v237, v125, s[34:35]
	v_cndmask_b32_e64 v122, v238, v126, s[34:35]
	v_cndmask_b32_e64 v123, v239, v127, s[34:35]
	v_cndmask_b32_e64 v124, v124, v236, s[34:35]
	v_cndmask_b32_e64 v125, v125, v237, s[34:35]
	v_cndmask_b32_e64 v126, v126, v238, s[34:35]
	v_cndmask_b32_e64 v127, v127, v239, s[34:35]
	v_mov_b32_dpp v236, v112 row_ror:8 row_mask:0xf bank_mask:0xf
	v_mov_b32_dpp v237, v113 row_ror:8 row_mask:0xf bank_mask:0xf
	v_mov_b32_dpp v238, v114 row_ror:8 row_mask:0xf bank_mask:0xf
	v_mov_b32_dpp v239, v115 row_ror:8 row_mask:0xf bank_mask:0xf
	v_cndmask_b32_e64 v112, v236, v116, s[34:35]
	v_cndmask_b32_e64 v113, v237, v117, s[34:35]
	v_cndmask_b32_e64 v114, v238, v118, s[34:35]
	v_cndmask_b32_e64 v115, v239, v119, s[34:35]
	v_cndmask_b32_e64 v116, v116, v236, s[34:35]
	v_cndmask_b32_e64 v117, v117, v237, s[34:35]
	v_cndmask_b32_e64 v118, v118, v238, s[34:35]
	v_cndmask_b32_e64 v119, v119, v239, s[34:35]
	s_waitcnt vmcnt(13)
	v_pk_add_f32 v[122:123], v[122:123], v[186:187]
	v_pk_add_f32 v[120:121], v[120:121], v[184:185]
	global_store_dwordx4 v[218:219], v[120:123], off
	v_pk_mul_f32 v[224:225], v[64:65], v[120:121]
	v_pk_mul_f32 v[226:227], v[66:67], v[122:123]
	v_mul_f32_e32 v173, v120, v120
	v_add_u32_e32 v224, 0x8000, v224
	v_add_u32_e32 v225, 0x8000, v225
	v_add_u32_e32 v226, 0x8000, v226
	v_add_u32_e32 v227, 0x8000, v227
	v_fmac_f32_e32 v173, v121, v121
	v_fmac_f32_e32 v173, v122, v122
	v_fmac_f32_e32 v173, v123, v123
	v_perm_b32 v222, v225, v224, s58
	v_perm_b32 v223, v227, v226, s58
	global_store_dwordx2 v[202:203], v[222:223], off
	v_pk_add_f32 v[114:115], v[114:115], v[190:191]
	v_pk_add_f32 v[112:113], v[112:113], v[188:189]
	global_store_dwordx4 v[218:219], v[112:115], off offset:512
	v_pk_mul_f32 v[228:229], v[72:73], v[112:113]
	v_pk_mul_f32 v[230:231], v[74:75], v[114:115]
	v_fmac_f32_e32 v173, v112, v112
	v_add_u32_e32 v228, 0x8000, v228
	v_add_u32_e32 v229, 0x8000, v229
	v_add_u32_e32 v230, 0x8000, v230
	v_add_u32_e32 v231, 0x8000, v231
	v_fmac_f32_e32 v173, v113, v113
	v_fmac_f32_e32 v173, v114, v114
	v_fmac_f32_e32 v173, v115, v115
	v_perm_b32 v232, v229, v228, s58
	v_perm_b32 v233, v231, v230, s58
	global_store_dwordx2 v[202:203], v[232:233], off offset:256
	v_pk_add_f32 v[126:127], v[126:127], v[194:195]
	v_pk_add_f32 v[124:125], v[124:125], v[192:193]
	global_store_dwordx4 v[220:221], v[124:127], off
	v_pk_mul_f32 v[224:225], v[76:77], v[124:125]
	v_pk_mul_f32 v[226:227], v[78:79], v[126:127]
	v_mul_f32_e32 v234, v124, v124
	v_add_u32_e32 v224, 0x8000, v224
	v_add_u32_e32 v225, 0x8000, v225
	v_add_u32_e32 v226, 0x8000, v226
	v_add_u32_e32 v227, 0x8000, v227
	v_fmac_f32_e32 v234, v125, v125
	v_fmac_f32_e32 v234, v126, v126
	v_fmac_f32_e32 v234, v127, v127
	v_perm_b32 v222, v225, v224, s58
	v_perm_b32 v223, v227, v226, s58
	global_store_dwordx2 v[204:205], v[222:223], off
	v_pk_add_f32 v[118:119], v[118:119], v[198:199]
	v_pk_add_f32 v[116:117], v[116:117], v[196:197]
	global_store_dwordx4 v[220:221], v[116:119], off offset:512
	v_pk_mul_f32 v[228:229], v[84:85], v[116:117]
	v_pk_mul_f32 v[230:231], v[86:87], v[118:119]
	v_fmac_f32_e32 v234, v116, v116
	v_add_u32_e32 v228, 0x8000, v228
	v_add_u32_e32 v229, 0x8000, v229
	v_add_u32_e32 v230, 0x8000, v230
	v_add_u32_e32 v231, 0x8000, v231
	v_fmac_f32_e32 v234, v117, v117
	v_fmac_f32_e32 v234, v118, v118
	v_fmac_f32_e32 v234, v119, v119
	v_perm_b32 v232, v229, v228, s58
	v_perm_b32 v233, v231, v230, s58
	global_store_dwordx2 v[204:205], v[232:233], off offset:256
	s_nop 1
	v_mov_b32_dpp v241, v173 row_ror:8 row_mask:0xf bank_mask:0xf
	v_mov_b32_dpp v242, v234 row_ror:8 row_mask:0xf bank_mask:0xf
	v_add_f32_e32 v173, v173, v241
	v_add_f32_e32 v234, v234, v242
	v_cndmask_b32_e64 v173, v234, v173, s[34:35]
	s_nop 0
	ds_bpermute_b32 v241, v235, v173
	global_load_dwordx4 v[184:187], v[174:175], off
	global_load_dwordx4 v[188:191], v[174:175], off offset:512
	global_load_dwordx4 v[192:195], v[200:201], off
	global_load_dwordx4 v[196:199], v[200:201], off offset:512
	s_mov_b64 vcc, 0xa0000
	v_lshl_add_u64 v[174:175], v[174:175], 0, vcc
	v_lshl_add_u64 v[200:201], v[200:201], 0, vcc
	s_mov_b64 vcc, 0x20000
	v_lshl_add_u64 v[218:219], v[218:219], 0, vcc
	v_lshl_add_u64 v[220:221], v[220:221], 0, vcc
	s_mov_b64 vcc, 0x10000
	v_lshl_add_u64 v[202:203], v[202:203], 0, vcc
	v_lshl_add_u64 v[204:205], v[204:205], 0, vcc
	s_waitcnt lgkmcnt(0)
	v_add_f32_e32 v173, v173, v241
	s_nop 0
	ds_bpermute_b32 v242, v240, v173
	s_waitcnt lgkmcnt(0)
;     __device__ __forceinline__ void operator()(const f32x4 (&acc)[2][2][4][2], const Unit& u, int wr, int wc, int fr, int fq) const {
;     ...
; #pragma unroll
;         for (int ai = 0; ai < 2; ++ai)
; #pragma unroll
;             for (int m = 0; m < 4; ++m) {
;                 const int row = row0 + ai * HALF + m * 16;
;                 const size_t off = (size_t)row * ldc + col0;
;                 float q = 0.f;
; #pragma unroll
;                 for (int bj = 0; bj < 2; ++bj)
; #pragma unroll
;                     for (int n = 0; n < 2; ++n) {
;                         const f32x4 rv = *(const f32x4*)(rbase + off + bj * HALF + n * 16);
;                         const f32x4 v = rv + acc[ai][bj][m][n] * scale;
;                         if (out) *(f32x4*)(out + off + bj * HALF + n * 16) = v;
;                         if (xn) { q += (v.x * v.x + v.y * v.y) + (v.z * v.z + v.w * v.w); const f32x4 o = v * wv[bj][n];
;                             u32x2 p; p.x = pk2(o.x, o.y); p.y = pk2(o.z, o.w); *(u32x2*)(xn + off + bj * HALF + n * 16) = p; }
;                     }
;                 if (xn) { q += __shfl_xor(q, 16); q += __shfl_xor(q, 32); if (fq == 0) (void)__hip_atomic_fetch_add(ss + row, q, __ATOMIC_RELAXED, __HIP_MEMORY_SCOPE_AGENT); }
;             }
	v_add_f32_e32 v173, v173, v242
	s_mov_b64 exec, s[0:1]
	global_atomic_add_f32 v[206:207], v173, off
	s_mov_b64 exec, -1
	s_mov_b64 vcc, 64
	v_lshl_add_u64 v[206:207], v[206:207], 0, vcc
	v_mov_b32_dpp v236, v104 row_ror:8 row_mask:0xf bank_mask:0xf
	v_mov_b32_dpp v237, v105 row_ror:8 row_mask:0xf bank_mask:0xf
	v_mov_b32_dpp v238, v106 row_ror:8 row_mask:0xf bank_mask:0xf
	v_mov_b32_dpp v239, v107 row_ror:8 row_mask:0xf bank_mask:0xf
	v_cndmask_b32_e64 v104, v236, v108, s[34:35]
	v_cndmask_b32_e64 v105, v237, v109, s[34:35]
	v_cndmask_b32_e64 v106, v238, v110, s[34:35]
	v_cndmask_b32_e64 v107, v239, v111, s[34:35]
	v_cndmask_b32_e64 v108, v108, v236, s[34:35]
	v_cndmask_b32_e64 v109, v109, v237, s[34:35]
	v_cndmask_b32_e64 v110, v110, v238, s[34:35]
	v_cndmask_b32_e64 v111, v111, v239, s[34:35]
	v_mov_b32_dpp v236, v96 row_ror:8 row_mask:0xf bank_mask:0xf
	v_mov_b32_dpp v237, v97 row_ror:8 row_mask:0xf bank_mask:0xf
	v_mov_b32_dpp v238, v98 row_ror:8 row_mask:0xf bank_mask:0xf
	v_mov_b32_dpp v239, v99 row_ror:8 row_mask:0xf bank_mask:0xf
	v_cndmask_b32_e64 v96, v236, v100, s[34:35]
	v_cndmask_b32_e64 v97, v237, v101, s[34:35]
	v_cndmask_b32_e64 v98, v238, v102, s[34:35]
	v_cndmask_b32_e64 v99, v239, v103, s[34:35]
	v_cndmask_b32_e64 v100, v100, v236, s[34:35]
	v_cndmask_b32_e64 v101, v101, v237, s[34:35]
	v_cndmask_b32_e64 v102, v102, v238, s[34:35]
	v_cndmask_b32_e64 v103, v103, v239, s[34:35]
	s_waitcnt vmcnt(14)
	v_pk_add_f32 v[106:107], v[106:107], v[158:159]
	v_pk_add_f32 v[104:105], v[104:105], v[156:157]
	global_store_dwordx4 v[218:219], v[104:107], off
	v_pk_mul_f32 v[224:225], v[64:65], v[104:105]
	v_pk_mul_f32 v[226:227], v[66:67], v[106:107]
	v_mul_f32_e32 v173, v104, v104
	v_add_u32_e32 v224, 0x8000, v224
	v_add_u32_e32 v225, 0x8000, v225
	v_add_u32_e32 v226, 0x8000, v226
	v_add_u32_e32 v227, 0x8000, v227
	v_fmac_f32_e32 v173, v105, v105
	v_fmac_f32_e32 v173, v106, v106
	v_fmac_f32_e32 v173, v107, v107
	v_perm_b32 v222, v225, v224, s58
	v_perm_b32 v223, v227, v226, s58
	global_store_dwordx2 v[202:203], v[222:223], off
	v_pk_add_f32 v[98:99], v[98:99], v[162:163]
	v_pk_add_f32 v[96:97], v[96:97], v[160:161]
	global_store_dwordx4 v[218:219], v[96:99], off offset:512
	v_pk_mul_f32 v[228:229], v[72:73], v[96:97]
	v_pk_mul_f32 v[230:231], v[74:75], v[98:99]
	v_fmac_f32_e32 v173, v96, v96
	v_add_u32_e32 v228, 0x8000, v228
	v_add_u32_e32 v229, 0x8000, v229
	v_add_u32_e32 v230, 0x8000, v230
	v_add_u32_e32 v231, 0x8000, v231
	v_fmac_f32_e32 v173, v97, v97
	v_fmac_f32_e32 v173, v98, v98
	v_fmac_f32_e32 v173, v99, v99
	v_perm_b32 v232, v229, v228, s58
	v_perm_b32 v233, v231, v230, s58
	global_store_dwordx2 v[202:203], v[232:233], off offset:256
	v_pk_add_f32 v[110:111], v[110:111], v[178:179]
	v_pk_add_f32 v[108:109], v[108:109], v[176:177]
	global_store_dwordx4 v[220:221], v[108:111], off
	v_pk_mul_f32 v[224:225], v[76:77], v[108:109]
	v_pk_mul_f32 v[226:227], v[78:79], v[110:111]
	v_mul_f32_e32 v234, v108, v108
	v_add_u32_e32 v224, 0x8000, v224
	v_add_u32_e32 v225, 0x8000, v225
	v_add_u32_e32 v226, 0x8000, v226
	v_add_u32_e32 v227, 0x8000, v227
	v_fmac_f32_e32 v234, v109, v109
	v_fmac_f32_e32 v234, v110, v110
	v_fmac_f32_e32 v234, v111, v111
	v_perm_b32 v222, v225, v224, s58
	v_perm_b32 v223, v227, v226, s58
	global_store_dwordx2 v[204:205], v[222:223], off
	v_pk_add_f32 v[102:103], v[102:103], v[182:183]
	v_pk_add_f32 v[100:101], v[100:101], v[180:181]
	global_store_dwordx4 v[220:221], v[100:103], off offset:512
	v_pk_mul_f32 v[228:229], v[84:85], v[100:101]
	v_pk_mul_f32 v[230:231], v[86:87], v[102:103]
	v_fmac_f32_e32 v234, v100, v100
	v_add_u32_e32 v228, 0x8000, v228
	v_add_u32_e32 v229, 0x8000, v229
	v_add_u32_e32 v230, 0x8000, v230
	v_add_u32_e32 v231, 0x8000, v231
	v_fmac_f32_e32 v234, v101, v101
	v_fmac_f32_e32 v234, v102, v102
	v_fmac_f32_e32 v234, v103, v103
	v_perm_b32 v232, v229, v228, s58
	v_perm_b32 v233, v231, v230, s58
	global_store_dwordx2 v[204:205], v[232:233], off offset:256
	s_nop 1
	v_mov_b32_dpp v241, v173 row_ror:8 row_mask:0xf bank_mask:0xf
	v_mov_b32_dpp v242, v234 row_ror:8 row_mask:0xf bank_mask:0xf
	v_add_f32_e32 v173, v173, v241
	v_add_f32_e32 v234, v234, v242
	v_cndmask_b32_e64 v173, v234, v173, s[34:35]
	s_nop 0
	ds_bpermute_b32 v241, v235, v173
	global_load_dwordx4 v[156:159], v[174:175], off
	global_load_dwordx4 v[160:163], v[174:175], off offset:512
	global_load_dwordx4 v[176:179], v[200:201], off
	global_load_dwordx4 v[180:183], v[200:201], off offset:512
	s_mov_b64 vcc, 0x20000
	v_lshl_add_u64 v[174:175], v[174:175], 0, vcc
	v_lshl_add_u64 v[200:201], v[200:201], 0, vcc
	s_mov_b64 vcc, 0x20000
	v_lshl_add_u64 v[218:219], v[218:219], 0, vcc
	v_lshl_add_u64 v[220:221], v[220:221], 0, vcc
	s_mov_b64 vcc, 0x10000
	v_lshl_add_u64 v[202:203], v[202:203], 0, vcc
	v_lshl_add_u64 v[204:205], v[204:205], 0, vcc
	s_waitcnt lgkmcnt(0)
	v_add_f32_e32 v173, v173, v241
	s_nop 0
	ds_bpermute_b32 v242, v240, v173
	s_waitcnt lgkmcnt(0)
;     __device__ __forceinline__ void operator()(const f32x4 (&acc)[2][2][4][2], const Unit& u, int wr, int wc, int fr, int fq) const {
;     ...
; #pragma unroll
;         for (int ai = 0; ai < 2; ++ai)
; #pragma unroll
;             for (int m = 0; m < 4; ++m) {
;                 const int row = row0 + ai * HALF + m * 16;
;                 const size_t off = (size_t)row * ldc + col0;
;                 float q = 0.f;
; #pragma unroll
;                 for (int bj = 0; bj < 2; ++bj)
; #pragma unroll
;                     for (int n = 0; n < 2; ++n) {
;                         const f32x4 rv = *(const f32x4*)(rbase + off + bj * HALF + n * 16);
;                         const f32x4 v = rv + acc[ai][bj][m][n] * scale;
;                         if (out) *(f32x4*)(out + off + bj * HALF + n * 16) = v;
;                         if (xn) { q += (v.x * v.x + v.y * v.y) + (v.z * v.z + v.w * v.w); const f32x4 o = v * wv[bj][n];
;                             u32x2 p; p.x = pk2(o.x, o.y); p.y = pk2(o.z, o.w); *(u32x2*)(xn + off + bj * HALF + n * 16) = p; }
;                     }
;                 if (xn) { q += __shfl_xor(q, 16); q += __shfl_xor(q, 32); if (fq == 0) (void)__hip_atomic_fetch_add(ss + row, q, __ATOMIC_RELAXED, __HIP_MEMORY_SCOPE_AGENT); }
;             }
	v_add_f32_e32 v173, v173, v242
	s_mov_b64 exec, s[0:1]
	global_atomic_add_f32 v[206:207], v173, off
	s_mov_b64 exec, -1
	s_mov_b64 vcc, 64
	v_lshl_add_u64 v[206:207], v[206:207], 0, vcc
	v_mov_b32_dpp v236, v88 row_ror:8 row_mask:0xf bank_mask:0xf
	v_mov_b32_dpp v237, v89 row_ror:8 row_mask:0xf bank_mask:0xf
	v_mov_b32_dpp v238, v90 row_ror:8 row_mask:0xf bank_mask:0xf
	v_mov_b32_dpp v239, v91 row_ror:8 row_mask:0xf bank_mask:0xf
	v_cndmask_b32_e64 v88, v236, v92, s[34:35]
	v_cndmask_b32_e64 v89, v237, v93, s[34:35]
	v_cndmask_b32_e64 v90, v238, v94, s[34:35]
	v_cndmask_b32_e64 v91, v239, v95, s[34:35]
	v_cndmask_b32_e64 v92, v92, v236, s[34:35]
	v_cndmask_b32_e64 v93, v93, v237, s[34:35]
	v_cndmask_b32_e64 v94, v94, v238, s[34:35]
	v_cndmask_b32_e64 v95, v95, v239, s[34:35]
	v_mov_b32_dpp v236, v68 row_ror:8 row_mask:0xf bank_mask:0xf
	v_mov_b32_dpp v237, v69 row_ror:8 row_mask:0xf bank_mask:0xf
	v_mov_b32_dpp v238, v70 row_ror:8 row_mask:0xf bank_mask:0xf
	v_mov_b32_dpp v239, v71 row_ror:8 row_mask:0xf bank_mask:0xf
	v_cndmask_b32_e64 v68, v236, v80, s[34:35]
	v_cndmask_b32_e64 v69, v237, v81, s[34:35]
	v_cndmask_b32_e64 v70, v238, v82, s[34:35]
	v_cndmask_b32_e64 v71, v239, v83, s[34:35]
	v_cndmask_b32_e64 v80, v80, v236, s[34:35]
	v_cndmask_b32_e64 v81, v81, v237, s[34:35]
	v_cndmask_b32_e64 v82, v82, v238, s[34:35]
	v_cndmask_b32_e64 v83, v83, v239, s[34:35]
	s_waitcnt vmcnt(14)
	v_pk_add_f32 v[90:91], v[90:91], v[186:187]
	v_pk_add_f32 v[88:89], v[88:89], v[184:185]
	global_store_dwordx4 v[218:219], v[88:91], off
	v_pk_mul_f32 v[224:225], v[64:65], v[88:89]
	v_pk_mul_f32 v[226:227], v[66:67], v[90:91]
	v_mul_f32_e32 v173, v88, v88
	v_add_u32_e32 v224, 0x8000, v224
	v_add_u32_e32 v225, 0x8000, v225
	v_add_u32_e32 v226, 0x8000, v226
	v_add_u32_e32 v227, 0x8000, v227
	v_fmac_f32_e32 v173, v89, v89
	v_fmac_f32_e32 v173, v90, v90
	v_fmac_f32_e32 v173, v91, v91
	v_perm_b32 v222, v225, v224, s58
	v_perm_b32 v223, v227, v226, s58
	global_store_dwordx2 v[202:203], v[222:223], off
	v_pk_add_f32 v[70:71], v[70:71], v[190:191]
	v_pk_add_f32 v[68:69], v[68:69], v[188:189]
	global_store_dwordx4 v[218:219], v[68:71], off offset:512
	v_pk_mul_f32 v[228:229], v[72:73], v[68:69]
	v_pk_mul_f32 v[230:231], v[74:75], v[70:71]
	v_fmac_f32_e32 v173, v68, v68
	v_add_u32_e32 v228, 0x8000, v228
	v_add_u32_e32 v229, 0x8000, v229
	v_add_u32_e32 v230, 0x8000, v230
	v_add_u32_e32 v231, 0x8000, v231
	v_fmac_f32_e32 v173, v69, v69
	v_fmac_f32_e32 v173, v70, v70
	v_fmac_f32_e32 v173, v71, v71
	v_perm_b32 v232, v229, v228, s58
	v_perm_b32 v233, v231, v230, s58
	global_store_dwordx2 v[202:203], v[232:233], off offset:256
	v_pk_add_f32 v[94:95], v[94:95], v[194:195]
	v_pk_add_f32 v[92:93], v[92:93], v[192:193]
	global_store_dwordx4 v[220:221], v[92:95], off
	v_pk_mul_f32 v[224:225], v[76:77], v[92:93]
	v_pk_mul_f32 v[226:227], v[78:79], v[94:95]
	v_mul_f32_e32 v234, v92, v92
	v_add_u32_e32 v224, 0x8000, v224
	v_add_u32_e32 v225, 0x8000, v225
	v_add_u32_e32 v226, 0x8000, v226
	v_add_u32_e32 v227, 0x8000, v227
	v_fmac_f32_e32 v234, v93, v93
	v_fmac_f32_e32 v234, v94, v94
	v_fmac_f32_e32 v234, v95, v95
	v_perm_b32 v222, v225, v224, s58
	v_perm_b32 v223, v227, v226, s58
	global_store_dwordx2 v[204:205], v[222:223], off
	v_pk_add_f32 v[82:83], v[82:83], v[198:199]
	v_pk_add_f32 v[80:81], v[80:81], v[196:197]
	global_store_dwordx4 v[220:221], v[80:83], off offset:512
	v_pk_mul_f32 v[228:229], v[84:85], v[80:81]
	v_pk_mul_f32 v[230:231], v[86:87], v[82:83]
	v_fmac_f32_e32 v234, v80, v80
	v_add_u32_e32 v228, 0x8000, v228
	v_add_u32_e32 v229, 0x8000, v229
	v_add_u32_e32 v230, 0x8000, v230
	v_add_u32_e32 v231, 0x8000, v231
	v_fmac_f32_e32 v234, v81, v81
	v_fmac_f32_e32 v234, v82, v82
	v_fmac_f32_e32 v234, v83, v83
	v_perm_b32 v232, v229, v228, s58
	v_perm_b32 v233, v231, v230, s58
	global_store_dwordx2 v[204:205], v[232:233], off offset:256
	s_nop 1
	v_mov_b32_dpp v241, v173 row_ror:8 row_mask:0xf bank_mask:0xf
	v_mov_b32_dpp v242, v234 row_ror:8 row_mask:0xf bank_mask:0xf
	v_add_f32_e32 v173, v173, v241
	v_add_f32_e32 v234, v234, v242
	v_cndmask_b32_e64 v173, v234, v173, s[34:35]
	s_nop 0
	ds_bpermute_b32 v241, v235, v173
	global_load_dwordx4 v[184:187], v[174:175], off
	global_load_dwordx4 v[188:191], v[174:175], off offset:512
	global_load_dwordx4 v[192:195], v[200:201], off
	global_load_dwordx4 v[196:199], v[200:201], off offset:512
	s_mov_b64 vcc, 0x20000
	v_lshl_add_u64 v[174:175], v[174:175], 0, vcc
	v_lshl_add_u64 v[200:201], v[200:201], 0, vcc
	s_mov_b64 vcc, 0xa0000
	v_lshl_add_u64 v[218:219], v[218:219], 0, vcc
	v_lshl_add_u64 v[220:221], v[220:221], 0, vcc
	s_mov_b64 vcc, 0x50000
	v_lshl_add_u64 v[202:203], v[202:203], 0, vcc
	v_lshl_add_u64 v[204:205], v[204:205], 0, vcc
	s_waitcnt lgkmcnt(0)
	v_add_f32_e32 v173, v173, v241
	s_nop 0
	ds_bpermute_b32 v242, v240, v173
	s_waitcnt lgkmcnt(0)
	v_add_f32_e32 v173, v173, v242
	s_mov_b64 exec, s[0:1]
	global_atomic_add_f32 v[206:207], v173, off
	s_mov_b64 exec, -1
	s_mov_b64 vcc, 320
	v_lshl_add_u64 v[206:207], v[206:207], 0, vcc
	v_mov_b32_dpp v236, v56 row_ror:8 row_mask:0xf bank_mask:0xf
	v_mov_b32_dpp v237, v57 row_ror:8 row_mask:0xf bank_mask:0xf
	v_mov_b32_dpp v238, v58 row_ror:8 row_mask:0xf bank_mask:0xf
	v_mov_b32_dpp v239, v59 row_ror:8 row_mask:0xf bank_mask:0xf
	v_cndmask_b32_e64 v56, v236, v60, s[34:35]
	v_cndmask_b32_e64 v57, v237, v61, s[34:35]
	v_cndmask_b32_e64 v58, v238, v62, s[34:35]
	v_cndmask_b32_e64 v59, v239, v63, s[34:35]
	v_cndmask_b32_e64 v60, v60, v236, s[34:35]
	v_cndmask_b32_e64 v61, v61, v237, s[34:35]
	v_cndmask_b32_e64 v62, v62, v238, s[34:35]
	v_cndmask_b32_e64 v63, v63, v239, s[34:35]
	v_mov_b32_dpp v236, v48 row_ror:8 row_mask:0xf bank_mask:0xf
	v_mov_b32_dpp v237, v49 row_ror:8 row_mask:0xf bank_mask:0xf
	v_mov_b32_dpp v238, v50 row_ror:8 row_mask:0xf bank_mask:0xf
	v_mov_b32_dpp v239, v51 row_ror:8 row_mask:0xf bank_mask:0xf
	v_cndmask_b32_e64 v48, v236, v52, s[34:35]
	v_cndmask_b32_e64 v49, v237, v53, s[34:35]
	v_cndmask_b32_e64 v50, v238, v54, s[34:35]
	v_cndmask_b32_e64 v51, v239, v55, s[34:35]
	v_cndmask_b32_e64 v52, v52, v236, s[34:35]
	v_cndmask_b32_e64 v53, v53, v237, s[34:35]
	v_cndmask_b32_e64 v54, v54, v238, s[34:35]
	v_cndmask_b32_e64 v55, v55, v239, s[34:35]
	s_waitcnt vmcnt(14)
;     __device__ __forceinline__ void operator()(const f32x4 (&acc)[2][2][4][2], const Unit& u, int wr, int wc, int fr, int fq) const {
;     ...
; #pragma unroll
;         for (int ai = 0; ai < 2; ++ai)
; #pragma unroll
;             for (int m = 0; m < 4; ++m) {
;                 const int row = row0 + ai * HALF + m * 16;
;                 const size_t off = (size_t)row * ldc + col0;
;                 float q = 0.f;
; #pragma unroll
;                 for (int bj = 0; bj < 2; ++bj)
; #pragma unroll
;                     for (int n = 0; n < 2; ++n) {
;                         const f32x4 rv = *(const f32x4*)(rbase + off + bj * HALF + n * 16);
;                         const f32x4 v = rv + acc[ai][bj][m][n] * scale;
;                         if (out) *(f32x4*)(out + off + bj * HALF + n * 16) = v;
;                         if (xn) { q += (v.x * v.x + v.y * v.y) + (v.z * v.z + v.w * v.w); const f32x4 o = v * wv[bj][n];
;                             u32x2 p; p.x = pk2(o.x, o.y); p.y = pk2(o.z, o.w); *(u32x2*)(xn + off + bj * HALF + n * 16) = p; }
;                     }
;                 if (xn) { q += __shfl_xor(q, 16); q += __shfl_xor(q, 32); if (fq == 0) (void)__hip_atomic_fetch_add(ss + row, q, __ATOMIC_RELAXED, __HIP_MEMORY_SCOPE_AGENT); }
;             }
	v_pk_add_f32 v[58:59], v[58:59], v[158:159]
	v_pk_add_f32 v[56:57], v[56:57], v[156:157]
	global_store_dwordx4 v[218:219], v[56:59], off
	v_pk_mul_f32 v[224:225], v[64:65], v[56:57]
	v_pk_mul_f32 v[226:227], v[66:67], v[58:59]
	v_mul_f32_e32 v173, v56, v56
	v_add_u32_e32 v224, 0x8000, v224
	v_add_u32_e32 v225, 0x8000, v225
	v_add_u32_e32 v226, 0x8000, v226
	v_add_u32_e32 v227, 0x8000, v227
	v_fmac_f32_e32 v173, v57, v57
	v_fmac_f32_e32 v173, v58, v58
	v_fmac_f32_e32 v173, v59, v59
	v_perm_b32 v222, v225, v224, s58
	v_perm_b32 v223, v227, v226, s58
	global_store_dwordx2 v[202:203], v[222:223], off
	v_pk_add_f32 v[50:51], v[50:51], v[162:163]
	v_pk_add_f32 v[48:49], v[48:49], v[160:161]
	global_store_dwordx4 v[218:219], v[48:51], off offset:512
	v_pk_mul_f32 v[228:229], v[72:73], v[48:49]
	v_pk_mul_f32 v[230:231], v[74:75], v[50:51]
	v_fmac_f32_e32 v173, v48, v48
	v_add_u32_e32 v228, 0x8000, v228
	v_add_u32_e32 v229, 0x8000, v229
	v_add_u32_e32 v230, 0x8000, v230
	v_add_u32_e32 v231, 0x8000, v231
	v_fmac_f32_e32 v173, v49, v49
	v_fmac_f32_e32 v173, v50, v50
	v_fmac_f32_e32 v173, v51, v51
	v_perm_b32 v232, v229, v228, s58
	v_perm_b32 v233, v231, v230, s58
	global_store_dwordx2 v[202:203], v[232:233], off offset:256
	v_pk_add_f32 v[62:63], v[62:63], v[178:179]
	v_pk_add_f32 v[60:61], v[60:61], v[176:177]
	global_store_dwordx4 v[220:221], v[60:63], off
	v_pk_mul_f32 v[224:225], v[76:77], v[60:61]
	v_pk_mul_f32 v[226:227], v[78:79], v[62:63]
	v_mul_f32_e32 v234, v60, v60
	v_add_u32_e32 v224, 0x8000, v224
	v_add_u32_e32 v225, 0x8000, v225
	v_add_u32_e32 v226, 0x8000, v226
	v_add_u32_e32 v227, 0x8000, v227
	v_fmac_f32_e32 v234, v61, v61
	v_fmac_f32_e32 v234, v62, v62
	v_fmac_f32_e32 v234, v63, v63
	v_perm_b32 v222, v225, v224, s58
	v_perm_b32 v223, v227, v226, s58
	global_store_dwordx2 v[204:205], v[222:223], off
	v_pk_add_f32 v[54:55], v[54:55], v[182:183]
	v_pk_add_f32 v[52:53], v[52:53], v[180:181]
	global_store_dwordx4 v[220:221], v[52:55], off offset:512
	v_pk_mul_f32 v[228:229], v[84:85], v[52:53]
	v_pk_mul_f32 v[230:231], v[86:87], v[54:55]
	v_fmac_f32_e32 v234, v52, v52
	v_add_u32_e32 v228, 0x8000, v228
	v_add_u32_e32 v229, 0x8000, v229
	v_add_u32_e32 v230, 0x8000, v230
	v_add_u32_e32 v231, 0x8000, v231
	v_fmac_f32_e32 v234, v53, v53
	v_fmac_f32_e32 v234, v54, v54
	v_fmac_f32_e32 v234, v55, v55
	v_perm_b32 v232, v229, v228, s58
	v_perm_b32 v233, v231, v230, s58
	global_store_dwordx2 v[204:205], v[232:233], off offset:256
	s_nop 1
	v_mov_b32_dpp v241, v173 row_ror:8 row_mask:0xf bank_mask:0xf
	v_mov_b32_dpp v242, v234 row_ror:8 row_mask:0xf bank_mask:0xf
	v_add_f32_e32 v173, v173, v241
	v_add_f32_e32 v234, v234, v242
	v_cndmask_b32_e64 v173, v234, v173, s[34:35]
	s_nop 0
	ds_bpermute_b32 v241, v235, v173
	global_load_dwordx4 v[156:159], v[174:175], off
	global_load_dwordx4 v[160:163], v[174:175], off offset:512
	global_load_dwordx4 v[176:179], v[200:201], off
	global_load_dwordx4 v[180:183], v[200:201], off offset:512
	s_mov_b64 vcc, 0x20000
	v_lshl_add_u64 v[174:175], v[174:175], 0, vcc
	v_lshl_add_u64 v[200:201], v[200:201], 0, vcc
	s_mov_b64 vcc, 0x20000
	v_lshl_add_u64 v[218:219], v[218:219], 0, vcc
	v_lshl_add_u64 v[220:221], v[220:221], 0, vcc
	s_mov_b64 vcc, 0x10000
	v_lshl_add_u64 v[202:203], v[202:203], 0, vcc
	v_lshl_add_u64 v[204:205], v[204:205], 0, vcc
	s_waitcnt lgkmcnt(0)
	v_add_f32_e32 v173, v173, v241
	s_nop 0
	ds_bpermute_b32 v242, v240, v173
	s_waitcnt lgkmcnt(0)
	v_add_f32_e32 v173, v173, v242
	s_mov_b64 exec, s[0:1]
	global_atomic_add_f32 v[206:207], v173, off
	s_mov_b64 exec, -1
	s_mov_b64 vcc, 64
	v_lshl_add_u64 v[206:207], v[206:207], 0, vcc
	v_mov_b32_dpp v236, v40 row_ror:8 row_mask:0xf bank_mask:0xf
	v_mov_b32_dpp v237, v41 row_ror:8 row_mask:0xf bank_mask:0xf
	v_mov_b32_dpp v238, v42 row_ror:8 row_mask:0xf bank_mask:0xf
	v_mov_b32_dpp v239, v43 row_ror:8 row_mask:0xf bank_mask:0xf
	v_cndmask_b32_e64 v40, v236, v44, s[34:35]
	v_cndmask_b32_e64 v41, v237, v45, s[34:35]
	v_cndmask_b32_e64 v42, v238, v46, s[34:35]
	v_cndmask_b32_e64 v43, v239, v47, s[34:35]
	v_cndmask_b32_e64 v44, v44, v236, s[34:35]
	v_cndmask_b32_e64 v45, v45, v237, s[34:35]
	v_cndmask_b32_e64 v46, v46, v238, s[34:35]
	v_cndmask_b32_e64 v47, v47, v239, s[34:35]
	v_mov_b32_dpp v236, v32 row_ror:8 row_mask:0xf bank_mask:0xf
	v_mov_b32_dpp v237, v33 row_ror:8 row_mask:0xf bank_mask:0xf
	v_mov_b32_dpp v238, v34 row_ror:8 row_mask:0xf bank_mask:0xf
	v_mov_b32_dpp v239, v35 row_ror:8 row_mask:0xf bank_mask:0xf
	v_cndmask_b32_e64 v32, v236, v36, s[34:35]
	v_cndmask_b32_e64 v33, v237, v37, s[34:35]
	v_cndmask_b32_e64 v34, v238, v38, s[34:35]
	v_cndmask_b32_e64 v35, v239, v39, s[34:35]
	v_cndmask_b32_e64 v36, v36, v236, s[34:35]
	v_cndmask_b32_e64 v37, v37, v237, s[34:35]
	v_cndmask_b32_e64 v38, v38, v238, s[34:35]
	v_cndmask_b32_e64 v39, v39, v239, s[34:35]
	s_waitcnt vmcnt(14)
;     __device__ __forceinline__ void operator()(const f32x4 (&acc)[2][2][4][2], const Unit& u, int wr, int wc, int fr, int fq) const {
;     ...
; #pragma unroll
;         for (int ai = 0; ai < 2; ++ai)
; #pragma unroll
;             for (int m = 0; m < 4; ++m) {
;                 const int row = row0 + ai * HALF + m * 16;
;                 const size_t off = (size_t)row * ldc + col0;
;                 float q = 0.f;
; #pragma unroll
;                 for (int bj = 0; bj < 2; ++bj)
; #pragma unroll
;                     for (int n = 0; n < 2; ++n) {
;                         const f32x4 rv = *(const f32x4*)(rbase + off + bj * HALF + n * 16);
;                         const f32x4 v = rv + acc[ai][bj][m][n] * scale;
;                         if (out) *(f32x4*)(out + off + bj * HALF + n * 16) = v;
;                         if (xn) { q += (v.x * v.x + v.y * v.y) + (v.z * v.z + v.w * v.w); const f32x4 o = v * wv[bj][n];
;                             u32x2 p; p.x = pk2(o.x, o.y); p.y = pk2(o.z, o.w); *(u32x2*)(xn + off + bj * HALF + n * 16) = p; }
;                     }
;                 if (xn) { q += __shfl_xor(q, 16); q += __shfl_xor(q, 32); if (fq == 0) (void)__hip_atomic_fetch_add(ss + row, q, __ATOMIC_RELAXED, __HIP_MEMORY_SCOPE_AGENT); }
;             }
	v_pk_add_f32 v[42:43], v[42:43], v[186:187]
	v_pk_add_f32 v[40:41], v[40:41], v[184:185]
	global_store_dwordx4 v[218:219], v[40:43], off
	v_pk_mul_f32 v[224:225], v[64:65], v[40:41]
	v_pk_mul_f32 v[226:227], v[66:67], v[42:43]
	v_mul_f32_e32 v173, v40, v40
	v_add_u32_e32 v224, 0x8000, v224
	v_add_u32_e32 v225, 0x8000, v225
	v_add_u32_e32 v226, 0x8000, v226
	v_add_u32_e32 v227, 0x8000, v227
	v_fmac_f32_e32 v173, v41, v41
	v_fmac_f32_e32 v173, v42, v42
	v_fmac_f32_e32 v173, v43, v43
	v_perm_b32 v222, v225, v224, s58
	v_perm_b32 v223, v227, v226, s58
	global_store_dwordx2 v[202:203], v[222:223], off
	v_pk_add_f32 v[34:35], v[34:35], v[190:191]
	v_pk_add_f32 v[32:33], v[32:33], v[188:189]
	global_store_dwordx4 v[218:219], v[32:35], off offset:512
	v_pk_mul_f32 v[228:229], v[72:73], v[32:33]
	v_pk_mul_f32 v[230:231], v[74:75], v[34:35]
	v_fmac_f32_e32 v173, v32, v32
	v_add_u32_e32 v228, 0x8000, v228
	v_add_u32_e32 v229, 0x8000, v229
	v_add_u32_e32 v230, 0x8000, v230
	v_add_u32_e32 v231, 0x8000, v231
	v_fmac_f32_e32 v173, v33, v33
	v_fmac_f32_e32 v173, v34, v34
	v_fmac_f32_e32 v173, v35, v35
	v_perm_b32 v232, v229, v228, s58
	v_perm_b32 v233, v231, v230, s58
	global_store_dwordx2 v[202:203], v[232:233], off offset:256
	v_pk_add_f32 v[46:47], v[46:47], v[194:195]
	v_pk_add_f32 v[44:45], v[44:45], v[192:193]
	global_store_dwordx4 v[220:221], v[44:47], off
	v_pk_mul_f32 v[224:225], v[76:77], v[44:45]
	v_pk_mul_f32 v[226:227], v[78:79], v[46:47]
	v_mul_f32_e32 v234, v44, v44
	v_add_u32_e32 v224, 0x8000, v224
	v_add_u32_e32 v225, 0x8000, v225
	v_add_u32_e32 v226, 0x8000, v226
	v_add_u32_e32 v227, 0x8000, v227
	v_fmac_f32_e32 v234, v45, v45
	v_fmac_f32_e32 v234, v46, v46
	v_fmac_f32_e32 v234, v47, v47
	v_perm_b32 v222, v225, v224, s58
	v_perm_b32 v223, v227, v226, s58
	global_store_dwordx2 v[204:205], v[222:223], off
	v_pk_add_f32 v[38:39], v[38:39], v[198:199]
	v_pk_add_f32 v[36:37], v[36:37], v[196:197]
	global_store_dwordx4 v[220:221], v[36:39], off offset:512
	v_pk_mul_f32 v[228:229], v[84:85], v[36:37]
	v_pk_mul_f32 v[230:231], v[86:87], v[38:39]
	v_fmac_f32_e32 v234, v36, v36
	v_add_u32_e32 v228, 0x8000, v228
	v_add_u32_e32 v229, 0x8000, v229
	v_add_u32_e32 v230, 0x8000, v230
	v_add_u32_e32 v231, 0x8000, v231
	v_fmac_f32_e32 v234, v37, v37
	v_fmac_f32_e32 v234, v38, v38
	v_fmac_f32_e32 v234, v39, v39
	v_perm_b32 v232, v229, v228, s58
	v_perm_b32 v233, v231, v230, s58
	global_store_dwordx2 v[204:205], v[232:233], off offset:256
	s_nop 1
	v_mov_b32_dpp v241, v173 row_ror:8 row_mask:0xf bank_mask:0xf
	v_mov_b32_dpp v242, v234 row_ror:8 row_mask:0xf bank_mask:0xf
	v_add_f32_e32 v173, v173, v241
	v_add_f32_e32 v234, v234, v242
	v_cndmask_b32_e64 v173, v234, v173, s[34:35]
	s_nop 0
	ds_bpermute_b32 v241, v235, v173
	global_load_dwordx4 v[184:187], v[174:175], off
	global_load_dwordx4 v[188:191], v[174:175], off offset:512
	global_load_dwordx4 v[192:195], v[200:201], off
	global_load_dwordx4 v[196:199], v[200:201], off offset:512
	s_mov_b64 vcc, 0x20000
	v_lshl_add_u64 v[218:219], v[218:219], 0, vcc
	v_lshl_add_u64 v[220:221], v[220:221], 0, vcc
	s_mov_b64 vcc, 0x10000
	v_lshl_add_u64 v[202:203], v[202:203], 0, vcc
	v_lshl_add_u64 v[204:205], v[204:205], 0, vcc
	s_waitcnt lgkmcnt(0)
	v_add_f32_e32 v173, v173, v241
	s_nop 0
	ds_bpermute_b32 v242, v240, v173
	s_waitcnt lgkmcnt(0)
	v_add_f32_e32 v173, v173, v242
	s_mov_b64 exec, s[0:1]
	global_atomic_add_f32 v[206:207], v173, off
	s_mov_b64 exec, -1
	s_mov_b64 vcc, 64
	v_lshl_add_u64 v[206:207], v[206:207], 0, vcc
	v_mov_b32_dpp v236, v24 row_ror:8 row_mask:0xf bank_mask:0xf
	v_mov_b32_dpp v237, v25 row_ror:8 row_mask:0xf bank_mask:0xf
	v_mov_b32_dpp v238, v26 row_ror:8 row_mask:0xf bank_mask:0xf
	v_mov_b32_dpp v239, v27 row_ror:8 row_mask:0xf bank_mask:0xf
	v_cndmask_b32_e64 v24, v236, v28, s[34:35]
	v_cndmask_b32_e64 v25, v237, v29, s[34:35]
	v_cndmask_b32_e64 v26, v238, v30, s[34:35]
	v_cndmask_b32_e64 v27, v239, v31, s[34:35]
	v_cndmask_b32_e64 v28, v28, v236, s[34:35]
	v_cndmask_b32_e64 v29, v29, v237, s[34:35]
	v_cndmask_b32_e64 v30, v30, v238, s[34:35]
	v_cndmask_b32_e64 v31, v31, v239, s[34:35]
	v_mov_b32_dpp v236, v16 row_ror:8 row_mask:0xf bank_mask:0xf
	v_mov_b32_dpp v237, v17 row_ror:8 row_mask:0xf bank_mask:0xf
	v_mov_b32_dpp v238, v18 row_ror:8 row_mask:0xf bank_mask:0xf
	v_mov_b32_dpp v239, v19 row_ror:8 row_mask:0xf bank_mask:0xf
	v_cndmask_b32_e64 v16, v236, v20, s[34:35]
	v_cndmask_b32_e64 v17, v237, v21, s[34:35]
	v_cndmask_b32_e64 v18, v238, v22, s[34:35]
	v_cndmask_b32_e64 v19, v239, v23, s[34:35]
	v_cndmask_b32_e64 v20, v20, v236, s[34:35]
	v_cndmask_b32_e64 v21, v21, v237, s[34:35]
	v_cndmask_b32_e64 v22, v22, v238, s[34:35]
	v_cndmask_b32_e64 v23, v23, v239, s[34:35]
	s_waitcnt vmcnt(14)
;     __device__ __forceinline__ void operator()(const f32x4 (&acc)[2][2][4][2], const Unit& u, int wr, int wc, int fr, int fq) const {
;     ...
; #pragma unroll
;         for (int ai = 0; ai < 2; ++ai)
; #pragma unroll
;             for (int m = 0; m < 4; ++m) {
;                 const int row = row0 + ai * HALF + m * 16;
;                 const size_t off = (size_t)row * ldc + col0;
;                 float q = 0.f;
; #pragma unroll
;                 for (int bj = 0; bj < 2; ++bj)
; #pragma unroll
;                     for (int n = 0; n < 2; ++n) {
;                         const f32x4 rv = *(const f32x4*)(rbase + off + bj * HALF + n * 16);
;                         const f32x4 v = rv + acc[ai][bj][m][n] * scale;
;                         if (out) *(f32x4*)(out + off + bj * HALF + n * 16) = v;
;                         if (xn) { q += (v.x * v.x + v.y * v.y) + (v.z * v.z + v.w * v.w); const f32x4 o = v * wv[bj][n];
;                             u32x2 p; p.x = pk2(o.x, o.y); p.y = pk2(o.z, o.w); *(u32x2*)(xn + off + bj * HALF + n * 16) = p; }
;                     }
;                 if (xn) { q += __shfl_xor(q, 16); q += __shfl_xor(q, 32); if (fq == 0) (void)__hip_atomic_fetch_add(ss + row, q, __ATOMIC_RELAXED, __HIP_MEMORY_SCOPE_AGENT); }
;             }
	v_pk_add_f32 v[26:27], v[26:27], v[158:159]
	v_pk_add_f32 v[24:25], v[24:25], v[156:157]
	global_store_dwordx4 v[218:219], v[24:27], off
	v_pk_mul_f32 v[224:225], v[64:65], v[24:25]
	v_pk_mul_f32 v[226:227], v[66:67], v[26:27]
	v_mul_f32_e32 v173, v24, v24
	v_add_u32_e32 v224, 0x8000, v224
	v_add_u32_e32 v225, 0x8000, v225
	v_add_u32_e32 v226, 0x8000, v226
	v_add_u32_e32 v227, 0x8000, v227
	v_fmac_f32_e32 v173, v25, v25
	v_fmac_f32_e32 v173, v26, v26
	v_fmac_f32_e32 v173, v27, v27
	v_perm_b32 v222, v225, v224, s58
	v_perm_b32 v223, v227, v226, s58
	global_store_dwordx2 v[202:203], v[222:223], off
	v_pk_add_f32 v[18:19], v[18:19], v[162:163]
	v_pk_add_f32 v[16:17], v[16:17], v[160:161]
	global_store_dwordx4 v[218:219], v[16:19], off offset:512
	v_pk_mul_f32 v[228:229], v[72:73], v[16:17]
	v_pk_mul_f32 v[230:231], v[74:75], v[18:19]
	v_fmac_f32_e32 v173, v16, v16
	v_add_u32_e32 v228, 0x8000, v228
	v_add_u32_e32 v229, 0x8000, v229
	v_add_u32_e32 v230, 0x8000, v230
	v_add_u32_e32 v231, 0x8000, v231
	v_fmac_f32_e32 v173, v17, v17
	v_fmac_f32_e32 v173, v18, v18
	v_fmac_f32_e32 v173, v19, v19
	v_perm_b32 v232, v229, v228, s58
	v_perm_b32 v233, v231, v230, s58
	global_store_dwordx2 v[202:203], v[232:233], off offset:256
	v_pk_add_f32 v[30:31], v[30:31], v[178:179]
	v_pk_add_f32 v[28:29], v[28:29], v[176:177]
	global_store_dwordx4 v[220:221], v[28:31], off
	v_pk_mul_f32 v[224:225], v[76:77], v[28:29]
	v_pk_mul_f32 v[226:227], v[78:79], v[30:31]
	v_mul_f32_e32 v234, v28, v28
	v_add_u32_e32 v224, 0x8000, v224
	v_add_u32_e32 v225, 0x8000, v225
	v_add_u32_e32 v226, 0x8000, v226
	v_add_u32_e32 v227, 0x8000, v227
	v_fmac_f32_e32 v234, v29, v29
	v_fmac_f32_e32 v234, v30, v30
	v_fmac_f32_e32 v234, v31, v31
	v_perm_b32 v222, v225, v224, s58
	v_perm_b32 v223, v227, v226, s58
	global_store_dwordx2 v[204:205], v[222:223], off
	v_pk_add_f32 v[22:23], v[22:23], v[182:183]
	v_pk_add_f32 v[20:21], v[20:21], v[180:181]
	global_store_dwordx4 v[220:221], v[20:23], off offset:512
	v_pk_mul_f32 v[228:229], v[84:85], v[20:21]
	v_pk_mul_f32 v[230:231], v[86:87], v[22:23]
	v_fmac_f32_e32 v234, v20, v20
	v_add_u32_e32 v228, 0x8000, v228
	v_add_u32_e32 v229, 0x8000, v229
	v_add_u32_e32 v230, 0x8000, v230
	v_add_u32_e32 v231, 0x8000, v231
	v_fmac_f32_e32 v234, v21, v21
	v_fmac_f32_e32 v234, v22, v22
	v_fmac_f32_e32 v234, v23, v23
	v_perm_b32 v232, v229, v228, s58
	v_perm_b32 v233, v231, v230, s58
	global_store_dwordx2 v[204:205], v[232:233], off offset:256
	s_nop 1
	v_mov_b32_dpp v241, v173 row_ror:8 row_mask:0xf bank_mask:0xf
	v_mov_b32_dpp v242, v234 row_ror:8 row_mask:0xf bank_mask:0xf
	v_add_f32_e32 v173, v173, v241
	v_add_f32_e32 v234, v234, v242
	v_cndmask_b32_e64 v173, v234, v173, s[34:35]
	s_nop 0
	ds_bpermute_b32 v241, v235, v173
	s_mov_b64 vcc, 0x20000
	v_lshl_add_u64 v[218:219], v[218:219], 0, vcc
	v_lshl_add_u64 v[220:221], v[220:221], 0, vcc
	s_mov_b64 vcc, 0x10000
	v_lshl_add_u64 v[202:203], v[202:203], 0, vcc
	v_lshl_add_u64 v[204:205], v[204:205], 0, vcc
	s_waitcnt lgkmcnt(0)
	v_add_f32_e32 v173, v173, v241
	s_nop 0
	ds_bpermute_b32 v242, v240, v173
	s_waitcnt lgkmcnt(0)
	v_add_f32_e32 v173, v173, v242
	s_mov_b64 exec, s[0:1]
	global_atomic_add_f32 v[206:207], v173, off
	s_mov_b64 exec, -1
	s_mov_b64 vcc, 64
	v_lshl_add_u64 v[206:207], v[206:207], 0, vcc
	v_mov_b32_dpp v236, v8 row_ror:8 row_mask:0xf bank_mask:0xf
	v_mov_b32_dpp v237, v9 row_ror:8 row_mask:0xf bank_mask:0xf
	v_mov_b32_dpp v238, v10 row_ror:8 row_mask:0xf bank_mask:0xf
	v_mov_b32_dpp v239, v11 row_ror:8 row_mask:0xf bank_mask:0xf
	v_cndmask_b32_e64 v8, v236, v12, s[34:35]
	v_cndmask_b32_e64 v9, v237, v13, s[34:35]
	v_cndmask_b32_e64 v10, v238, v14, s[34:35]
	v_cndmask_b32_e64 v11, v239, v15, s[34:35]
	v_cndmask_b32_e64 v12, v12, v236, s[34:35]
	v_cndmask_b32_e64 v13, v13, v237, s[34:35]
	v_cndmask_b32_e64 v14, v14, v238, s[34:35]
	v_cndmask_b32_e64 v15, v15, v239, s[34:35]
	v_mov_b32_dpp v236, v0 row_ror:8 row_mask:0xf bank_mask:0xf
	v_mov_b32_dpp v237, v1 row_ror:8 row_mask:0xf bank_mask:0xf
	v_mov_b32_dpp v238, v2 row_ror:8 row_mask:0xf bank_mask:0xf
	v_mov_b32_dpp v239, v3 row_ror:8 row_mask:0xf bank_mask:0xf
	v_cndmask_b32_e64 v0, v236, v4, s[34:35]
	v_cndmask_b32_e64 v1, v237, v5, s[34:35]
	v_cndmask_b32_e64 v2, v238, v6, s[34:35]
	v_cndmask_b32_e64 v3, v239, v7, s[34:35]
	v_cndmask_b32_e64 v4, v4, v236, s[34:35]
	v_cndmask_b32_e64 v5, v5, v237, s[34:35]
	v_cndmask_b32_e64 v6, v6, v238, s[34:35]
	v_cndmask_b32_e64 v7, v7, v239, s[34:35]
	s_waitcnt vmcnt(10)
;     __device__ __forceinline__ void operator()(const f32x4 (&acc)[2][2][4][2], const Unit& u, int wr, int wc, int fr, int fq) const {
;     ...
; #pragma unroll
;                 for (int bj = 0; bj < 2; ++bj)
; #pragma unroll
;                     for (int n = 0; n < 2; ++n) {
;                         const f32x4 rv = *(const f32x4*)(rbase + off + bj * HALF + n * 16);
;                         const f32x4 v = rv + acc[ai][bj][m][n] * scale;
;                         if (out) *(f32x4*)(out + off + bj * HALF + n * 16) = v;
;                         if (xn) { q += (v.x * v.x + v.y * v.y) + (v.z * v.z + v.w * v.w); const f32x4 o = v * wv[bj][n];
;                             u32x2 p; p.x = pk2(o.x, o.y); p.y = pk2(o.z, o.w); *(u32x2*)(xn + off + bj * HALF + n * 16) = p; }
;                     }
;                 if (xn) { q += __shfl_xor(q, 16); q += __shfl_xor(q, 32); if (fq == 0) (void)__hip_atomic_fetch_add(ss + row, q, __ATOMIC_RELAXED, __HIP_MEMORY_SCOPE_AGENT); }
;             }
	v_pk_add_f32 v[10:11], v[10:11], v[186:187]
	v_pk_add_f32 v[8:9], v[8:9], v[184:185]
	global_store_dwordx4 v[218:219], v[8:11], off
	v_pk_mul_f32 v[224:225], v[64:65], v[8:9]
	v_pk_mul_f32 v[226:227], v[66:67], v[10:11]
	v_mul_f32_e32 v173, v8, v8
	v_add_u32_e32 v224, 0x8000, v224
	v_add_u32_e32 v225, 0x8000, v225
	v_add_u32_e32 v226, 0x8000, v226
	v_add_u32_e32 v227, 0x8000, v227
	v_fmac_f32_e32 v173, v9, v9
	v_fmac_f32_e32 v173, v10, v10
	v_fmac_f32_e32 v173, v11, v11
	v_perm_b32 v222, v225, v224, s58
	v_perm_b32 v223, v227, v226, s58
	global_store_dwordx2 v[202:203], v[222:223], off
	v_pk_add_f32 v[2:3], v[2:3], v[190:191]
	v_pk_add_f32 v[0:1], v[0:1], v[188:189]
	global_store_dwordx4 v[218:219], v[0:3], off offset:512
	v_pk_mul_f32 v[228:229], v[72:73], v[0:1]
	v_pk_mul_f32 v[230:231], v[74:75], v[2:3]
	v_fmac_f32_e32 v173, v0, v0
	v_add_u32_e32 v228, 0x8000, v228
	v_add_u32_e32 v229, 0x8000, v229
	v_add_u32_e32 v230, 0x8000, v230
	v_add_u32_e32 v231, 0x8000, v231
	v_fmac_f32_e32 v173, v1, v1
	v_fmac_f32_e32 v173, v2, v2
	v_fmac_f32_e32 v173, v3, v3
	v_perm_b32 v232, v229, v228, s58
	v_perm_b32 v233, v231, v230, s58
	global_store_dwordx2 v[202:203], v[232:233], off offset:256
	v_pk_add_f32 v[14:15], v[14:15], v[194:195]
	v_pk_add_f32 v[12:13], v[12:13], v[192:193]
	global_store_dwordx4 v[220:221], v[12:15], off
	v_pk_mul_f32 v[224:225], v[76:77], v[12:13]
	v_pk_mul_f32 v[226:227], v[78:79], v[14:15]
	v_mul_f32_e32 v234, v12, v12
	v_add_u32_e32 v224, 0x8000, v224
	v_add_u32_e32 v225, 0x8000, v225
	v_add_u32_e32 v226, 0x8000, v226
	v_add_u32_e32 v227, 0x8000, v227
	v_fmac_f32_e32 v234, v13, v13
	v_fmac_f32_e32 v234, v14, v14
	v_fmac_f32_e32 v234, v15, v15
	v_perm_b32 v222, v225, v224, s58
	v_perm_b32 v223, v227, v226, s58
	global_store_dwordx2 v[204:205], v[222:223], off
	v_pk_add_f32 v[6:7], v[6:7], v[198:199]
	v_pk_add_f32 v[4:5], v[4:5], v[196:197]
	global_store_dwordx4 v[220:221], v[4:7], off offset:512
	v_pk_mul_f32 v[228:229], v[84:85], v[4:5]
	v_pk_mul_f32 v[230:231], v[86:87], v[6:7]
	v_fmac_f32_e32 v234, v4, v4
	v_add_u32_e32 v228, 0x8000, v228
	v_add_u32_e32 v229, 0x8000, v229
	v_add_u32_e32 v230, 0x8000, v230
	v_add_u32_e32 v231, 0x8000, v231
	v_fmac_f32_e32 v234, v5, v5
	v_fmac_f32_e32 v234, v6, v6
	v_fmac_f32_e32 v234, v7, v7
	v_perm_b32 v232, v229, v228, s58
	v_perm_b32 v233, v231, v230, s58
	global_store_dwordx2 v[204:205], v[232:233], off offset:256
	s_nop 1
	v_mov_b32_dpp v241, v173 row_ror:8 row_mask:0xf bank_mask:0xf
	v_mov_b32_dpp v242, v234 row_ror:8 row_mask:0xf bank_mask:0xf
	v_add_f32_e32 v173, v173, v241
	v_add_f32_e32 v234, v234, v242
	v_cndmask_b32_e64 v173, v234, v173, s[34:35]
	s_nop 0
	ds_bpermute_b32 v241, v235, v173
	s_waitcnt lgkmcnt(0)
	v_add_f32_e32 v173, v173, v241
	s_nop 0
	ds_bpermute_b32 v242, v240, v173
	s_waitcnt lgkmcnt(0)
	v_add_f32_e32 v173, v173, v242
	s_mov_b64 exec, s[0:1]
	global_atomic_add_f32 v[206:207], v173, off
	s_mov_b64 exec, -1
	s_andn2_b64 vcc, exec, s[6:7]
	s_mov_b64 s[4:5], -1
	s_cbranch_vccnz .LBB0_1078
	s_andn2_b64 vcc, exec, s[12:13]
	s_cbranch_vccnz .LBB0_1077
	s_barrier
	s_branch .LBB0_1077

;     __device__ __forceinline__ void operator()(const f32x4 (&acc)[2][2][4][2], const Unit& u, int wr, int wc, int fr, int fq) const {
;         const int row0 = u.pm * BM + wr * 64 + fr, col0 = u.pn * BM + wc * 32 + 4 * fq;
;         const float* rbase = (u.pm * BM < SEQ_P) ? resA : (resB - (size_t)SEQ_P * ldc);
;         f32x4 wv[2][2];
;         if (xn) {
; #pragma unroll
;             for (int bj = 0; bj < 2; ++bj)
; #pragma unroll
;                 for (int n = 0; n < 2; ++n) wv[bj][n] = *(const f32x4*)(wn + col0 + bj * HALF + n * 16);
;         }
; #pragma unroll
;         for (int ai = 0; ai < 2; ++ai)
; #pragma unroll
;             for (int m = 0; m < 4; ++m) {
;                 const int row = row0 + ai * HALF + m * 16;
;                 const size_t off = (size_t)row * ldc + col0;
;                 float q = 0.f;
; #pragma unroll
;                 for (int bj = 0; bj < 2; ++bj)
; #pragma unroll
;                     for (int n = 0; n < 2; ++n) {
;                         const f32x4 rv = *(const f32x4*)(rbase + off + bj * HALF + n * 16);
;                         const f32x4 v = rv + acc[ai][bj][m][n] * scale;
;                         if (out) *(f32x4*)(out + off + bj * HALF + n * 16) = v;
;                         if (xn) { q += (v.x * v.x + v.y * v.y) + (v.z * v.z + v.w * v.w); const f32x4 o = v * wv[bj][n];
;                             u32x2 p; p.x = pk2(o.x, o.y); p.y = pk2(o.z, o.w); *(u32x2*)(xn + off + bj * HALF + n * 16) = p; }
;                     }
;                 if (xn) { q += __shfl_xor(q, 16); q += __shfl_xor(q, 32); if (fq == 0) (void)__hip_atomic_fetch_add(ss + row, q, __ATOMIC_RELAXED, __HIP_MEMORY_SCOPE_AGENT); }
;             }
.LBB0_1382:
	v_lshl_add_u32 v210, s54, 8, v160
	v_lshl_or_b32 v212, s53, 8, v162
	v_and_b32_e32 v238, 8, v167
	v_mov_b32_e32 v211, 0
	v_cmp_eq_u32_e64 s[24:25], 0, v238
	v_lshlrev_b32_e32 v232, 1, v238
	v_add_u32_e32 v214, v212, v232
	v_sub_u32_e32 v233, 16, v232
	v_add_u32_e32 v233, v212, v233
	v_mov_b32_e32 v212, v214
	v_mov_b32_e32 v214, v233
	v_mov_b32_e32 v213, 0
	v_mov_b32_e32 v215, 0
	v_sub_u32_e32 v208, v210, v238
	v_mov_b32_e32 v209, 0
	v_lshlrev_b64 v[206:207], 11, v[208:209]
	v_add_u32_e32 v208, 8, v208
	v_lshlrev_b64 v[208:209], 11, v[208:209]
	v_lshl_add_u64 v[206:207], v[206:207], 0, v[212:213]
	v_lshl_add_u64 v[208:209], v[208:209], 0, v[214:215]
	v_lshl_add_u64 v[196:197], v[206:207], 2, s[8:9]
	v_lshl_add_u64 v[198:199], v[208:209], 2, s[8:9]
	v_lshl_add_u64 v[200:201], v[212:213], 2, s[10:11]
	v_lshl_add_u64 v[202:203], v[214:215], 2, s[10:11]
	global_load_dwordx4 v[72:75], v[200:201], off
	global_load_dwordx4 v[84:87], v[200:201], off offset:512
	global_load_dwordx4 v[88:91], v[202:203], off
	global_load_dwordx4 v[96:99], v[202:203], off offset:512
	global_load_dwordx4 v[156:159], v[196:197], off
	global_load_dwordx4 v[168:171], v[196:197], off offset:512
	global_load_dwordx4 v[172:175], v[198:199], off
	global_load_dwordx4 v[176:179], v[198:199], off offset:512
	s_mov_b64 vcc, 0x20000
	v_lshl_add_u64 v[196:197], v[196:197], 0, vcc
	v_lshl_add_u64 v[198:199], v[198:199], 0, vcc
	global_load_dwordx4 v[180:183], v[196:197], off
	global_load_dwordx4 v[184:187], v[196:197], off offset:512
	global_load_dwordx4 v[188:191], v[198:199], off
	global_load_dwordx4 v[192:195], v[198:199], off offset:512
	s_mov_b64 vcc, 0x20000
	v_lshl_add_u64 v[196:197], v[196:197], 0, vcc
	v_lshl_add_u64 v[198:199], v[198:199], 0, vcc
	v_lshl_add_u64 v[200:201], v[206:207], 1, s[14:15]
	v_lshl_add_u64 v[202:203], v[208:209], 1, s[14:15]
	v_lshl_add_u64 v[204:205], v[210:211], 2, s[16:17]
	v_xor_b32_e32 v234, 16, v167
	v_xor_b32_e32 v235, 32, v167
	v_lshlrev_b32_e32 v234, 2, v234
	v_lshlrev_b32_e32 v235, 2, v235
	v_mov_b32_dpp v228, v136 row_ror:8 row_mask:0xf bank_mask:0xf
	v_mov_b32_dpp v229, v137 row_ror:8 row_mask:0xf bank_mask:0xf
	v_mov_b32_dpp v230, v138 row_ror:8 row_mask:0xf bank_mask:0xf
	v_mov_b32_dpp v231, v139 row_ror:8 row_mask:0xf bank_mask:0xf
	v_cndmask_b32_e64 v136, v228, v140, s[24:25]
	v_cndmask_b32_e64 v137, v229, v141, s[24:25]
	v_cndmask_b32_e64 v138, v230, v142, s[24:25]
	v_cndmask_b32_e64 v139, v231, v143, s[24:25]
	v_cndmask_b32_e64 v140, v140, v228, s[24:25]
	v_cndmask_b32_e64 v141, v141, v229, s[24:25]
	v_cndmask_b32_e64 v142, v142, v230, s[24:25]
	v_cndmask_b32_e64 v143, v143, v231, s[24:25]
	v_mov_b32_dpp v228, v128 row_ror:8 row_mask:0xf bank_mask:0xf
	v_mov_b32_dpp v229, v129 row_ror:8 row_mask:0xf bank_mask:0xf
	v_mov_b32_dpp v230, v130 row_ror:8 row_mask:0xf bank_mask:0xf
	v_mov_b32_dpp v231, v131 row_ror:8 row_mask:0xf bank_mask:0xf
	v_cndmask_b32_e64 v128, v228, v132, s[24:25]
	v_cndmask_b32_e64 v129, v229, v133, s[24:25]
	v_cndmask_b32_e64 v130, v230, v134, s[24:25]
	v_cndmask_b32_e64 v131, v231, v135, s[24:25]
	v_cndmask_b32_e64 v132, v132, v228, s[24:25]
	v_cndmask_b32_e64 v133, v133, v229, s[24:25]
	v_cndmask_b32_e64 v134, v134, v230, s[24:25]
	v_cndmask_b32_e64 v135, v135, v231, s[24:25]
	s_waitcnt vmcnt(4)
	v_pk_fma_f32 v[138:139], v[138:139], 0.5, v[158:159] op_sel_hi:[1,0,1]
	v_pk_fma_f32 v[136:137], v[136:137], 0.5, v[156:157] op_sel_hi:[1,0,1]
	v_pk_mul_f32 v[216:217], v[72:73], v[136:137]
	v_pk_mul_f32 v[218:219], v[74:75], v[138:139]
	v_mul_f32_e32 v232, v136, v136
	v_add_u32_e32 v216, 0x8000, v216
	v_add_u32_e32 v217, 0x8000, v217
	v_add_u32_e32 v218, 0x8000, v218
	v_add_u32_e32 v219, 0x8000, v219
	v_fmac_f32_e32 v232, v137, v137
	v_fmac_f32_e32 v232, v138, v138
	v_fmac_f32_e32 v232, v139, v139
	v_perm_b32 v224, v217, v216, s50
	v_perm_b32 v225, v219, v218, s50
	global_store_dwordx2 v[200:201], v[224:225], off
	v_pk_fma_f32 v[130:131], v[130:131], 0.5, v[170:171] op_sel_hi:[1,0,1]
	v_pk_fma_f32 v[128:129], v[128:129], 0.5, v[168:169] op_sel_hi:[1,0,1]
	v_pk_mul_f32 v[220:221], v[84:85], v[128:129]
	v_pk_mul_f32 v[222:223], v[86:87], v[130:131]
	v_fmac_f32_e32 v232, v128, v128
	v_add_u32_e32 v220, 0x8000, v220
	v_add_u32_e32 v221, 0x8000, v221
	v_add_u32_e32 v222, 0x8000, v222
	v_add_u32_e32 v223, 0x8000, v223
	v_fmac_f32_e32 v232, v129, v129
	v_fmac_f32_e32 v232, v130, v130
	v_fmac_f32_e32 v232, v131, v131
	v_perm_b32 v226, v221, v220, s50
	v_perm_b32 v227, v223, v222, s50
	global_store_dwordx2 v[200:201], v[226:227], off offset:256
	v_pk_fma_f32 v[142:143], v[142:143], 0.5, v[174:175] op_sel_hi:[1,0,1]
	v_pk_fma_f32 v[140:141], v[140:141], 0.5, v[172:173] op_sel_hi:[1,0,1]
	v_pk_mul_f32 v[216:217], v[88:89], v[140:141]
	v_pk_mul_f32 v[218:219], v[90:91], v[142:143]
	v_mul_f32_e32 v233, v140, v140
	v_add_u32_e32 v216, 0x8000, v216
	v_add_u32_e32 v217, 0x8000, v217
	v_add_u32_e32 v218, 0x8000, v218
	v_add_u32_e32 v219, 0x8000, v219
	v_fmac_f32_e32 v233, v141, v141
	v_fmac_f32_e32 v233, v142, v142
	v_fmac_f32_e32 v233, v143, v143
	v_perm_b32 v224, v217, v216, s50
	v_perm_b32 v225, v219, v218, s50
	global_store_dwordx2 v[202:203], v[224:225], off
	v_pk_fma_f32 v[134:135], v[134:135], 0.5, v[178:179] op_sel_hi:[1,0,1]
	v_pk_fma_f32 v[132:133], v[132:133], 0.5, v[176:177] op_sel_hi:[1,0,1]
	v_pk_mul_f32 v[220:221], v[96:97], v[132:133]
	v_pk_mul_f32 v[222:223], v[98:99], v[134:135]
	v_fmac_f32_e32 v233, v132, v132
	v_add_u32_e32 v220, 0x8000, v220
	v_add_u32_e32 v221, 0x8000, v221
	v_add_u32_e32 v222, 0x8000, v222
	v_add_u32_e32 v223, 0x8000, v223
	v_fmac_f32_e32 v233, v133, v133
	v_fmac_f32_e32 v233, v134, v134
	v_fmac_f32_e32 v233, v135, v135
	v_perm_b32 v226, v221, v220, s50
	v_perm_b32 v227, v223, v222, s50
	global_store_dwordx2 v[202:203], v[226:227], off offset:256
	s_nop 1
	v_mov_b32_dpp v236, v232 row_ror:8 row_mask:0xf bank_mask:0xf
	v_mov_b32_dpp v237, v233 row_ror:8 row_mask:0xf bank_mask:0xf
	v_add_f32_e32 v232, v232, v236
	v_add_f32_e32 v233, v233, v237
	v_cndmask_b32_e64 v232, v233, v232, s[24:25]
	s_nop 0
	ds_bpermute_b32 v236, v234, v232
	global_load_dwordx4 v[156:159], v[196:197], off
	global_load_dwordx4 v[168:171], v[196:197], off offset:512
	global_load_dwordx4 v[172:175], v[198:199], off
	global_load_dwordx4 v[176:179], v[198:199], off offset:512
	s_mov_b64 vcc, 0x20000
	v_lshl_add_u64 v[196:197], v[196:197], 0, vcc
	v_lshl_add_u64 v[198:199], v[198:199], 0, vcc
	s_mov_b64 vcc, 0x20000
	s_mov_b64 vcc, 0x10000
	v_lshl_add_u64 v[200:201], v[200:201], 0, vcc
	v_lshl_add_u64 v[202:203], v[202:203], 0, vcc
	s_waitcnt lgkmcnt(0)
;     __device__ __forceinline__ void operator()(const f32x4 (&acc)[2][2][4][2], const Unit& u, int wr, int wc, int fr, int fq) const {
;     ...
; #pragma unroll
;         for (int ai = 0; ai < 2; ++ai)
; #pragma unroll
;             for (int m = 0; m < 4; ++m) {
;                 const int row = row0 + ai * HALF + m * 16;
;                 const size_t off = (size_t)row * ldc + col0;
;                 float q = 0.f;
; #pragma unroll
;                 for (int bj = 0; bj < 2; ++bj)
; #pragma unroll
;                     for (int n = 0; n < 2; ++n) {
;                         const f32x4 rv = *(const f32x4*)(rbase + off + bj * HALF + n * 16);
;                         const f32x4 v = rv + acc[ai][bj][m][n] * scale;
;                         if (out) *(f32x4*)(out + off + bj * HALF + n * 16) = v;
;                         if (xn) { q += (v.x * v.x + v.y * v.y) + (v.z * v.z + v.w * v.w); const f32x4 o = v * wv[bj][n];
;                             u32x2 p; p.x = pk2(o.x, o.y); p.y = pk2(o.z, o.w); *(u32x2*)(xn + off + bj * HALF + n * 16) = p; }
;                     }
;                 if (xn) { q += __shfl_xor(q, 16); q += __shfl_xor(q, 32); if (fq == 0) (void)__hip_atomic_fetch_add(ss + row, q, __ATOMIC_RELAXED, __HIP_MEMORY_SCOPE_AGENT); }
;             }
	v_add_f32_e32 v232, v232, v236
	s_nop 0
	ds_bpermute_b32 v237, v235, v232
	s_waitcnt lgkmcnt(0)
	v_add_f32_e32 v232, v232, v237
	s_mov_b64 exec, s[0:1]
	global_atomic_add_f32 v[204:205], v232, off
	s_mov_b64 exec, -1
	s_mov_b64 vcc, 64
	v_lshl_add_u64 v[204:205], v[204:205], 0, vcc
	v_mov_b32_dpp v228, v120 row_ror:8 row_mask:0xf bank_mask:0xf
	v_mov_b32_dpp v229, v121 row_ror:8 row_mask:0xf bank_mask:0xf
	v_mov_b32_dpp v230, v122 row_ror:8 row_mask:0xf bank_mask:0xf
	v_mov_b32_dpp v231, v123 row_ror:8 row_mask:0xf bank_mask:0xf
	v_cndmask_b32_e64 v120, v228, v124, s[24:25]
	v_cndmask_b32_e64 v121, v229, v125, s[24:25]
	v_cndmask_b32_e64 v122, v230, v126, s[24:25]
	v_cndmask_b32_e64 v123, v231, v127, s[24:25]
	v_cndmask_b32_e64 v124, v124, v228, s[24:25]
	v_cndmask_b32_e64 v125, v125, v229, s[24:25]
	v_cndmask_b32_e64 v126, v126, v230, s[24:25]
	v_cndmask_b32_e64 v127, v127, v231, s[24:25]
	v_mov_b32_dpp v228, v112 row_ror:8 row_mask:0xf bank_mask:0xf
	v_mov_b32_dpp v229, v113 row_ror:8 row_mask:0xf bank_mask:0xf
	v_mov_b32_dpp v230, v114 row_ror:8 row_mask:0xf bank_mask:0xf
	v_mov_b32_dpp v231, v115 row_ror:8 row_mask:0xf bank_mask:0xf
	v_cndmask_b32_e64 v112, v228, v116, s[24:25]
	v_cndmask_b32_e64 v113, v229, v117, s[24:25]
	v_cndmask_b32_e64 v114, v230, v118, s[24:25]
	v_cndmask_b32_e64 v115, v231, v119, s[24:25]
	v_cndmask_b32_e64 v116, v116, v228, s[24:25]
	v_cndmask_b32_e64 v117, v117, v229, s[24:25]
	v_cndmask_b32_e64 v118, v118, v230, s[24:25]
	v_cndmask_b32_e64 v119, v119, v231, s[24:25]
	s_waitcnt vmcnt(9)
	v_pk_fma_f32 v[122:123], v[122:123], 0.5, v[182:183] op_sel_hi:[1,0,1]
	v_pk_fma_f32 v[120:121], v[120:121], 0.5, v[180:181] op_sel_hi:[1,0,1]
	v_pk_mul_f32 v[216:217], v[72:73], v[120:121]
	v_pk_mul_f32 v[218:219], v[74:75], v[122:123]
	v_mul_f32_e32 v232, v120, v120
	v_add_u32_e32 v216, 0x8000, v216
	v_add_u32_e32 v217, 0x8000, v217
	v_add_u32_e32 v218, 0x8000, v218
	v_add_u32_e32 v219, 0x8000, v219
	v_fmac_f32_e32 v232, v121, v121
	v_fmac_f32_e32 v232, v122, v122
	v_fmac_f32_e32 v232, v123, v123
	v_perm_b32 v224, v217, v216, s50
	v_perm_b32 v225, v219, v218, s50
	global_store_dwordx2 v[200:201], v[224:225], off
	v_pk_fma_f32 v[114:115], v[114:115], 0.5, v[186:187] op_sel_hi:[1,0,1]
	v_pk_fma_f32 v[112:113], v[112:113], 0.5, v[184:185] op_sel_hi:[1,0,1]
	v_pk_mul_f32 v[220:221], v[84:85], v[112:113]
	v_pk_mul_f32 v[222:223], v[86:87], v[114:115]
	v_fmac_f32_e32 v232, v112, v112
	v_add_u32_e32 v220, 0x8000, v220
	v_add_u32_e32 v221, 0x8000, v221
	v_add_u32_e32 v222, 0x8000, v222
	v_add_u32_e32 v223, 0x8000, v223
	v_fmac_f32_e32 v232, v113, v113
	v_fmac_f32_e32 v232, v114, v114
	v_fmac_f32_e32 v232, v115, v115
	v_perm_b32 v226, v221, v220, s50
	v_perm_b32 v227, v223, v222, s50
	global_store_dwordx2 v[200:201], v[226:227], off offset:256
	v_pk_fma_f32 v[126:127], v[126:127], 0.5, v[190:191] op_sel_hi:[1,0,1]
	v_pk_fma_f32 v[124:125], v[124:125], 0.5, v[188:189] op_sel_hi:[1,0,1]
	v_pk_mul_f32 v[216:217], v[88:89], v[124:125]
	v_pk_mul_f32 v[218:219], v[90:91], v[126:127]
	v_mul_f32_e32 v233, v124, v124
	v_add_u32_e32 v216, 0x8000, v216
	v_add_u32_e32 v217, 0x8000, v217
	v_add_u32_e32 v218, 0x8000, v218
	v_add_u32_e32 v219, 0x8000, v219
	v_fmac_f32_e32 v233, v125, v125
	v_fmac_f32_e32 v233, v126, v126
	v_fmac_f32_e32 v233, v127, v127
	v_perm_b32 v224, v217, v216, s50
	v_perm_b32 v225, v219, v218, s50
	global_store_dwordx2 v[202:203], v[224:225], off
	v_pk_fma_f32 v[118:119], v[118:119], 0.5, v[194:195] op_sel_hi:[1,0,1]
	v_pk_fma_f32 v[116:117], v[116:117], 0.5, v[192:193] op_sel_hi:[1,0,1]
	v_pk_mul_f32 v[220:221], v[96:97], v[116:117]
	v_pk_mul_f32 v[222:223], v[98:99], v[118:119]
	v_fmac_f32_e32 v233, v116, v116
	v_add_u32_e32 v220, 0x8000, v220
	v_add_u32_e32 v221, 0x8000, v221
	v_add_u32_e32 v222, 0x8000, v222
	v_add_u32_e32 v223, 0x8000, v223
	v_fmac_f32_e32 v233, v117, v117
	v_fmac_f32_e32 v233, v118, v118
	v_fmac_f32_e32 v233, v119, v119
	v_perm_b32 v226, v221, v220, s50
	v_perm_b32 v227, v223, v222, s50
	global_store_dwordx2 v[202:203], v[226:227], off offset:256
	s_nop 1
	v_mov_b32_dpp v236, v232 row_ror:8 row_mask:0xf bank_mask:0xf
	v_mov_b32_dpp v237, v233 row_ror:8 row_mask:0xf bank_mask:0xf
	v_add_f32_e32 v232, v232, v236
	v_add_f32_e32 v233, v233, v237
	v_cndmask_b32_e64 v232, v233, v232, s[24:25]
	s_nop 0
	ds_bpermute_b32 v236, v234, v232
	global_load_dwordx4 v[180:183], v[196:197], off
	global_load_dwordx4 v[184:187], v[196:197], off offset:512
	global_load_dwordx4 v[188:191], v[198:199], off
	global_load_dwordx4 v[192:195], v[198:199], off offset:512
	s_mov_b64 vcc, 0xa0000
	v_lshl_add_u64 v[196:197], v[196:197], 0, vcc
	v_lshl_add_u64 v[198:199], v[198:199], 0, vcc
	s_mov_b64 vcc, 0x20000
	s_mov_b64 vcc, 0x10000
	v_lshl_add_u64 v[200:201], v[200:201], 0, vcc
	v_lshl_add_u64 v[202:203], v[202:203], 0, vcc
	s_waitcnt lgkmcnt(0)
	v_add_f32_e32 v232, v232, v236
	s_nop 0
	ds_bpermute_b32 v237, v235, v232
	s_waitcnt lgkmcnt(0)
;     __device__ __forceinline__ void operator()(const f32x4 (&acc)[2][2][4][2], const Unit& u, int wr, int wc, int fr, int fq) const {
;     ...
; #pragma unroll
;         for (int ai = 0; ai < 2; ++ai)
; #pragma unroll
;             for (int m = 0; m < 4; ++m) {
;                 const int row = row0 + ai * HALF + m * 16;
;                 const size_t off = (size_t)row * ldc + col0;
;                 float q = 0.f;
; #pragma unroll
;                 for (int bj = 0; bj < 2; ++bj)
; #pragma unroll
;                     for (int n = 0; n < 2; ++n) {
;                         const f32x4 rv = *(const f32x4*)(rbase + off + bj * HALF + n * 16);
;                         const f32x4 v = rv + acc[ai][bj][m][n] * scale;
;                         if (out) *(f32x4*)(out + off + bj * HALF + n * 16) = v;
;                         if (xn) { q += (v.x * v.x + v.y * v.y) + (v.z * v.z + v.w * v.w); const f32x4 o = v * wv[bj][n];
;                             u32x2 p; p.x = pk2(o.x, o.y); p.y = pk2(o.z, o.w); *(u32x2*)(xn + off + bj * HALF + n * 16) = p; }
;                     }
;                 if (xn) { q += __shfl_xor(q, 16); q += __shfl_xor(q, 32); if (fq == 0) (void)__hip_atomic_fetch_add(ss + row, q, __ATOMIC_RELAXED, __HIP_MEMORY_SCOPE_AGENT); }
;             }
	v_add_f32_e32 v232, v232, v237
	s_mov_b64 exec, s[0:1]
	global_atomic_add_f32 v[204:205], v232, off
	s_mov_b64 exec, -1
	s_mov_b64 vcc, 64
	v_lshl_add_u64 v[204:205], v[204:205], 0, vcc
	v_mov_b32_dpp v228, v104 row_ror:8 row_mask:0xf bank_mask:0xf
	v_mov_b32_dpp v229, v105 row_ror:8 row_mask:0xf bank_mask:0xf
	v_mov_b32_dpp v230, v106 row_ror:8 row_mask:0xf bank_mask:0xf
	v_mov_b32_dpp v231, v107 row_ror:8 row_mask:0xf bank_mask:0xf
	v_cndmask_b32_e64 v104, v228, v108, s[24:25]
	v_cndmask_b32_e64 v105, v229, v109, s[24:25]
	v_cndmask_b32_e64 v106, v230, v110, s[24:25]
	v_cndmask_b32_e64 v107, v231, v111, s[24:25]
	v_cndmask_b32_e64 v108, v108, v228, s[24:25]
	v_cndmask_b32_e64 v109, v109, v229, s[24:25]
	v_cndmask_b32_e64 v110, v110, v230, s[24:25]
	v_cndmask_b32_e64 v111, v111, v231, s[24:25]
	v_mov_b32_dpp v228, v92 row_ror:8 row_mask:0xf bank_mask:0xf
	v_mov_b32_dpp v229, v93 row_ror:8 row_mask:0xf bank_mask:0xf
	v_mov_b32_dpp v230, v94 row_ror:8 row_mask:0xf bank_mask:0xf
	v_mov_b32_dpp v231, v95 row_ror:8 row_mask:0xf bank_mask:0xf
	v_cndmask_b32_e64 v92, v228, v100, s[24:25]
	v_cndmask_b32_e64 v93, v229, v101, s[24:25]
	v_cndmask_b32_e64 v94, v230, v102, s[24:25]
	v_cndmask_b32_e64 v95, v231, v103, s[24:25]
	v_cndmask_b32_e64 v100, v100, v228, s[24:25]
	v_cndmask_b32_e64 v101, v101, v229, s[24:25]
	v_cndmask_b32_e64 v102, v102, v230, s[24:25]
	v_cndmask_b32_e64 v103, v103, v231, s[24:25]
	s_waitcnt vmcnt(10)
	v_pk_fma_f32 v[106:107], v[106:107], 0.5, v[158:159] op_sel_hi:[1,0,1]
	v_pk_fma_f32 v[104:105], v[104:105], 0.5, v[156:157] op_sel_hi:[1,0,1]
	v_pk_mul_f32 v[216:217], v[72:73], v[104:105]
	v_pk_mul_f32 v[218:219], v[74:75], v[106:107]
	v_mul_f32_e32 v232, v104, v104
	v_add_u32_e32 v216, 0x8000, v216
	v_add_u32_e32 v217, 0x8000, v217
	v_add_u32_e32 v218, 0x8000, v218
	v_add_u32_e32 v219, 0x8000, v219
	v_fmac_f32_e32 v232, v105, v105
	v_fmac_f32_e32 v232, v106, v106
	v_fmac_f32_e32 v232, v107, v107
	v_perm_b32 v224, v217, v216, s50
	v_perm_b32 v225, v219, v218, s50
	global_store_dwordx2 v[200:201], v[224:225], off
	v_pk_fma_f32 v[94:95], v[94:95], 0.5, v[170:171] op_sel_hi:[1,0,1]
	v_pk_fma_f32 v[92:93], v[92:93], 0.5, v[168:169] op_sel_hi:[1,0,1]
	v_pk_mul_f32 v[220:221], v[84:85], v[92:93]
	v_pk_mul_f32 v[222:223], v[86:87], v[94:95]
	v_fmac_f32_e32 v232, v92, v92
	v_add_u32_e32 v220, 0x8000, v220
	v_add_u32_e32 v221, 0x8000, v221
	v_add_u32_e32 v222, 0x8000, v222
	v_add_u32_e32 v223, 0x8000, v223
	v_fmac_f32_e32 v232, v93, v93
	v_fmac_f32_e32 v232, v94, v94
	v_fmac_f32_e32 v232, v95, v95
	v_perm_b32 v226, v221, v220, s50
	v_perm_b32 v227, v223, v222, s50
	global_store_dwordx2 v[200:201], v[226:227], off offset:256
	v_pk_fma_f32 v[110:111], v[110:111], 0.5, v[174:175] op_sel_hi:[1,0,1]
	v_pk_fma_f32 v[108:109], v[108:109], 0.5, v[172:173] op_sel_hi:[1,0,1]
	v_pk_mul_f32 v[216:217], v[88:89], v[108:109]
	v_pk_mul_f32 v[218:219], v[90:91], v[110:111]
	v_mul_f32_e32 v233, v108, v108
	v_add_u32_e32 v216, 0x8000, v216
	v_add_u32_e32 v217, 0x8000, v217
	v_add_u32_e32 v218, 0x8000, v218
	v_add_u32_e32 v219, 0x8000, v219
	v_fmac_f32_e32 v233, v109, v109
	v_fmac_f32_e32 v233, v110, v110
	v_fmac_f32_e32 v233, v111, v111
	v_perm_b32 v224, v217, v216, s50
	v_perm_b32 v225, v219, v218, s50
	global_store_dwordx2 v[202:203], v[224:225], off
	v_pk_fma_f32 v[102:103], v[102:103], 0.5, v[178:179] op_sel_hi:[1,0,1]
	v_pk_fma_f32 v[100:101], v[100:101], 0.5, v[176:177] op_sel_hi:[1,0,1]
	v_pk_mul_f32 v[220:221], v[96:97], v[100:101]
	v_pk_mul_f32 v[222:223], v[98:99], v[102:103]
	v_fmac_f32_e32 v233, v100, v100
	v_add_u32_e32 v220, 0x8000, v220
	v_add_u32_e32 v221, 0x8000, v221
	v_add_u32_e32 v222, 0x8000, v222
	v_add_u32_e32 v223, 0x8000, v223
	v_fmac_f32_e32 v233, v101, v101
	v_fmac_f32_e32 v233, v102, v102
	v_fmac_f32_e32 v233, v103, v103
	v_perm_b32 v226, v221, v220, s50
	v_perm_b32 v227, v223, v222, s50
	global_store_dwordx2 v[202:203], v[226:227], off offset:256
	s_nop 1
	v_mov_b32_dpp v236, v232 row_ror:8 row_mask:0xf bank_mask:0xf
	v_mov_b32_dpp v237, v233 row_ror:8 row_mask:0xf bank_mask:0xf
	v_add_f32_e32 v232, v232, v236
	v_add_f32_e32 v233, v233, v237
	v_cndmask_b32_e64 v232, v233, v232, s[24:25]
	s_nop 0
	ds_bpermute_b32 v236, v234, v232
	global_load_dwordx4 v[156:159], v[196:197], off
	global_load_dwordx4 v[168:171], v[196:197], off offset:512
	global_load_dwordx4 v[172:175], v[198:199], off
	global_load_dwordx4 v[176:179], v[198:199], off offset:512
	s_mov_b64 vcc, 0x20000
	v_lshl_add_u64 v[196:197], v[196:197], 0, vcc
	v_lshl_add_u64 v[198:199], v[198:199], 0, vcc
	s_mov_b64 vcc, 0x20000
	s_mov_b64 vcc, 0x10000
	v_lshl_add_u64 v[200:201], v[200:201], 0, vcc
	v_lshl_add_u64 v[202:203], v[202:203], 0, vcc
	s_waitcnt lgkmcnt(0)
	v_add_f32_e32 v232, v232, v236
	s_nop 0
	ds_bpermute_b32 v237, v235, v232
	s_waitcnt lgkmcnt(0)
	v_add_f32_e32 v232, v232, v237
	s_mov_b64 exec, s[0:1]
	global_atomic_add_f32 v[204:205], v232, off
	s_mov_b64 exec, -1
	s_mov_b64 vcc, 64
	v_lshl_add_u64 v[204:205], v[204:205], 0, vcc
	v_mov_b32_dpp v228, v76 row_ror:8 row_mask:0xf bank_mask:0xf
	v_mov_b32_dpp v229, v77 row_ror:8 row_mask:0xf bank_mask:0xf
	v_mov_b32_dpp v230, v78 row_ror:8 row_mask:0xf bank_mask:0xf
	v_mov_b32_dpp v231, v79 row_ror:8 row_mask:0xf bank_mask:0xf
	v_cndmask_b32_e64 v76, v228, v80, s[24:25]
	v_cndmask_b32_e64 v77, v229, v81, s[24:25]
	v_cndmask_b32_e64 v78, v230, v82, s[24:25]
	v_cndmask_b32_e64 v79, v231, v83, s[24:25]
	v_cndmask_b32_e64 v80, v80, v228, s[24:25]
	v_cndmask_b32_e64 v81, v81, v229, s[24:25]
	v_cndmask_b32_e64 v82, v82, v230, s[24:25]
	v_cndmask_b32_e64 v83, v83, v231, s[24:25]
	v_mov_b32_dpp v228, v64 row_ror:8 row_mask:0xf bank_mask:0xf
	v_mov_b32_dpp v229, v65 row_ror:8 row_mask:0xf bank_mask:0xf
	v_mov_b32_dpp v230, v66 row_ror:8 row_mask:0xf bank_mask:0xf
	v_mov_b32_dpp v231, v67 row_ror:8 row_mask:0xf bank_mask:0xf
	v_cndmask_b32_e64 v64, v228, v68, s[24:25]
	v_cndmask_b32_e64 v65, v229, v69, s[24:25]
	v_cndmask_b32_e64 v66, v230, v70, s[24:25]
	v_cndmask_b32_e64 v67, v231, v71, s[24:25]
	v_cndmask_b32_e64 v68, v68, v228, s[24:25]
	v_cndmask_b32_e64 v69, v69, v229, s[24:25]
	v_cndmask_b32_e64 v70, v70, v230, s[24:25]
	v_cndmask_b32_e64 v71, v71, v231, s[24:25]
	s_waitcnt vmcnt(10)
;     __device__ __forceinline__ void operator()(const f32x4 (&acc)[2][2][4][2], const Unit& u, int wr, int wc, int fr, int fq) const {
;     ...
; #pragma unroll
;         for (int ai = 0; ai < 2; ++ai)
; #pragma unroll
;             for (int m = 0; m < 4; ++m) {
;                 const int row = row0 + ai * HALF + m * 16;
;                 const size_t off = (size_t)row * ldc + col0;
;                 float q = 0.f;
; #pragma unroll
;                 for (int bj = 0; bj < 2; ++bj)
; #pragma unroll
;                     for (int n = 0; n < 2; ++n) {
;                         const f32x4 rv = *(const f32x4*)(rbase + off + bj * HALF + n * 16);
;                         const f32x4 v = rv + acc[ai][bj][m][n] * scale;
;                         if (out) *(f32x4*)(out + off + bj * HALF + n * 16) = v;
;                         if (xn) { q += (v.x * v.x + v.y * v.y) + (v.z * v.z + v.w * v.w); const f32x4 o = v * wv[bj][n];
;                             u32x2 p; p.x = pk2(o.x, o.y); p.y = pk2(o.z, o.w); *(u32x2*)(xn + off + bj * HALF + n * 16) = p; }
;                     }
;                 if (xn) { q += __shfl_xor(q, 16); q += __shfl_xor(q, 32); if (fq == 0) (void)__hip_atomic_fetch_add(ss + row, q, __ATOMIC_RELAXED, __HIP_MEMORY_SCOPE_AGENT); }
;             }
	v_pk_fma_f32 v[78:79], v[78:79], 0.5, v[182:183] op_sel_hi:[1,0,1]
	v_pk_fma_f32 v[76:77], v[76:77], 0.5, v[180:181] op_sel_hi:[1,0,1]
	v_pk_mul_f32 v[216:217], v[72:73], v[76:77]
	v_pk_mul_f32 v[218:219], v[74:75], v[78:79]
	v_mul_f32_e32 v232, v76, v76
	v_add_u32_e32 v216, 0x8000, v216
	v_add_u32_e32 v217, 0x8000, v217
	v_add_u32_e32 v218, 0x8000, v218
	v_add_u32_e32 v219, 0x8000, v219
	v_fmac_f32_e32 v232, v77, v77
	v_fmac_f32_e32 v232, v78, v78
	v_fmac_f32_e32 v232, v79, v79
	v_perm_b32 v224, v217, v216, s50
	v_perm_b32 v225, v219, v218, s50
	global_store_dwordx2 v[200:201], v[224:225], off
	v_pk_fma_f32 v[66:67], v[66:67], 0.5, v[186:187] op_sel_hi:[1,0,1]
	v_pk_fma_f32 v[64:65], v[64:65], 0.5, v[184:185] op_sel_hi:[1,0,1]
	v_pk_mul_f32 v[220:221], v[84:85], v[64:65]
	v_pk_mul_f32 v[222:223], v[86:87], v[66:67]
	v_fmac_f32_e32 v232, v64, v64
	v_add_u32_e32 v220, 0x8000, v220
	v_add_u32_e32 v221, 0x8000, v221
	v_add_u32_e32 v222, 0x8000, v222
	v_add_u32_e32 v223, 0x8000, v223
	v_fmac_f32_e32 v232, v65, v65
	v_fmac_f32_e32 v232, v66, v66
	v_fmac_f32_e32 v232, v67, v67
	v_perm_b32 v226, v221, v220, s50
	v_perm_b32 v227, v223, v222, s50
	global_store_dwordx2 v[200:201], v[226:227], off offset:256
	v_pk_fma_f32 v[82:83], v[82:83], 0.5, v[190:191] op_sel_hi:[1,0,1]
	v_pk_fma_f32 v[80:81], v[80:81], 0.5, v[188:189] op_sel_hi:[1,0,1]
	v_pk_mul_f32 v[216:217], v[88:89], v[80:81]
	v_pk_mul_f32 v[218:219], v[90:91], v[82:83]
	v_mul_f32_e32 v233, v80, v80
	v_add_u32_e32 v216, 0x8000, v216
	v_add_u32_e32 v217, 0x8000, v217
	v_add_u32_e32 v218, 0x8000, v218
	v_add_u32_e32 v219, 0x8000, v219
	v_fmac_f32_e32 v233, v81, v81
	v_fmac_f32_e32 v233, v82, v82
	v_fmac_f32_e32 v233, v83, v83
	v_perm_b32 v224, v217, v216, s50
	v_perm_b32 v225, v219, v218, s50
	global_store_dwordx2 v[202:203], v[224:225], off
	v_pk_fma_f32 v[70:71], v[70:71], 0.5, v[194:195] op_sel_hi:[1,0,1]
	v_pk_fma_f32 v[68:69], v[68:69], 0.5, v[192:193] op_sel_hi:[1,0,1]
	v_pk_mul_f32 v[220:221], v[96:97], v[68:69]
	v_pk_mul_f32 v[222:223], v[98:99], v[70:71]
	v_fmac_f32_e32 v233, v68, v68
	v_add_u32_e32 v220, 0x8000, v220
	v_add_u32_e32 v221, 0x8000, v221
	v_add_u32_e32 v222, 0x8000, v222
	v_add_u32_e32 v223, 0x8000, v223
	v_fmac_f32_e32 v233, v69, v69
	v_fmac_f32_e32 v233, v70, v70
	v_fmac_f32_e32 v233, v71, v71
	v_perm_b32 v226, v221, v220, s50
	v_perm_b32 v227, v223, v222, s50
	global_store_dwordx2 v[202:203], v[226:227], off offset:256
	s_nop 1
	v_mov_b32_dpp v236, v232 row_ror:8 row_mask:0xf bank_mask:0xf
	v_mov_b32_dpp v237, v233 row_ror:8 row_mask:0xf bank_mask:0xf
	v_add_f32_e32 v232, v232, v236
	v_add_f32_e32 v233, v233, v237
	v_cndmask_b32_e64 v232, v233, v232, s[24:25]
	s_nop 0
	ds_bpermute_b32 v236, v234, v232
	global_load_dwordx4 v[180:183], v[196:197], off
	global_load_dwordx4 v[184:187], v[196:197], off offset:512
	global_load_dwordx4 v[188:191], v[198:199], off
	global_load_dwordx4 v[192:195], v[198:199], off offset:512
	s_mov_b64 vcc, 0x20000
	v_lshl_add_u64 v[196:197], v[196:197], 0, vcc
	v_lshl_add_u64 v[198:199], v[198:199], 0, vcc
	s_mov_b64 vcc, 0xa0000
	s_mov_b64 vcc, 0x50000
	v_lshl_add_u64 v[200:201], v[200:201], 0, vcc
	v_lshl_add_u64 v[202:203], v[202:203], 0, vcc
	s_waitcnt lgkmcnt(0)
	v_add_f32_e32 v232, v232, v236
	s_nop 0
	ds_bpermute_b32 v237, v235, v232
	s_waitcnt lgkmcnt(0)
	v_add_f32_e32 v232, v232, v237
	s_mov_b64 exec, s[0:1]
	global_atomic_add_f32 v[204:205], v232, off
	s_mov_b64 exec, -1
	s_mov_b64 vcc, 320
	v_lshl_add_u64 v[204:205], v[204:205], 0, vcc
	v_mov_b32_dpp v228, v56 row_ror:8 row_mask:0xf bank_mask:0xf
	v_mov_b32_dpp v229, v57 row_ror:8 row_mask:0xf bank_mask:0xf
	v_mov_b32_dpp v230, v58 row_ror:8 row_mask:0xf bank_mask:0xf
	v_mov_b32_dpp v231, v59 row_ror:8 row_mask:0xf bank_mask:0xf
	v_cndmask_b32_e64 v56, v228, v60, s[24:25]
	v_cndmask_b32_e64 v57, v229, v61, s[24:25]
	v_cndmask_b32_e64 v58, v230, v62, s[24:25]
	v_cndmask_b32_e64 v59, v231, v63, s[24:25]
	v_cndmask_b32_e64 v60, v60, v228, s[24:25]
	v_cndmask_b32_e64 v61, v61, v229, s[24:25]
	v_cndmask_b32_e64 v62, v62, v230, s[24:25]
	v_cndmask_b32_e64 v63, v63, v231, s[24:25]
	v_mov_b32_dpp v228, v48 row_ror:8 row_mask:0xf bank_mask:0xf
	v_mov_b32_dpp v229, v49 row_ror:8 row_mask:0xf bank_mask:0xf
	v_mov_b32_dpp v230, v50 row_ror:8 row_mask:0xf bank_mask:0xf
	v_mov_b32_dpp v231, v51 row_ror:8 row_mask:0xf bank_mask:0xf
	v_cndmask_b32_e64 v48, v228, v52, s[24:25]
	v_cndmask_b32_e64 v49, v229, v53, s[24:25]
	v_cndmask_b32_e64 v50, v230, v54, s[24:25]
	v_cndmask_b32_e64 v51, v231, v55, s[24:25]
	v_cndmask_b32_e64 v52, v52, v228, s[24:25]
	v_cndmask_b32_e64 v53, v53, v229, s[24:25]
	v_cndmask_b32_e64 v54, v54, v230, s[24:25]
	v_cndmask_b32_e64 v55, v55, v231, s[24:25]
	s_waitcnt vmcnt(10)
;     __device__ __forceinline__ void operator()(const f32x4 (&acc)[2][2][4][2], const Unit& u, int wr, int wc, int fr, int fq) const {
;     ...
; #pragma unroll
;         for (int ai = 0; ai < 2; ++ai)
; #pragma unroll
;             for (int m = 0; m < 4; ++m) {
;                 const int row = row0 + ai * HALF + m * 16;
;                 const size_t off = (size_t)row * ldc + col0;
;                 float q = 0.f;
; #pragma unroll
;                 for (int bj = 0; bj < 2; ++bj)
; #pragma unroll
;                     for (int n = 0; n < 2; ++n) {
;                         const f32x4 rv = *(const f32x4*)(rbase + off + bj * HALF + n * 16);
;                         const f32x4 v = rv + acc[ai][bj][m][n] * scale;
;                         if (out) *(f32x4*)(out + off + bj * HALF + n * 16) = v;
;                         if (xn) { q += (v.x * v.x + v.y * v.y) + (v.z * v.z + v.w * v.w); const f32x4 o = v * wv[bj][n];
;                             u32x2 p; p.x = pk2(o.x, o.y); p.y = pk2(o.z, o.w); *(u32x2*)(xn + off + bj * HALF + n * 16) = p; }
;                     }
;                 if (xn) { q += __shfl_xor(q, 16); q += __shfl_xor(q, 32); if (fq == 0) (void)__hip_atomic_fetch_add(ss + row, q, __ATOMIC_RELAXED, __HIP_MEMORY_SCOPE_AGENT); }
;             }
	v_pk_fma_f32 v[58:59], v[58:59], 0.5, v[158:159] op_sel_hi:[1,0,1]
	v_pk_fma_f32 v[56:57], v[56:57], 0.5, v[156:157] op_sel_hi:[1,0,1]
	v_pk_mul_f32 v[216:217], v[72:73], v[56:57]
	v_pk_mul_f32 v[218:219], v[74:75], v[58:59]
	v_mul_f32_e32 v232, v56, v56
	v_add_u32_e32 v216, 0x8000, v216
	v_add_u32_e32 v217, 0x8000, v217
	v_add_u32_e32 v218, 0x8000, v218
	v_add_u32_e32 v219, 0x8000, v219
	v_fmac_f32_e32 v232, v57, v57
	v_fmac_f32_e32 v232, v58, v58
	v_fmac_f32_e32 v232, v59, v59
	v_perm_b32 v224, v217, v216, s50
	v_perm_b32 v225, v219, v218, s50
	global_store_dwordx2 v[200:201], v[224:225], off
	v_pk_fma_f32 v[50:51], v[50:51], 0.5, v[170:171] op_sel_hi:[1,0,1]
	v_pk_fma_f32 v[48:49], v[48:49], 0.5, v[168:169] op_sel_hi:[1,0,1]
	v_pk_mul_f32 v[220:221], v[84:85], v[48:49]
	v_pk_mul_f32 v[222:223], v[86:87], v[50:51]
	v_fmac_f32_e32 v232, v48, v48
	v_add_u32_e32 v220, 0x8000, v220
	v_add_u32_e32 v221, 0x8000, v221
	v_add_u32_e32 v222, 0x8000, v222
	v_add_u32_e32 v223, 0x8000, v223
	v_fmac_f32_e32 v232, v49, v49
	v_fmac_f32_e32 v232, v50, v50
	v_fmac_f32_e32 v232, v51, v51
	v_perm_b32 v226, v221, v220, s50
	v_perm_b32 v227, v223, v222, s50
	global_store_dwordx2 v[200:201], v[226:227], off offset:256
	v_pk_fma_f32 v[62:63], v[62:63], 0.5, v[174:175] op_sel_hi:[1,0,1]
	v_pk_fma_f32 v[60:61], v[60:61], 0.5, v[172:173] op_sel_hi:[1,0,1]
	v_pk_mul_f32 v[216:217], v[88:89], v[60:61]
	v_pk_mul_f32 v[218:219], v[90:91], v[62:63]
	v_mul_f32_e32 v233, v60, v60
	v_add_u32_e32 v216, 0x8000, v216
	v_add_u32_e32 v217, 0x8000, v217
	v_add_u32_e32 v218, 0x8000, v218
	v_add_u32_e32 v219, 0x8000, v219
	v_fmac_f32_e32 v233, v61, v61
	v_fmac_f32_e32 v233, v62, v62
	v_fmac_f32_e32 v233, v63, v63
	v_perm_b32 v224, v217, v216, s50
	v_perm_b32 v225, v219, v218, s50
	global_store_dwordx2 v[202:203], v[224:225], off
	v_pk_fma_f32 v[54:55], v[54:55], 0.5, v[178:179] op_sel_hi:[1,0,1]
	v_pk_fma_f32 v[52:53], v[52:53], 0.5, v[176:177] op_sel_hi:[1,0,1]
	v_pk_mul_f32 v[220:221], v[96:97], v[52:53]
	v_pk_mul_f32 v[222:223], v[98:99], v[54:55]
	v_fmac_f32_e32 v233, v52, v52
	v_add_u32_e32 v220, 0x8000, v220
	v_add_u32_e32 v221, 0x8000, v221
	v_add_u32_e32 v222, 0x8000, v222
	v_add_u32_e32 v223, 0x8000, v223
	v_fmac_f32_e32 v233, v53, v53
	v_fmac_f32_e32 v233, v54, v54
	v_fmac_f32_e32 v233, v55, v55
	v_perm_b32 v226, v221, v220, s50
	v_perm_b32 v227, v223, v222, s50
	global_store_dwordx2 v[202:203], v[226:227], off offset:256
	s_nop 1
	v_mov_b32_dpp v236, v232 row_ror:8 row_mask:0xf bank_mask:0xf
	v_mov_b32_dpp v237, v233 row_ror:8 row_mask:0xf bank_mask:0xf
	v_add_f32_e32 v232, v232, v236
	v_add_f32_e32 v233, v233, v237
	v_cndmask_b32_e64 v232, v233, v232, s[24:25]
	s_nop 0
	ds_bpermute_b32 v236, v234, v232
	global_load_dwordx4 v[156:159], v[196:197], off
	global_load_dwordx4 v[168:171], v[196:197], off offset:512
	global_load_dwordx4 v[172:175], v[198:199], off
	global_load_dwordx4 v[176:179], v[198:199], off offset:512
	s_mov_b64 vcc, 0x20000
	v_lshl_add_u64 v[196:197], v[196:197], 0, vcc
	v_lshl_add_u64 v[198:199], v[198:199], 0, vcc
	s_mov_b64 vcc, 0x20000
	s_mov_b64 vcc, 0x10000
	v_lshl_add_u64 v[200:201], v[200:201], 0, vcc
	v_lshl_add_u64 v[202:203], v[202:203], 0, vcc
	s_waitcnt lgkmcnt(0)
	v_add_f32_e32 v232, v232, v236
	s_nop 0
	ds_bpermute_b32 v237, v235, v232
	s_waitcnt lgkmcnt(0)
	v_add_f32_e32 v232, v232, v237
	s_mov_b64 exec, s[0:1]
	global_atomic_add_f32 v[204:205], v232, off
	s_mov_b64 exec, -1
	s_mov_b64 vcc, 64
	v_lshl_add_u64 v[204:205], v[204:205], 0, vcc
	v_mov_b32_dpp v228, v40 row_ror:8 row_mask:0xf bank_mask:0xf
	v_mov_b32_dpp v229, v41 row_ror:8 row_mask:0xf bank_mask:0xf
	v_mov_b32_dpp v230, v42 row_ror:8 row_mask:0xf bank_mask:0xf
	v_mov_b32_dpp v231, v43 row_ror:8 row_mask:0xf bank_mask:0xf
	v_cndmask_b32_e64 v40, v228, v44, s[24:25]
	v_cndmask_b32_e64 v41, v229, v45, s[24:25]
	v_cndmask_b32_e64 v42, v230, v46, s[24:25]
	v_cndmask_b32_e64 v43, v231, v47, s[24:25]
	v_cndmask_b32_e64 v44, v44, v228, s[24:25]
	v_cndmask_b32_e64 v45, v45, v229, s[24:25]
	v_cndmask_b32_e64 v46, v46, v230, s[24:25]
	v_cndmask_b32_e64 v47, v47, v231, s[24:25]
	v_mov_b32_dpp v228, v32 row_ror:8 row_mask:0xf bank_mask:0xf
	v_mov_b32_dpp v229, v33 row_ror:8 row_mask:0xf bank_mask:0xf
	v_mov_b32_dpp v230, v34 row_ror:8 row_mask:0xf bank_mask:0xf
	v_mov_b32_dpp v231, v35 row_ror:8 row_mask:0xf bank_mask:0xf
	v_cndmask_b32_e64 v32, v228, v36, s[24:25]
	v_cndmask_b32_e64 v33, v229, v37, s[24:25]
	v_cndmask_b32_e64 v34, v230, v38, s[24:25]
	v_cndmask_b32_e64 v35, v231, v39, s[24:25]
	v_cndmask_b32_e64 v36, v36, v228, s[24:25]
	v_cndmask_b32_e64 v37, v37, v229, s[24:25]
	v_cndmask_b32_e64 v38, v38, v230, s[24:25]
	v_cndmask_b32_e64 v39, v39, v231, s[24:25]
	s_waitcnt vmcnt(10)
;     __device__ __forceinline__ void operator()(const f32x4 (&acc)[2][2][4][2], const Unit& u, int wr, int wc, int fr, int fq) const {
;     ...
; #pragma unroll
;         for (int ai = 0; ai < 2; ++ai)
; #pragma unroll
;             for (int m = 0; m < 4; ++m) {
;                 const int row = row0 + ai * HALF + m * 16;
;                 const size_t off = (size_t)row * ldc + col0;
;                 float q = 0.f;
; #pragma unroll
;                 for (int bj = 0; bj < 2; ++bj)
; #pragma unroll
;                     for (int n = 0; n < 2; ++n) {
;                         const f32x4 rv = *(const f32x4*)(rbase + off + bj * HALF + n * 16);
;                         const f32x4 v = rv + acc[ai][bj][m][n] * scale;
;                         if (out) *(f32x4*)(out + off + bj * HALF + n * 16) = v;
;                         if (xn) { q += (v.x * v.x + v.y * v.y) + (v.z * v.z + v.w * v.w); const f32x4 o = v * wv[bj][n];
;                             u32x2 p; p.x = pk2(o.x, o.y); p.y = pk2(o.z, o.w); *(u32x2*)(xn + off + bj * HALF + n * 16) = p; }
;                     }
;                 if (xn) { q += __shfl_xor(q, 16); q += __shfl_xor(q, 32); if (fq == 0) (void)__hip_atomic_fetch_add(ss + row, q, __ATOMIC_RELAXED, __HIP_MEMORY_SCOPE_AGENT); }
;             }
	v_pk_fma_f32 v[42:43], v[42:43], 0.5, v[182:183] op_sel_hi:[1,0,1]
	v_pk_fma_f32 v[40:41], v[40:41], 0.5, v[180:181] op_sel_hi:[1,0,1]
	v_pk_mul_f32 v[216:217], v[72:73], v[40:41]
	v_pk_mul_f32 v[218:219], v[74:75], v[42:43]
	v_mul_f32_e32 v232, v40, v40
	v_add_u32_e32 v216, 0x8000, v216
	v_add_u32_e32 v217, 0x8000, v217
	v_add_u32_e32 v218, 0x8000, v218
	v_add_u32_e32 v219, 0x8000, v219
	v_fmac_f32_e32 v232, v41, v41
	v_fmac_f32_e32 v232, v42, v42
	v_fmac_f32_e32 v232, v43, v43
	v_perm_b32 v224, v217, v216, s50
	v_perm_b32 v225, v219, v218, s50
	global_store_dwordx2 v[200:201], v[224:225], off
	v_pk_fma_f32 v[34:35], v[34:35], 0.5, v[186:187] op_sel_hi:[1,0,1]
	v_pk_fma_f32 v[32:33], v[32:33], 0.5, v[184:185] op_sel_hi:[1,0,1]
	v_pk_mul_f32 v[220:221], v[84:85], v[32:33]
	v_pk_mul_f32 v[222:223], v[86:87], v[34:35]
	v_fmac_f32_e32 v232, v32, v32
	v_add_u32_e32 v220, 0x8000, v220
	v_add_u32_e32 v221, 0x8000, v221
	v_add_u32_e32 v222, 0x8000, v222
	v_add_u32_e32 v223, 0x8000, v223
	v_fmac_f32_e32 v232, v33, v33
	v_fmac_f32_e32 v232, v34, v34
	v_fmac_f32_e32 v232, v35, v35
	v_perm_b32 v226, v221, v220, s50
	v_perm_b32 v227, v223, v222, s50
	global_store_dwordx2 v[200:201], v[226:227], off offset:256
	v_pk_fma_f32 v[46:47], v[46:47], 0.5, v[190:191] op_sel_hi:[1,0,1]
	v_pk_fma_f32 v[44:45], v[44:45], 0.5, v[188:189] op_sel_hi:[1,0,1]
	v_pk_mul_f32 v[216:217], v[88:89], v[44:45]
	v_pk_mul_f32 v[218:219], v[90:91], v[46:47]
	v_mul_f32_e32 v233, v44, v44
	v_add_u32_e32 v216, 0x8000, v216
	v_add_u32_e32 v217, 0x8000, v217
	v_add_u32_e32 v218, 0x8000, v218
	v_add_u32_e32 v219, 0x8000, v219
	v_fmac_f32_e32 v233, v45, v45
	v_fmac_f32_e32 v233, v46, v46
	v_fmac_f32_e32 v233, v47, v47
	v_perm_b32 v224, v217, v216, s50
	v_perm_b32 v225, v219, v218, s50
	global_store_dwordx2 v[202:203], v[224:225], off
	v_pk_fma_f32 v[38:39], v[38:39], 0.5, v[194:195] op_sel_hi:[1,0,1]
	v_pk_fma_f32 v[36:37], v[36:37], 0.5, v[192:193] op_sel_hi:[1,0,1]
	v_pk_mul_f32 v[220:221], v[96:97], v[36:37]
	v_pk_mul_f32 v[222:223], v[98:99], v[38:39]
	v_fmac_f32_e32 v233, v36, v36
	v_add_u32_e32 v220, 0x8000, v220
	v_add_u32_e32 v221, 0x8000, v221
	v_add_u32_e32 v222, 0x8000, v222
	v_add_u32_e32 v223, 0x8000, v223
	v_fmac_f32_e32 v233, v37, v37
	v_fmac_f32_e32 v233, v38, v38
	v_fmac_f32_e32 v233, v39, v39
	v_perm_b32 v226, v221, v220, s50
	v_perm_b32 v227, v223, v222, s50
	global_store_dwordx2 v[202:203], v[226:227], off offset:256
	s_nop 1
	v_mov_b32_dpp v236, v232 row_ror:8 row_mask:0xf bank_mask:0xf
	v_mov_b32_dpp v237, v233 row_ror:8 row_mask:0xf bank_mask:0xf
	v_add_f32_e32 v232, v232, v236
	v_add_f32_e32 v233, v233, v237
	v_cndmask_b32_e64 v232, v233, v232, s[24:25]
	s_nop 0
	ds_bpermute_b32 v236, v234, v232
	global_load_dwordx4 v[180:183], v[196:197], off
	global_load_dwordx4 v[184:187], v[196:197], off offset:512
	global_load_dwordx4 v[188:191], v[198:199], off
	global_load_dwordx4 v[192:195], v[198:199], off offset:512
	s_mov_b64 vcc, 0x20000
	s_mov_b64 vcc, 0x10000
	v_lshl_add_u64 v[200:201], v[200:201], 0, vcc
	v_lshl_add_u64 v[202:203], v[202:203], 0, vcc
	s_waitcnt lgkmcnt(0)
	v_add_f32_e32 v232, v232, v236
	s_nop 0
	ds_bpermute_b32 v237, v235, v232
	s_waitcnt lgkmcnt(0)
	v_add_f32_e32 v232, v232, v237
	s_mov_b64 exec, s[0:1]
	global_atomic_add_f32 v[204:205], v232, off
	s_mov_b64 exec, -1
	s_mov_b64 vcc, 64
	v_lshl_add_u64 v[204:205], v[204:205], 0, vcc
	v_mov_b32_dpp v228, v24 row_ror:8 row_mask:0xf bank_mask:0xf
	v_mov_b32_dpp v229, v25 row_ror:8 row_mask:0xf bank_mask:0xf
	v_mov_b32_dpp v230, v26 row_ror:8 row_mask:0xf bank_mask:0xf
	v_mov_b32_dpp v231, v27 row_ror:8 row_mask:0xf bank_mask:0xf
	v_cndmask_b32_e64 v24, v228, v28, s[24:25]
	v_cndmask_b32_e64 v25, v229, v29, s[24:25]
	v_cndmask_b32_e64 v26, v230, v30, s[24:25]
	v_cndmask_b32_e64 v27, v231, v31, s[24:25]
	v_cndmask_b32_e64 v28, v28, v228, s[24:25]
	v_cndmask_b32_e64 v29, v29, v229, s[24:25]
	v_cndmask_b32_e64 v30, v30, v230, s[24:25]
	v_cndmask_b32_e64 v31, v31, v231, s[24:25]
	v_mov_b32_dpp v228, v16 row_ror:8 row_mask:0xf bank_mask:0xf
	v_mov_b32_dpp v229, v17 row_ror:8 row_mask:0xf bank_mask:0xf
	v_mov_b32_dpp v230, v18 row_ror:8 row_mask:0xf bank_mask:0xf
	v_mov_b32_dpp v231, v19 row_ror:8 row_mask:0xf bank_mask:0xf
	v_cndmask_b32_e64 v16, v228, v20, s[24:25]
	v_cndmask_b32_e64 v17, v229, v21, s[24:25]
	v_cndmask_b32_e64 v18, v230, v22, s[24:25]
	v_cndmask_b32_e64 v19, v231, v23, s[24:25]
	v_cndmask_b32_e64 v20, v20, v228, s[24:25]
	v_cndmask_b32_e64 v21, v21, v229, s[24:25]
	v_cndmask_b32_e64 v22, v22, v230, s[24:25]
	v_cndmask_b32_e64 v23, v23, v231, s[24:25]
	s_waitcnt vmcnt(10)
;     __device__ __forceinline__ void operator()(const f32x4 (&acc)[2][2][4][2], const Unit& u, int wr, int wc, int fr, int fq) const {
;     ...
; #pragma unroll
;         for (int ai = 0; ai < 2; ++ai)
; #pragma unroll
;             for (int m = 0; m < 4; ++m) {
;                 const int row = row0 + ai * HALF + m * 16;
;                 const size_t off = (size_t)row * ldc + col0;
;                 float q = 0.f;
; #pragma unroll
;                 for (int bj = 0; bj < 2; ++bj)
; #pragma unroll
;                     for (int n = 0; n < 2; ++n) {
;                         const f32x4 rv = *(const f32x4*)(rbase + off + bj * HALF + n * 16);
;                         const f32x4 v = rv + acc[ai][bj][m][n] * scale;
;                         if (out) *(f32x4*)(out + off + bj * HALF + n * 16) = v;
;                         if (xn) { q += (v.x * v.x + v.y * v.y) + (v.z * v.z + v.w * v.w); const f32x4 o = v * wv[bj][n];
;                             u32x2 p; p.x = pk2(o.x, o.y); p.y = pk2(o.z, o.w); *(u32x2*)(xn + off + bj * HALF + n * 16) = p; }
;                     }
;                 if (xn) { q += __shfl_xor(q, 16); q += __shfl_xor(q, 32); if (fq == 0) (void)__hip_atomic_fetch_add(ss + row, q, __ATOMIC_RELAXED, __HIP_MEMORY_SCOPE_AGENT); }
;             }
	v_pk_fma_f32 v[26:27], v[26:27], 0.5, v[158:159] op_sel_hi:[1,0,1]
	v_pk_fma_f32 v[24:25], v[24:25], 0.5, v[156:157] op_sel_hi:[1,0,1]
	v_pk_mul_f32 v[216:217], v[72:73], v[24:25]
	v_pk_mul_f32 v[218:219], v[74:75], v[26:27]
	v_mul_f32_e32 v232, v24, v24
	v_add_u32_e32 v216, 0x8000, v216
	v_add_u32_e32 v217, 0x8000, v217
	v_add_u32_e32 v218, 0x8000, v218
	v_add_u32_e32 v219, 0x8000, v219
	v_fmac_f32_e32 v232, v25, v25
	v_fmac_f32_e32 v232, v26, v26
	v_fmac_f32_e32 v232, v27, v27
	v_perm_b32 v224, v217, v216, s50
	v_perm_b32 v225, v219, v218, s50
	global_store_dwordx2 v[200:201], v[224:225], off
	v_pk_fma_f32 v[18:19], v[18:19], 0.5, v[170:171] op_sel_hi:[1,0,1]
	v_pk_fma_f32 v[16:17], v[16:17], 0.5, v[168:169] op_sel_hi:[1,0,1]
	v_pk_mul_f32 v[220:221], v[84:85], v[16:17]
	v_pk_mul_f32 v[222:223], v[86:87], v[18:19]
	v_fmac_f32_e32 v232, v16, v16
	v_add_u32_e32 v220, 0x8000, v220
	v_add_u32_e32 v221, 0x8000, v221
	v_add_u32_e32 v222, 0x8000, v222
	v_add_u32_e32 v223, 0x8000, v223
	v_fmac_f32_e32 v232, v17, v17
	v_fmac_f32_e32 v232, v18, v18
	v_fmac_f32_e32 v232, v19, v19
	v_perm_b32 v226, v221, v220, s50
	v_perm_b32 v227, v223, v222, s50
	global_store_dwordx2 v[200:201], v[226:227], off offset:256
	v_pk_fma_f32 v[30:31], v[30:31], 0.5, v[174:175] op_sel_hi:[1,0,1]
	v_pk_fma_f32 v[28:29], v[28:29], 0.5, v[172:173] op_sel_hi:[1,0,1]
	v_pk_mul_f32 v[216:217], v[88:89], v[28:29]
	v_pk_mul_f32 v[218:219], v[90:91], v[30:31]
	v_mul_f32_e32 v233, v28, v28
	v_add_u32_e32 v216, 0x8000, v216
	v_add_u32_e32 v217, 0x8000, v217
	v_add_u32_e32 v218, 0x8000, v218
	v_add_u32_e32 v219, 0x8000, v219
	v_fmac_f32_e32 v233, v29, v29
	v_fmac_f32_e32 v233, v30, v30
	v_fmac_f32_e32 v233, v31, v31
	v_perm_b32 v224, v217, v216, s50
	v_perm_b32 v225, v219, v218, s50
	global_store_dwordx2 v[202:203], v[224:225], off
	v_pk_fma_f32 v[22:23], v[22:23], 0.5, v[178:179] op_sel_hi:[1,0,1]
	v_pk_fma_f32 v[20:21], v[20:21], 0.5, v[176:177] op_sel_hi:[1,0,1]
	v_pk_mul_f32 v[220:221], v[96:97], v[20:21]
	v_pk_mul_f32 v[222:223], v[98:99], v[22:23]
	v_fmac_f32_e32 v233, v20, v20
	v_add_u32_e32 v220, 0x8000, v220
	v_add_u32_e32 v221, 0x8000, v221
	v_add_u32_e32 v222, 0x8000, v222
	v_add_u32_e32 v223, 0x8000, v223
	v_fmac_f32_e32 v233, v21, v21
	v_fmac_f32_e32 v233, v22, v22
	v_fmac_f32_e32 v233, v23, v23
	v_perm_b32 v226, v221, v220, s50
	v_perm_b32 v227, v223, v222, s50
	global_store_dwordx2 v[202:203], v[226:227], off offset:256
	s_nop 1
	v_mov_b32_dpp v236, v232 row_ror:8 row_mask:0xf bank_mask:0xf
	v_mov_b32_dpp v237, v233 row_ror:8 row_mask:0xf bank_mask:0xf
	v_add_f32_e32 v232, v232, v236
	v_add_f32_e32 v233, v233, v237
	v_cndmask_b32_e64 v232, v233, v232, s[24:25]
	s_nop 0
	ds_bpermute_b32 v236, v234, v232
	s_mov_b64 vcc, 0x20000
	s_mov_b64 vcc, 0x10000
	v_lshl_add_u64 v[200:201], v[200:201], 0, vcc
	v_lshl_add_u64 v[202:203], v[202:203], 0, vcc
	s_waitcnt lgkmcnt(0)
	v_add_f32_e32 v232, v232, v236
	s_nop 0
	ds_bpermute_b32 v237, v235, v232
	s_waitcnt lgkmcnt(0)
	v_add_f32_e32 v232, v232, v237
	s_mov_b64 exec, s[0:1]
	global_atomic_add_f32 v[204:205], v232, off
	s_mov_b64 exec, -1
	s_mov_b64 vcc, 64
	v_lshl_add_u64 v[204:205], v[204:205], 0, vcc
	v_mov_b32_dpp v228, v8 row_ror:8 row_mask:0xf bank_mask:0xf
	v_mov_b32_dpp v229, v9 row_ror:8 row_mask:0xf bank_mask:0xf
	v_mov_b32_dpp v230, v10 row_ror:8 row_mask:0xf bank_mask:0xf
	v_mov_b32_dpp v231, v11 row_ror:8 row_mask:0xf bank_mask:0xf
	v_cndmask_b32_e64 v8, v228, v12, s[24:25]
	v_cndmask_b32_e64 v9, v229, v13, s[24:25]
	v_cndmask_b32_e64 v10, v230, v14, s[24:25]
	v_cndmask_b32_e64 v11, v231, v15, s[24:25]
	v_cndmask_b32_e64 v12, v12, v228, s[24:25]
	v_cndmask_b32_e64 v13, v13, v229, s[24:25]
	v_cndmask_b32_e64 v14, v14, v230, s[24:25]
	v_cndmask_b32_e64 v15, v15, v231, s[24:25]
	v_mov_b32_dpp v228, v0 row_ror:8 row_mask:0xf bank_mask:0xf
	v_mov_b32_dpp v229, v1 row_ror:8 row_mask:0xf bank_mask:0xf
	v_mov_b32_dpp v230, v2 row_ror:8 row_mask:0xf bank_mask:0xf
	v_mov_b32_dpp v231, v3 row_ror:8 row_mask:0xf bank_mask:0xf
	v_cndmask_b32_e64 v0, v228, v4, s[24:25]
	v_cndmask_b32_e64 v1, v229, v5, s[24:25]
	v_cndmask_b32_e64 v2, v230, v6, s[24:25]
	v_cndmask_b32_e64 v3, v231, v7, s[24:25]
	v_cndmask_b32_e64 v4, v4, v228, s[24:25]
	v_cndmask_b32_e64 v5, v5, v229, s[24:25]
	v_cndmask_b32_e64 v6, v6, v230, s[24:25]
	v_cndmask_b32_e64 v7, v7, v231, s[24:25]
	s_waitcnt vmcnt(6)
;     __device__ __forceinline__ void operator()(const f32x4 (&acc)[2][2][4][2], const Unit& u, int wr, int wc, int fr, int fq) const {
;     ...
; #pragma unroll
;         for (int ai = 0; ai < 2; ++ai)
; #pragma unroll
;             for (int m = 0; m < 4; ++m) {
;                 const int row = row0 + ai * HALF + m * 16;
;                 const size_t off = (size_t)row * ldc + col0;
;                 float q = 0.f;
; #pragma unroll
;                 for (int bj = 0; bj < 2; ++bj)
; #pragma unroll
;                     for (int n = 0; n < 2; ++n) {
;                         const f32x4 rv = *(const f32x4*)(rbase + off + bj * HALF + n * 16);
;                         const f32x4 v = rv + acc[ai][bj][m][n] * scale;
;                         if (out) *(f32x4*)(out + off + bj * HALF + n * 16) = v;
;                         if (xn) { q += (v.x * v.x + v.y * v.y) + (v.z * v.z + v.w * v.w); const f32x4 o = v * wv[bj][n];
;                             u32x2 p; p.x = pk2(o.x, o.y); p.y = pk2(o.z, o.w); *(u32x2*)(xn + off + bj * HALF + n * 16) = p; }
;                     }
;                 if (xn) { q += __shfl_xor(q, 16); q += __shfl_xor(q, 32); if (fq == 0) (void)__hip_atomic_fetch_add(ss + row, q, __ATOMIC_RELAXED, __HIP_MEMORY_SCOPE_AGENT); }
;             }
	v_pk_fma_f32 v[10:11], v[10:11], 0.5, v[182:183] op_sel_hi:[1,0,1]
	v_pk_fma_f32 v[8:9], v[8:9], 0.5, v[180:181] op_sel_hi:[1,0,1]
	v_pk_mul_f32 v[216:217], v[72:73], v[8:9]
	v_pk_mul_f32 v[218:219], v[74:75], v[10:11]
	v_mul_f32_e32 v232, v8, v8
	v_add_u32_e32 v216, 0x8000, v216
	v_add_u32_e32 v217, 0x8000, v217
	v_add_u32_e32 v218, 0x8000, v218
	v_add_u32_e32 v219, 0x8000, v219
	v_fmac_f32_e32 v232, v9, v9
	v_fmac_f32_e32 v232, v10, v10
	v_fmac_f32_e32 v232, v11, v11
	v_perm_b32 v224, v217, v216, s50
	v_perm_b32 v225, v219, v218, s50
	global_store_dwordx2 v[200:201], v[224:225], off
	v_pk_fma_f32 v[2:3], v[2:3], 0.5, v[186:187] op_sel_hi:[1,0,1]
	v_pk_fma_f32 v[0:1], v[0:1], 0.5, v[184:185] op_sel_hi:[1,0,1]
	v_pk_mul_f32 v[220:221], v[84:85], v[0:1]
	v_pk_mul_f32 v[222:223], v[86:87], v[2:3]
	v_fmac_f32_e32 v232, v0, v0
	v_add_u32_e32 v220, 0x8000, v220
	v_add_u32_e32 v221, 0x8000, v221
	v_add_u32_e32 v222, 0x8000, v222
	v_add_u32_e32 v223, 0x8000, v223
	v_fmac_f32_e32 v232, v1, v1
	v_fmac_f32_e32 v232, v2, v2
	v_fmac_f32_e32 v232, v3, v3
	v_perm_b32 v226, v221, v220, s50
	v_perm_b32 v227, v223, v222, s50
	global_store_dwordx2 v[200:201], v[226:227], off offset:256
	v_pk_fma_f32 v[14:15], v[14:15], 0.5, v[190:191] op_sel_hi:[1,0,1]
	v_pk_fma_f32 v[12:13], v[12:13], 0.5, v[188:189] op_sel_hi:[1,0,1]
	v_pk_mul_f32 v[216:217], v[88:89], v[12:13]
	v_pk_mul_f32 v[218:219], v[90:91], v[14:15]
	v_mul_f32_e32 v233, v12, v12
	v_add_u32_e32 v216, 0x8000, v216
	v_add_u32_e32 v217, 0x8000, v217
	v_add_u32_e32 v218, 0x8000, v218
	v_add_u32_e32 v219, 0x8000, v219
	v_fmac_f32_e32 v233, v13, v13
	v_fmac_f32_e32 v233, v14, v14
	v_fmac_f32_e32 v233, v15, v15
	v_perm_b32 v224, v217, v216, s50
	v_perm_b32 v225, v219, v218, s50
	global_store_dwordx2 v[202:203], v[224:225], off
	v_pk_fma_f32 v[6:7], v[6:7], 0.5, v[194:195] op_sel_hi:[1,0,1]
	v_pk_fma_f32 v[4:5], v[4:5], 0.5, v[192:193] op_sel_hi:[1,0,1]
	v_pk_mul_f32 v[220:221], v[96:97], v[4:5]
	v_pk_mul_f32 v[222:223], v[98:99], v[6:7]
	v_fmac_f32_e32 v233, v4, v4
	v_add_u32_e32 v220, 0x8000, v220
	v_add_u32_e32 v221, 0x8000, v221
	v_add_u32_e32 v222, 0x8000, v222
	v_add_u32_e32 v223, 0x8000, v223
	v_fmac_f32_e32 v233, v5, v5
	v_fmac_f32_e32 v233, v6, v6
	v_fmac_f32_e32 v233, v7, v7
	v_perm_b32 v226, v221, v220, s50
	v_perm_b32 v227, v223, v222, s50
	global_store_dwordx2 v[202:203], v[226:227], off offset:256
	s_nop 1
	v_mov_b32_dpp v236, v232 row_ror:8 row_mask:0xf bank_mask:0xf
	v_mov_b32_dpp v237, v233 row_ror:8 row_mask:0xf bank_mask:0xf
	v_add_f32_e32 v232, v232, v236
	v_add_f32_e32 v233, v233, v237
	v_cndmask_b32_e64 v232, v233, v232, s[24:25]
	s_nop 0
	ds_bpermute_b32 v236, v234, v232
	s_waitcnt lgkmcnt(0)
	v_add_f32_e32 v232, v232, v236
	s_nop 0
	ds_bpermute_b32 v237, v235, v232
	s_waitcnt lgkmcnt(0)
	v_add_f32_e32 v232, v232, v237
	s_mov_b64 exec, s[0:1]
	global_atomic_add_f32 v[204:205], v232, off
	s_mov_b64 exec, -1
	s_and_b64 vcc, exec, s[6:7]
	s_mov_b64 s[6:7], -1
	s_cbranch_vccnz .LBB0_1371
	s_andn2_b64 vcc, exec, s[12:13]
	s_cbranch_vccnz .LBB0_1370
	s_barrier
	s_branch .LBB0_1370
